# GEMM K-loops: LDS-DMA uses SGPR base + 32-bit VGPR offset (no per-DMA 64-bit VALU address adds)
# speedup vs baseline: 1.0066x; 1.0036x over previous
; #define PG8_STAGE(bufoff, gbase, voff) do { _Pragma("unroll") for (int _i = 0; _i < 2; ++_i) \
;         __builtin_amdgcn_global_load_lds((const unsigned*)((const char*)(gbase) + (voff)[_i]), (PG8_LAS unsigned*)(lds + (bufoff) + ldsw + _i * 8192), 16, 0, 0); } while (0)
; #define PG8_LDA(dst, b, h) do { _Pragma("unroll") for (int m = 0; m < 4; ++m) _Pragma("unroll") for (int k = 0; k < 2; ++k) dst[m][k] = *(const PG8_LAS bf16x8*)(lds + PG8_SA(b, h) + aoff + m * 2048 + k * 1024); } while (0)
; #define PG8_LDB(dst, b, h) do { _Pragma("unroll") for (int n = 0; n < 2; ++n) _Pragma("unroll") for (int k = 0; k < 2; ++k) dst[n][k] = *(const PG8_LAS bf16x8*)(lds + PG8_SB(b, h) + boff + n * 2048 + k * 1024); } while (0)
; #define PG8_MMA(ai, bj, At, Bt) do { __builtin_amdgcn_s_setprio(1); _Pragma("unroll") for (int m = 0; m < 4; ++m) _Pragma("unroll") for (int n = 0; n < 2; ++n) _Pragma("unroll") for (int k = 0; k < 2; ++k) \
;         acc[ai][bj][m][n] = __builtin_amdgcn_mfma_f32_16x16x32_bf16(Bt[n][k], At[m][k], acc[ai][bj][m][n], 0, 0, 0); __builtin_amdgcn_s_setprio(0); } while (0)
; #define PG8_WAIT_V(n) asm volatile("s_waitcnt vmcnt(" #n ")" ::: "memory")
; #define PG8_WAIT_L(n) asm volatile("s_waitcnt lgkmcnt(" #n ")" ::: "memory")
; #define PG8_BAR __builtin_amdgcn_s_barrier()
; #define PG8_SCHED __builtin_amdgcn_sched_barrier(0)
; template <class Epi, class Sched, bool ALIGN_EPI = false, bool SP2 = false>
; __device__ __forceinline__ void gemm_phase(PG8_LAS unsigned char* lds, const Gemm g, const Sched& S, const Epi& E) {
;     ...
;             PG8_LDB(B0, 0, 0); PG8_LDB(B1, 0, 1); PG8_SCHED; PG8_LDA(At, 0, 0); PG8_STAGE(PG8_SA(1, 1), a1 + hstepA, voffA);
;             PG8_WAIT_V(8); PG8_WAIT_L(0); PG8_BAR; PG8_MMA(0, 0, At, B0); PG8_MMA(0, 1, At, B1); PG8_BAR; PG8_SCHED;
;             PG8_LDA(At, 0, 1); PG8_STAGE(PG8_SB(0, 0), b2, voffB); PG8_STAGE(PG8_SB(0, 1), b2 + hstep, voffB); PG8_STAGE(PG8_SA(0, 0), a2, voffA);
;             PG8_WAIT_V(8); PG8_WAIT_L(0); PG8_BAR; PG8_MMA(1, 0, At, B0); PG8_MMA(1, 1, At, B1); PG8_BAR; PG8_SCHED;
.LBB0_115:
	ds_read_b128 v[150:153], v158
	ds_read_b128 v[162:165], v158 offset:1024
	ds_read_b128 v[166:169], v158 offset:2048
	ds_read_b128 v[170:173], v158 offset:3072
	ds_read_b128 v[174:177], v159
	ds_read_b128 v[178:181], v159 offset:1024
	ds_read_b128 v[182:185], v159 offset:2048
	ds_read_b128 v[186:189], v159 offset:3072
	s_add_u32 s68, s34, 0xfff00080
	s_addc_u32 s69, s35, -1
	s_cmp_eq_u32 s67, 60
	s_cselect_b32 s87, s21, s69
	s_cselect_b32 s86, s27, s68
	s_cselect_b32 s85, s19, s66
	s_cselect_b32 s84, s31, s65
	s_add_i32 m0, s53, 0xc000
	ds_read_b128 v[190:193], v160
	ds_read_b128 v[194:197], v160 offset:1024
	ds_read_b128 v[198:201], v160 offset:2048
	ds_read_b128 v[202:205], v160 offset:3072
	ds_read_b128 v[206:209], v160 offset:4096
	ds_read_b128 v[210:213], v160 offset:5120
	ds_read_b128 v[214:217], v160 offset:6144
	ds_read_b128 v[218:221], v160 offset:7168
	global_load_lds_dwordx4 v140, s[34:35]
	s_add_i32 m0, s53, 0xe000
	s_nop 0
	global_load_lds_dwordx4 v142, s[34:35]
	s_waitcnt vmcnt(8)
	s_waitcnt lgkmcnt(0)
	s_barrier
	s_setprio 1
	s_waitcnt lgkmcnt(0)
	v_mfma_f32_16x16x32_bf16 v[124:127], v[150:153], v[190:193], v[124:127]
	v_mfma_f32_16x16x32_bf16 v[120:123], v[166:169], v[190:193], v[120:123]
	v_mfma_f32_16x16x32_bf16 v[108:111], v[150:153], v[198:201], v[108:111]
	v_mfma_f32_16x16x32_bf16 v[104:107], v[166:169], v[198:201], v[104:107]
	v_mfma_f32_16x16x32_bf16 v[92:95], v[150:153], v[206:209], v[92:95]
	v_mfma_f32_16x16x32_bf16 v[88:91], v[166:169], v[206:209], v[88:91]
	v_mfma_f32_16x16x32_bf16 v[76:79], v[150:153], v[214:217], v[76:79]
	v_mfma_f32_16x16x32_bf16 v[72:75], v[166:169], v[214:217], v[72:75]
	v_mfma_f32_16x16x32_bf16 v[124:127], v[162:165], v[194:197], v[124:127]
	v_mfma_f32_16x16x32_bf16 v[120:123], v[170:173], v[194:197], v[120:123]
	v_mfma_f32_16x16x32_bf16 v[108:111], v[162:165], v[202:205], v[108:111]
	v_mfma_f32_16x16x32_bf16 v[104:107], v[170:173], v[202:205], v[104:107]
	v_mfma_f32_16x16x32_bf16 v[92:95], v[162:165], v[210:213], v[92:95]
	v_mfma_f32_16x16x32_bf16 v[88:91], v[170:173], v[210:213], v[88:91]
	v_mfma_f32_16x16x32_bf16 v[76:79], v[162:165], v[218:221], v[76:79]
	v_mfma_f32_16x16x32_bf16 v[72:75], v[170:173], v[218:221], v[72:75]
	s_setprio 0
	s_setprio 1
	v_mfma_f32_16x16x32_bf16 v[116:119], v[174:177], v[190:193], v[116:119]
	v_mfma_f32_16x16x32_bf16 v[112:115], v[182:185], v[190:193], v[112:115]
	v_mfma_f32_16x16x32_bf16 v[100:103], v[174:177], v[198:201], v[100:103]
	v_mfma_f32_16x16x32_bf16 v[96:99], v[182:185], v[198:201], v[96:99]
	v_mfma_f32_16x16x32_bf16 v[84:87], v[174:177], v[206:209], v[84:87]
	v_mfma_f32_16x16x32_bf16 v[80:83], v[182:185], v[206:209], v[80:83]
	v_mfma_f32_16x16x32_bf16 v[68:71], v[174:177], v[214:217], v[68:71]
	v_mfma_f32_16x16x32_bf16 v[64:67], v[182:185], v[214:217], v[64:67]
	v_mfma_f32_16x16x32_bf16 v[116:119], v[178:181], v[194:197], v[116:119]
	v_mfma_f32_16x16x32_bf16 v[112:115], v[186:189], v[194:197], v[112:115]
	v_mfma_f32_16x16x32_bf16 v[100:103], v[178:181], v[202:205], v[100:103]
	v_mfma_f32_16x16x32_bf16 v[96:99], v[186:189], v[202:205], v[96:99]
	v_mfma_f32_16x16x32_bf16 v[84:87], v[178:181], v[210:213], v[84:87]
	v_mfma_f32_16x16x32_bf16 v[80:83], v[186:189], v[210:213], v[80:83]
	v_mfma_f32_16x16x32_bf16 v[68:71], v[178:181], v[218:221], v[68:71]
	v_mfma_f32_16x16x32_bf16 v[64:67], v[186:189], v[218:221], v[64:67]
	s_setprio 0
	s_barrier
	s_add_u32 s98, s84, s12
	s_addc_u32 s99, s85, s13
	s_add_u32 s100, s86, s12
	s_addc_u32 s101, s87, s13
	s_add_i32 s68, s62, s33
	s_mov_b32 m0, s68
	ds_read_b128 v[190:193], v160 offset:16384
	ds_read_b128 v[194:197], v160 offset:17408
	ds_read_b128 v[198:201], v160 offset:18432
	ds_read_b128 v[202:205], v160 offset:19456
	ds_read_b128 v[206:209], v160 offset:20480
	ds_read_b128 v[210:213], v160 offset:21504
	ds_read_b128 v[214:217], v160 offset:22528
	ds_read_b128 v[218:221], v160 offset:23552
	global_load_lds_dwordx4 v132, s[84:85]
	s_add_i32 m0, s68, 0x2000
	s_add_u32 s68, s84, 0x100000
	s_addc_u32 s69, s85, 0
	s_add_i32 s70, s63, s33
	global_load_lds_dwordx4 v128, s[84:85]
	s_mov_b32 m0, s70
	s_nop 0
	global_load_lds_dwordx4 v132, s[68:69]
	s_add_i32 m0, s70, 0x2000
	s_nop 0
	global_load_lds_dwordx4 v128, s[68:69]
	s_mov_b32 m0, s53
	s_nop 0
	global_load_lds_dwordx4 v134, s[86:87]
	s_mov_b32 m0, s54
	s_nop 0
	global_load_lds_dwordx4 v130, s[86:87]
	s_waitcnt vmcnt(8)
	s_waitcnt lgkmcnt(0)
	s_barrier
	s_setprio 1
	s_waitcnt lgkmcnt(0)
	v_mfma_f32_16x16x32_bf16 v[60:63], v[150:153], v[190:193], v[60:63]
	v_mfma_f32_16x16x32_bf16 v[56:59], v[166:169], v[190:193], v[56:59]
	v_mfma_f32_16x16x32_bf16 v[44:47], v[150:153], v[198:201], v[44:47]
	v_mfma_f32_16x16x32_bf16 v[40:43], v[166:169], v[198:201], v[40:43]
	v_mfma_f32_16x16x32_bf16 v[28:31], v[150:153], v[206:209], v[28:31]
	v_mfma_f32_16x16x32_bf16 v[24:27], v[166:169], v[206:209], v[24:27]
	v_mfma_f32_16x16x32_bf16 v[12:15], v[150:153], v[214:217], v[12:15]
	v_mfma_f32_16x16x32_bf16 v[8:11], v[166:169], v[214:217], v[8:11]
	v_mfma_f32_16x16x32_bf16 v[60:63], v[162:165], v[194:197], v[60:63]
	v_mfma_f32_16x16x32_bf16 v[56:59], v[170:173], v[194:197], v[56:59]
	v_mfma_f32_16x16x32_bf16 v[44:47], v[162:165], v[202:205], v[44:47]
	v_mfma_f32_16x16x32_bf16 v[40:43], v[170:173], v[202:205], v[40:43]
	v_mfma_f32_16x16x32_bf16 v[28:31], v[162:165], v[210:213], v[28:31]
	v_mfma_f32_16x16x32_bf16 v[24:27], v[170:173], v[210:213], v[24:27]
	v_mfma_f32_16x16x32_bf16 v[12:15], v[162:165], v[218:221], v[12:15]
	v_mfma_f32_16x16x32_bf16 v[8:11], v[170:173], v[218:221], v[8:11]
	s_setprio 0
	s_setprio 1
	v_mfma_f32_16x16x32_bf16 v[52:55], v[174:177], v[190:193], v[52:55]
	v_mfma_f32_16x16x32_bf16 v[48:51], v[182:185], v[190:193], v[48:51]
	v_mfma_f32_16x16x32_bf16 v[36:39], v[174:177], v[198:201], v[36:39]
	v_mfma_f32_16x16x32_bf16 v[32:35], v[182:185], v[198:201], v[32:35]
	v_mfma_f32_16x16x32_bf16 v[20:23], v[174:177], v[206:209], v[20:23]
	v_mfma_f32_16x16x32_bf16 v[16:19], v[182:185], v[206:209], v[16:19]
	v_mfma_f32_16x16x32_bf16 v[4:7], v[174:177], v[214:217], v[4:7]
	v_mfma_f32_16x16x32_bf16 v[0:3], v[182:185], v[214:217], v[0:3]
	v_mfma_f32_16x16x32_bf16 v[52:55], v[178:181], v[194:197], v[52:55]
	v_mfma_f32_16x16x32_bf16 v[48:51], v[186:189], v[194:197], v[48:51]
	v_mfma_f32_16x16x32_bf16 v[36:39], v[178:181], v[202:205], v[36:39]
	v_mfma_f32_16x16x32_bf16 v[32:35], v[186:189], v[202:205], v[32:35]
	v_mfma_f32_16x16x32_bf16 v[20:23], v[178:181], v[210:213], v[20:23]
	v_mfma_f32_16x16x32_bf16 v[16:19], v[186:189], v[210:213], v[16:19]
	v_mfma_f32_16x16x32_bf16 v[4:7], v[178:181], v[218:221], v[4:7]
	v_mfma_f32_16x16x32_bf16 v[0:3], v[186:189], v[218:221], v[0:3]
	s_setprio 0
	s_barrier
; #define PG8_STAGE(bufoff, gbase, voff) do { _Pragma("unroll") for (int _i = 0; _i < 2; ++_i) \
;         __builtin_amdgcn_global_load_lds((const unsigned*)((const char*)(gbase) + (voff)[_i]), (PG8_LAS unsigned*)(lds + (bufoff) + ldsw + _i * 8192), 16, 0, 0); } while (0)
; #define PG8_LDA(dst, b, h) do { _Pragma("unroll") for (int m = 0; m < 4; ++m) _Pragma("unroll") for (int k = 0; k < 2; ++k) dst[m][k] = *(const PG8_LAS bf16x8*)(lds + PG8_SA(b, h) + aoff + m * 2048 + k * 1024); } while (0)
; #define PG8_LDB(dst, b, h) do { _Pragma("unroll") for (int n = 0; n < 2; ++n) _Pragma("unroll") for (int k = 0; k < 2; ++k) dst[n][k] = *(const PG8_LAS bf16x8*)(lds + PG8_SB(b, h) + boff + n * 2048 + k * 1024); } while (0)
; #define PG8_MMA(ai, bj, At, Bt) do { __builtin_amdgcn_s_setprio(1); _Pragma("unroll") for (int m = 0; m < 4; ++m) _Pragma("unroll") for (int n = 0; n < 2; ++n) _Pragma("unroll") for (int k = 0; k < 2; ++k) \
;         acc[ai][bj][m][n] = __builtin_amdgcn_mfma_f32_16x16x32_bf16(Bt[n][k], At[m][k], acc[ai][bj][m][n], 0, 0, 0); __builtin_amdgcn_s_setprio(0); } while (0)
; #define PG8_WAIT_V(n) asm volatile("s_waitcnt vmcnt(" #n ")" ::: "memory")
; #define PG8_WAIT_L(n) asm volatile("s_waitcnt lgkmcnt(" #n ")" ::: "memory")
; #define PG8_BAR __builtin_amdgcn_s_barrier()
; #define PG8_SCHED __builtin_amdgcn_sched_barrier(0)
; template <class Epi, class Sched, bool ALIGN_EPI = false, bool SP2 = false>
; __device__ __forceinline__ void gemm_phase(PG8_LAS unsigned char* lds, const Gemm g, const Sched& S, const Epi& E) {
;     ...
;         for (int t = 0; t < nt; t += 2) {
;     ...
;             PG8_LDB(B0, 1, 0); PG8_LDB(B1, 1, 1); PG8_SCHED; PG8_LDA(At, 1, 0); PG8_STAGE(PG8_SA(0, 1), a2 + hstepA, voffA);
;             PG8_WAIT_V(8); PG8_WAIT_L(0); PG8_BAR; PG8_MMA(0, 0, At, B0); PG8_MMA(0, 1, At, B1); PG8_BAR; PG8_SCHED;
;             PG8_LDA(At, 1, 1); PG8_STAGE(PG8_SB(1, 0), b3, voffB); PG8_STAGE(PG8_SB(1, 1), b3 + hstep, voffB); PG8_STAGE(PG8_SA(1, 0), a3, voffA);
;             PG8_WAIT_V(8); PG8_WAIT_L(0); PG8_BAR; PG8_MMA(1, 0, At, B0); PG8_MMA(1, 1, At, B1); PG8_BAR; PG8_SCHED;
	s_add_i32 s70, 0, 0x18000
	v_add_u32_e32 v136, s70, v157
	s_add_i32 s71, 0, 0x1c000
	ds_read_b128 v[150:153], v136
	ds_read_b128 v[162:165], v136 offset:1024
	ds_read_b128 v[166:169], v136 offset:2048
	ds_read_b128 v[170:173], v136 offset:3072
	v_add_u32_e32 v136, s71, v157
	ds_read_b128 v[174:177], v136
	ds_read_b128 v[178:181], v136 offset:1024
	ds_read_b128 v[182:185], v136 offset:2048
	ds_read_b128 v[186:189], v136 offset:3072
	s_add_u32 s68, s86, 0x100000
	s_addc_u32 s69, s87, 0
	s_mov_b32 m0, s55
	ds_read_b128 v[190:193], v160 offset:32768
	ds_read_b128 v[194:197], v160 offset:33792
	ds_read_b128 v[198:201], v160 offset:34816
	ds_read_b128 v[202:205], v160 offset:35840
	ds_read_b128 v[206:209], v160 offset:36864
	ds_read_b128 v[210:213], v160 offset:37888
	ds_read_b128 v[214:217], v160 offset:38912
	ds_read_b128 v[218:221], v160 offset:39936
	global_load_lds_dwordx4 v134, s[68:69]
	s_mov_b32 m0, s56
	s_nop 0
	global_load_lds_dwordx4 v130, s[68:69]
	s_waitcnt vmcnt(8)
	s_waitcnt lgkmcnt(0)
	s_barrier
	s_setprio 1
	s_waitcnt lgkmcnt(0)
	v_mfma_f32_16x16x32_bf16 v[124:127], v[150:153], v[190:193], v[124:127]
	v_mfma_f32_16x16x32_bf16 v[120:123], v[166:169], v[190:193], v[120:123]
	v_mfma_f32_16x16x32_bf16 v[108:111], v[150:153], v[198:201], v[108:111]
	v_mfma_f32_16x16x32_bf16 v[104:107], v[166:169], v[198:201], v[104:107]
	v_mfma_f32_16x16x32_bf16 v[92:95], v[150:153], v[206:209], v[92:95]
	v_mfma_f32_16x16x32_bf16 v[88:91], v[166:169], v[206:209], v[88:91]
	v_mfma_f32_16x16x32_bf16 v[76:79], v[150:153], v[214:217], v[76:79]
	v_mfma_f32_16x16x32_bf16 v[72:75], v[166:169], v[214:217], v[72:75]
	v_mfma_f32_16x16x32_bf16 v[124:127], v[162:165], v[194:197], v[124:127]
	v_mfma_f32_16x16x32_bf16 v[120:123], v[170:173], v[194:197], v[120:123]
	v_mfma_f32_16x16x32_bf16 v[108:111], v[162:165], v[202:205], v[108:111]
	v_mfma_f32_16x16x32_bf16 v[104:107], v[170:173], v[202:205], v[104:107]
	v_mfma_f32_16x16x32_bf16 v[92:95], v[162:165], v[210:213], v[92:95]
	v_mfma_f32_16x16x32_bf16 v[88:91], v[170:173], v[210:213], v[88:91]
	v_mfma_f32_16x16x32_bf16 v[76:79], v[162:165], v[218:221], v[76:79]
	v_mfma_f32_16x16x32_bf16 v[72:75], v[170:173], v[218:221], v[72:75]
	s_setprio 0
	s_setprio 1
	v_mfma_f32_16x16x32_bf16 v[116:119], v[174:177], v[190:193], v[116:119]
	v_mfma_f32_16x16x32_bf16 v[112:115], v[182:185], v[190:193], v[112:115]
	v_mfma_f32_16x16x32_bf16 v[100:103], v[174:177], v[198:201], v[100:103]
	v_mfma_f32_16x16x32_bf16 v[96:99], v[182:185], v[198:201], v[96:99]
	v_mfma_f32_16x16x32_bf16 v[84:87], v[174:177], v[206:209], v[84:87]
	v_mfma_f32_16x16x32_bf16 v[80:83], v[182:185], v[206:209], v[80:83]
	v_mfma_f32_16x16x32_bf16 v[68:71], v[174:177], v[214:217], v[68:71]
	v_mfma_f32_16x16x32_bf16 v[64:67], v[182:185], v[214:217], v[64:67]
	v_mfma_f32_16x16x32_bf16 v[116:119], v[178:181], v[194:197], v[116:119]
	v_mfma_f32_16x16x32_bf16 v[112:115], v[186:189], v[194:197], v[112:115]
	v_mfma_f32_16x16x32_bf16 v[100:103], v[178:181], v[202:205], v[100:103]
	v_mfma_f32_16x16x32_bf16 v[96:99], v[186:189], v[202:205], v[96:99]
	v_mfma_f32_16x16x32_bf16 v[84:87], v[178:181], v[210:213], v[84:87]
	v_mfma_f32_16x16x32_bf16 v[80:83], v[186:189], v[210:213], v[80:83]
	v_mfma_f32_16x16x32_bf16 v[68:71], v[178:181], v[218:221], v[68:71]
	v_mfma_f32_16x16x32_bf16 v[64:67], v[186:189], v[218:221], v[64:67]
	s_setprio 0
	s_barrier
	s_add_i32 s68, s70, s33
	s_mov_b32 m0, s68
	ds_read_b128 v[190:193], v160 offset:49152
	ds_read_b128 v[194:197], v160 offset:50176
	ds_read_b128 v[198:201], v160 offset:51200
	ds_read_b128 v[202:205], v160 offset:52224
	ds_read_b128 v[206:209], v160 offset:53248
	ds_read_b128 v[210:213], v160 offset:54272
	ds_read_b128 v[214:217], v160 offset:55296
	ds_read_b128 v[218:221], v160 offset:56320
	global_load_lds_dwordx4 v132, s[98:99]
	s_add_i32 m0, s68, 0x2000
	s_add_u32 s68, s84, 0x100080
	s_addc_u32 s69, s85, 0
	s_add_i32 s70, s71, s33
	global_load_lds_dwordx4 v128, s[98:99]
	s_mov_b32 m0, s70
	s_nop 0
	global_load_lds_dwordx4 v132, s[68:69]
	s_add_i32 m0, s70, 0x2000
	s_nop 0
	global_load_lds_dwordx4 v128, s[68:69]
	s_mov_b32 m0, s60
	s_nop 0
	global_load_lds_dwordx4 v134, s[100:101]
	s_mov_b32 m0, s61
	s_nop 0
	global_load_lds_dwordx4 v130, s[100:101]
	s_waitcnt vmcnt(8)
	s_waitcnt lgkmcnt(0)
	s_barrier
	s_setprio 1
	s_waitcnt lgkmcnt(0)
	v_mfma_f32_16x16x32_bf16 v[60:63], v[150:153], v[190:193], v[60:63]
	v_mfma_f32_16x16x32_bf16 v[56:59], v[166:169], v[190:193], v[56:59]
	v_mfma_f32_16x16x32_bf16 v[44:47], v[150:153], v[198:201], v[44:47]
	v_mfma_f32_16x16x32_bf16 v[40:43], v[166:169], v[198:201], v[40:43]
	v_mfma_f32_16x16x32_bf16 v[28:31], v[150:153], v[206:209], v[28:31]
	v_mfma_f32_16x16x32_bf16 v[24:27], v[166:169], v[206:209], v[24:27]
	v_mfma_f32_16x16x32_bf16 v[12:15], v[150:153], v[214:217], v[12:15]
	v_mfma_f32_16x16x32_bf16 v[8:11], v[166:169], v[214:217], v[8:11]
	v_mfma_f32_16x16x32_bf16 v[60:63], v[162:165], v[194:197], v[60:63]
	v_mfma_f32_16x16x32_bf16 v[56:59], v[170:173], v[194:197], v[56:59]
	v_mfma_f32_16x16x32_bf16 v[44:47], v[162:165], v[202:205], v[44:47]
	v_mfma_f32_16x16x32_bf16 v[40:43], v[170:173], v[202:205], v[40:43]
	v_mfma_f32_16x16x32_bf16 v[28:31], v[162:165], v[210:213], v[28:31]
	v_mfma_f32_16x16x32_bf16 v[24:27], v[170:173], v[210:213], v[24:27]
	v_mfma_f32_16x16x32_bf16 v[12:15], v[162:165], v[218:221], v[12:15]
	v_mfma_f32_16x16x32_bf16 v[8:11], v[170:173], v[218:221], v[8:11]
	s_setprio 0
	s_setprio 1
	v_mfma_f32_16x16x32_bf16 v[52:55], v[174:177], v[190:193], v[52:55]
	v_mfma_f32_16x16x32_bf16 v[48:51], v[182:185], v[190:193], v[48:51]
	v_mfma_f32_16x16x32_bf16 v[36:39], v[174:177], v[198:201], v[36:39]
	v_mfma_f32_16x16x32_bf16 v[32:35], v[182:185], v[198:201], v[32:35]
	v_mfma_f32_16x16x32_bf16 v[20:23], v[174:177], v[206:209], v[20:23]
	v_mfma_f32_16x16x32_bf16 v[16:19], v[182:185], v[206:209], v[16:19]
	v_mfma_f32_16x16x32_bf16 v[4:7], v[174:177], v[214:217], v[4:7]
	v_mfma_f32_16x16x32_bf16 v[0:3], v[182:185], v[214:217], v[0:3]
	v_mfma_f32_16x16x32_bf16 v[52:55], v[178:181], v[194:197], v[52:55]
	v_mfma_f32_16x16x32_bf16 v[48:51], v[186:189], v[194:197], v[48:51]
	v_mfma_f32_16x16x32_bf16 v[36:39], v[178:181], v[202:205], v[36:39]
	v_mfma_f32_16x16x32_bf16 v[32:35], v[186:189], v[202:205], v[32:35]
	v_mfma_f32_16x16x32_bf16 v[20:23], v[178:181], v[210:213], v[20:23]
	v_mfma_f32_16x16x32_bf16 v[16:19], v[186:189], v[210:213], v[16:19]
	v_mfma_f32_16x16x32_bf16 v[4:7], v[178:181], v[218:221], v[4:7]
	v_mfma_f32_16x16x32_bf16 v[0:3], v[186:189], v[218:221], v[0:3]
	s_setprio 0
	s_barrier
	s_add_i32 s67, s67, 2
	s_add_u32 s34, s34, 0x100
	s_addc_u32 s35, s35, 0
	s_add_u32 s65, s65, 0x100
	s_addc_u32 s66, s66, 0
	s_cmp_gt_u32 s67, 61
	s_cbranch_scc0 .LBB0_115
	s_and_b64 vcc, exec, s[14:15]
	s_cbranch_vccz .LBB0_118
	s_barrier

; #define PG8_STAGE(bufoff, gbase, voff) do { _Pragma("unroll") for (int _i = 0; _i < 2; ++_i) \
;         __builtin_amdgcn_global_load_lds((const unsigned*)((const char*)(gbase) + (voff)[_i]), (PG8_LAS unsigned*)(lds + (bufoff) + ldsw + _i * 8192), 16, 0, 0); } while (0)
; #define PG8_LDA(dst, b, h) do { _Pragma("unroll") for (int m = 0; m < 4; ++m) _Pragma("unroll") for (int k = 0; k < 2; ++k) dst[m][k] = *(const PG8_LAS bf16x8*)(lds + PG8_SA(b, h) + aoff + m * 2048 + k * 1024); } while (0)
; #define PG8_LDB(dst, b, h) do { _Pragma("unroll") for (int n = 0; n < 2; ++n) _Pragma("unroll") for (int k = 0; k < 2; ++k) dst[n][k] = *(const PG8_LAS bf16x8*)(lds + PG8_SB(b, h) + boff + n * 2048 + k * 1024); } while (0)
; #define PG8_MMA(ai, bj, At, Bt) do { __builtin_amdgcn_s_setprio(1); _Pragma("unroll") for (int m = 0; m < 4; ++m) _Pragma("unroll") for (int n = 0; n < 2; ++n) _Pragma("unroll") for (int k = 0; k < 2; ++k) \
;         acc[ai][bj][m][n] = __builtin_amdgcn_mfma_f32_16x16x32_bf16(Bt[n][k], At[m][k], acc[ai][bj][m][n], 0, 0, 0); __builtin_amdgcn_s_setprio(0); } while (0)
; #define PG8_WAIT_V(n) asm volatile("s_waitcnt vmcnt(" #n ")" ::: "memory")
; #define PG8_WAIT_L(n) asm volatile("s_waitcnt lgkmcnt(" #n ")" ::: "memory")
; #define PG8_BAR __builtin_amdgcn_s_barrier()
; #define PG8_SCHED __builtin_amdgcn_sched_barrier(0)
; template <class Epi, class Sched, bool ALIGN_EPI = false, bool SP2 = false>
; __device__ __forceinline__ void gemm_phase(PG8_LAS unsigned char* lds, const Gemm g, const Sched& S, const Epi& E) {
;     ...
;             PG8_LDB(B0, 0, 0); PG8_LDB(B1, 0, 1); PG8_SCHED; PG8_LDA(At, 0, 0); PG8_STAGE(PG8_SA(1, 1), a1 + hstepA, voffA);
;             PG8_WAIT_V(8); PG8_WAIT_L(0); PG8_BAR; PG8_MMA(0, 0, At, B0); PG8_MMA(0, 1, At, B1); PG8_BAR; PG8_SCHED;
;             PG8_LDA(At, 0, 1); PG8_STAGE(PG8_SB(0, 0), b2, voffB); PG8_STAGE(PG8_SB(0, 1), b2 + hstep, voffB); PG8_STAGE(PG8_SA(0, 0), a2, voffA);
;             PG8_WAIT_V(8); PG8_WAIT_L(0); PG8_BAR; PG8_MMA(1, 0, At, B0); PG8_MMA(1, 1, At, B1); PG8_BAR; PG8_SCHED;
.LBB0_1198:
	ds_read_b128 v[144:147], v153
	ds_read_b128 v[158:161], v153 offset:1024
	ds_read_b128 v[162:165], v153 offset:2048
	ds_read_b128 v[166:169], v153 offset:3072
	ds_read_b128 v[170:173], v154
	ds_read_b128 v[174:177], v154 offset:1024
	ds_read_b128 v[178:181], v154 offset:2048
	ds_read_b128 v[182:185], v154 offset:3072
	s_add_u32 s38, s34, 0xfff00080
	s_addc_u32 s39, s35, -1
	s_cmp_eq_u32 s65, 60
	s_cselect_b32 s41, s21, s39
	s_cselect_b32 s40, s27, s38
	s_cselect_b32 s39, s19, s64
	s_cselect_b32 s38, s62, s63
	s_add_i32 m0, s31, 0xc000
	ds_read_b128 v[186:189], v155
	ds_read_b128 v[190:193], v155 offset:1024
	ds_read_b128 v[194:197], v155 offset:2048
	ds_read_b128 v[198:201], v155 offset:3072
	ds_read_b128 v[202:205], v155 offset:4096
	ds_read_b128 v[206:209], v155 offset:5120
	ds_read_b128 v[210:213], v155 offset:6144
	ds_read_b128 v[214:217], v155 offset:7168
	global_load_lds_dwordx4 v136, s[34:35]
	s_add_i32 m0, s31, 0xe000
	s_nop 0
	global_load_lds_dwordx4 v138, s[34:35]
	s_waitcnt vmcnt(8)
	s_waitcnt lgkmcnt(0)
	s_barrier
	s_setprio 1
	s_waitcnt lgkmcnt(0)
	v_mfma_f32_16x16x32_bf16 v[124:127], v[144:147], v[186:189], v[124:127]
	v_mfma_f32_16x16x32_bf16 v[120:123], v[162:165], v[186:189], v[120:123]
	v_mfma_f32_16x16x32_bf16 v[108:111], v[144:147], v[194:197], v[108:111]
	v_mfma_f32_16x16x32_bf16 v[48:51], v[162:165], v[194:197], v[48:51]
	v_mfma_f32_16x16x32_bf16 v[100:103], v[144:147], v[202:205], v[100:103]
	v_mfma_f32_16x16x32_bf16 v[64:67], v[162:165], v[202:205], v[64:67]
	v_mfma_f32_16x16x32_bf16 v[92:95], v[144:147], v[210:213], v[92:95]
	v_mfma_f32_16x16x32_bf16 v[80:83], v[162:165], v[210:213], v[80:83]
	v_mfma_f32_16x16x32_bf16 v[124:127], v[158:161], v[190:193], v[124:127]
	v_mfma_f32_16x16x32_bf16 v[120:123], v[166:169], v[190:193], v[120:123]
	v_mfma_f32_16x16x32_bf16 v[108:111], v[158:161], v[198:201], v[108:111]
	v_mfma_f32_16x16x32_bf16 v[48:51], v[166:169], v[198:201], v[48:51]
	v_mfma_f32_16x16x32_bf16 v[100:103], v[158:161], v[206:209], v[100:103]
	v_mfma_f32_16x16x32_bf16 v[64:67], v[166:169], v[206:209], v[64:67]
	v_mfma_f32_16x16x32_bf16 v[92:95], v[158:161], v[214:217], v[92:95]
	v_mfma_f32_16x16x32_bf16 v[80:83], v[166:169], v[214:217], v[80:83]
	s_setprio 0
	s_setprio 1
	v_mfma_f32_16x16x32_bf16 v[116:119], v[170:173], v[186:189], v[116:119]
	v_mfma_f32_16x16x32_bf16 v[112:115], v[178:181], v[186:189], v[112:115]
	v_mfma_f32_16x16x32_bf16 v[104:107], v[170:173], v[194:197], v[104:107]
	v_mfma_f32_16x16x32_bf16 v[52:55], v[178:181], v[194:197], v[52:55]
	v_mfma_f32_16x16x32_bf16 v[96:99], v[170:173], v[202:205], v[96:99]
	v_mfma_f32_16x16x32_bf16 v[76:79], v[178:181], v[202:205], v[76:79]
	v_mfma_f32_16x16x32_bf16 v[88:91], v[170:173], v[210:213], v[88:91]
	v_mfma_f32_16x16x32_bf16 v[84:87], v[178:181], v[210:213], v[84:87]
	v_mfma_f32_16x16x32_bf16 v[116:119], v[174:177], v[190:193], v[116:119]
	v_mfma_f32_16x16x32_bf16 v[112:115], v[182:185], v[190:193], v[112:115]
	v_mfma_f32_16x16x32_bf16 v[104:107], v[174:177], v[198:201], v[104:107]
	v_mfma_f32_16x16x32_bf16 v[52:55], v[182:185], v[198:201], v[52:55]
	v_mfma_f32_16x16x32_bf16 v[96:99], v[174:177], v[206:209], v[96:99]
	v_mfma_f32_16x16x32_bf16 v[76:79], v[182:185], v[206:209], v[76:79]
	v_mfma_f32_16x16x32_bf16 v[88:91], v[174:177], v[214:217], v[88:91]
	v_mfma_f32_16x16x32_bf16 v[84:87], v[182:185], v[214:217], v[84:87]
	s_setprio 0
	s_barrier
	s_add_u32 s98, s38, s14
	s_addc_u32 s99, s39, s15
	s_add_u32 s100, s40, s14
	s_addc_u32 s101, s41, s15
	s_add_i32 s66, s60, s33
	s_mov_b32 m0, s66
	ds_read_b128 v[186:189], v155 offset:16384
	ds_read_b128 v[190:193], v155 offset:17408
	ds_read_b128 v[194:197], v155 offset:18432
	ds_read_b128 v[198:201], v155 offset:19456
	ds_read_b128 v[202:205], v155 offset:20480
	ds_read_b128 v[206:209], v155 offset:21504
	ds_read_b128 v[210:213], v155 offset:22528
	ds_read_b128 v[214:217], v155 offset:23552
	global_load_lds_dwordx4 v130, s[38:39]
	s_add_i32 m0, s66, 0x2000
	s_add_u32 s66, s38, 0x100000
	s_addc_u32 s67, s39, 0
	s_add_i32 s68, s61, s33
	global_load_lds_dwordx4 v134, s[38:39]
	s_mov_b32 m0, s68
	s_nop 0
	global_load_lds_dwordx4 v130, s[66:67]
	s_add_i32 m0, s68, 0x2000
	s_nop 0
	global_load_lds_dwordx4 v134, s[66:67]
	s_mov_b32 m0, s31
	s_nop 0
	global_load_lds_dwordx4 v128, s[40:41]
	s_mov_b32 m0, s52
	s_nop 0
	global_load_lds_dwordx4 v132, s[40:41]
	s_waitcnt vmcnt(8)
	s_waitcnt lgkmcnt(0)
	s_barrier
	s_setprio 1
	s_waitcnt lgkmcnt(0)
	v_mfma_f32_16x16x32_bf16 v[72:75], v[144:147], v[186:189], v[72:75]
	v_mfma_f32_16x16x32_bf16 v[68:71], v[162:165], v[186:189], v[68:71]
	v_mfma_f32_16x16x32_bf16 v[44:47], v[144:147], v[194:197], v[44:47]
	v_mfma_f32_16x16x32_bf16 v[40:43], v[162:165], v[194:197], v[40:43]
	v_mfma_f32_16x16x32_bf16 v[28:31], v[144:147], v[202:205], v[28:31]
	v_mfma_f32_16x16x32_bf16 v[24:27], v[162:165], v[202:205], v[24:27]
	v_mfma_f32_16x16x32_bf16 v[12:15], v[144:147], v[210:213], v[12:15]
	v_mfma_f32_16x16x32_bf16 v[8:11], v[162:165], v[210:213], v[8:11]
	v_mfma_f32_16x16x32_bf16 v[72:75], v[158:161], v[190:193], v[72:75]
	v_mfma_f32_16x16x32_bf16 v[68:71], v[166:169], v[190:193], v[68:71]
	v_mfma_f32_16x16x32_bf16 v[44:47], v[158:161], v[198:201], v[44:47]
	v_mfma_f32_16x16x32_bf16 v[40:43], v[166:169], v[198:201], v[40:43]
	v_mfma_f32_16x16x32_bf16 v[28:31], v[158:161], v[206:209], v[28:31]
	v_mfma_f32_16x16x32_bf16 v[24:27], v[166:169], v[206:209], v[24:27]
	v_mfma_f32_16x16x32_bf16 v[12:15], v[158:161], v[214:217], v[12:15]
	v_mfma_f32_16x16x32_bf16 v[8:11], v[166:169], v[214:217], v[8:11]
	s_setprio 0
	s_setprio 1
	v_mfma_f32_16x16x32_bf16 v[60:63], v[170:173], v[186:189], v[60:63]
	v_mfma_f32_16x16x32_bf16 v[56:59], v[178:181], v[186:189], v[56:59]
	v_mfma_f32_16x16x32_bf16 v[36:39], v[170:173], v[194:197], v[36:39]
	v_mfma_f32_16x16x32_bf16 v[32:35], v[178:181], v[194:197], v[32:35]
	v_mfma_f32_16x16x32_bf16 v[20:23], v[170:173], v[202:205], v[20:23]
	v_mfma_f32_16x16x32_bf16 v[16:19], v[178:181], v[202:205], v[16:19]
	v_mfma_f32_16x16x32_bf16 v[4:7], v[170:173], v[210:213], v[4:7]
	v_mfma_f32_16x16x32_bf16 v[0:3], v[178:181], v[210:213], v[0:3]
	v_mfma_f32_16x16x32_bf16 v[60:63], v[174:177], v[190:193], v[60:63]
	v_mfma_f32_16x16x32_bf16 v[56:59], v[182:185], v[190:193], v[56:59]
	v_mfma_f32_16x16x32_bf16 v[36:39], v[174:177], v[198:201], v[36:39]
	v_mfma_f32_16x16x32_bf16 v[32:35], v[182:185], v[198:201], v[32:35]
	v_mfma_f32_16x16x32_bf16 v[20:23], v[174:177], v[206:209], v[20:23]
	v_mfma_f32_16x16x32_bf16 v[16:19], v[182:185], v[206:209], v[16:19]
	v_mfma_f32_16x16x32_bf16 v[4:7], v[174:177], v[214:217], v[4:7]
	v_mfma_f32_16x16x32_bf16 v[0:3], v[182:185], v[214:217], v[0:3]
	s_setprio 0
	s_barrier
; #define PG8_STAGE(bufoff, gbase, voff) do { _Pragma("unroll") for (int _i = 0; _i < 2; ++_i) \
;         __builtin_amdgcn_global_load_lds((const unsigned*)((const char*)(gbase) + (voff)[_i]), (PG8_LAS unsigned*)(lds + (bufoff) + ldsw + _i * 8192), 16, 0, 0); } while (0)
; #define PG8_LDA(dst, b, h) do { _Pragma("unroll") for (int m = 0; m < 4; ++m) _Pragma("unroll") for (int k = 0; k < 2; ++k) dst[m][k] = *(const PG8_LAS bf16x8*)(lds + PG8_SA(b, h) + aoff + m * 2048 + k * 1024); } while (0)
; #define PG8_LDB(dst, b, h) do { _Pragma("unroll") for (int n = 0; n < 2; ++n) _Pragma("unroll") for (int k = 0; k < 2; ++k) dst[n][k] = *(const PG8_LAS bf16x8*)(lds + PG8_SB(b, h) + boff + n * 2048 + k * 1024); } while (0)
; #define PG8_MMA(ai, bj, At, Bt) do { __builtin_amdgcn_s_setprio(1); _Pragma("unroll") for (int m = 0; m < 4; ++m) _Pragma("unroll") for (int n = 0; n < 2; ++n) _Pragma("unroll") for (int k = 0; k < 2; ++k) \
;         acc[ai][bj][m][n] = __builtin_amdgcn_mfma_f32_16x16x32_bf16(Bt[n][k], At[m][k], acc[ai][bj][m][n], 0, 0, 0); __builtin_amdgcn_s_setprio(0); } while (0)
; #define PG8_WAIT_V(n) asm volatile("s_waitcnt vmcnt(" #n ")" ::: "memory")
; #define PG8_WAIT_L(n) asm volatile("s_waitcnt lgkmcnt(" #n ")" ::: "memory")
; #define PG8_BAR __builtin_amdgcn_s_barrier()
; #define PG8_SCHED __builtin_amdgcn_sched_barrier(0)
; template <class Epi, class Sched, bool ALIGN_EPI = false, bool SP2 = false>
; __device__ __forceinline__ void gemm_phase(PG8_LAS unsigned char* lds, const Gemm g, const Sched& S, const Epi& E) {
;     ...
;         for (int t = 0; t < nt; t += 2) {
;     ...
;             PG8_LDB(B0, 1, 0); PG8_LDB(B1, 1, 1); PG8_SCHED; PG8_LDA(At, 1, 0); PG8_STAGE(PG8_SA(0, 1), a2 + hstepA, voffA);
;             PG8_WAIT_V(8); PG8_WAIT_L(0); PG8_BAR; PG8_MMA(0, 0, At, B0); PG8_MMA(0, 1, At, B1); PG8_BAR; PG8_SCHED;
;             PG8_LDA(At, 1, 1); PG8_STAGE(PG8_SB(1, 0), b3, voffB); PG8_STAGE(PG8_SB(1, 1), b3 + hstep, voffB); PG8_STAGE(PG8_SA(1, 0), a3, voffA);
;             PG8_WAIT_V(8); PG8_WAIT_L(0); PG8_BAR; PG8_MMA(1, 0, At, B0); PG8_MMA(1, 1, At, B1); PG8_BAR; PG8_SCHED;
	s_add_i32 s66, 0, 0x18000
	v_add_u32_e32 v157, s66, v151
	s_add_i32 s67, 0, 0x1c000
	ds_read_b128 v[144:147], v157
	ds_read_b128 v[158:161], v157 offset:1024
	ds_read_b128 v[162:165], v157 offset:2048
	ds_read_b128 v[166:169], v157 offset:3072
	v_add_u32_e32 v157, s67, v151
	ds_read_b128 v[170:173], v157
	ds_read_b128 v[174:177], v157 offset:1024
	ds_read_b128 v[178:181], v157 offset:2048
	ds_read_b128 v[182:185], v157 offset:3072
	s_add_u32 s40, s40, 0x100000
	s_addc_u32 s41, s41, 0
	s_mov_b32 m0, s53
	ds_read_b128 v[186:189], v155 offset:32768
	ds_read_b128 v[190:193], v155 offset:33792
	ds_read_b128 v[194:197], v155 offset:34816
	ds_read_b128 v[198:201], v155 offset:35840
	ds_read_b128 v[202:205], v155 offset:36864
	ds_read_b128 v[206:209], v155 offset:37888
	ds_read_b128 v[210:213], v155 offset:38912
	ds_read_b128 v[214:217], v155 offset:39936
	global_load_lds_dwordx4 v128, s[40:41]
	s_mov_b32 m0, s54
	s_nop 0
	global_load_lds_dwordx4 v132, s[40:41]
	s_waitcnt vmcnt(8)
	s_waitcnt lgkmcnt(0)
	s_barrier
	s_setprio 1
	s_waitcnt lgkmcnt(0)
	v_mfma_f32_16x16x32_bf16 v[124:127], v[144:147], v[186:189], v[124:127]
	v_mfma_f32_16x16x32_bf16 v[120:123], v[162:165], v[186:189], v[120:123]
	v_mfma_f32_16x16x32_bf16 v[108:111], v[144:147], v[194:197], v[108:111]
	v_mfma_f32_16x16x32_bf16 v[48:51], v[162:165], v[194:197], v[48:51]
	v_mfma_f32_16x16x32_bf16 v[100:103], v[144:147], v[202:205], v[100:103]
	v_mfma_f32_16x16x32_bf16 v[64:67], v[162:165], v[202:205], v[64:67]
	v_mfma_f32_16x16x32_bf16 v[92:95], v[144:147], v[210:213], v[92:95]
	v_mfma_f32_16x16x32_bf16 v[80:83], v[162:165], v[210:213], v[80:83]
	v_mfma_f32_16x16x32_bf16 v[124:127], v[158:161], v[190:193], v[124:127]
	v_mfma_f32_16x16x32_bf16 v[120:123], v[166:169], v[190:193], v[120:123]
	v_mfma_f32_16x16x32_bf16 v[108:111], v[158:161], v[198:201], v[108:111]
	v_mfma_f32_16x16x32_bf16 v[48:51], v[166:169], v[198:201], v[48:51]
	v_mfma_f32_16x16x32_bf16 v[100:103], v[158:161], v[206:209], v[100:103]
	v_mfma_f32_16x16x32_bf16 v[64:67], v[166:169], v[206:209], v[64:67]
	v_mfma_f32_16x16x32_bf16 v[92:95], v[158:161], v[214:217], v[92:95]
	v_mfma_f32_16x16x32_bf16 v[80:83], v[166:169], v[214:217], v[80:83]
	s_setprio 0
	s_setprio 1
	v_mfma_f32_16x16x32_bf16 v[116:119], v[170:173], v[186:189], v[116:119]
	v_mfma_f32_16x16x32_bf16 v[112:115], v[178:181], v[186:189], v[112:115]
	v_mfma_f32_16x16x32_bf16 v[104:107], v[170:173], v[194:197], v[104:107]
	v_mfma_f32_16x16x32_bf16 v[52:55], v[178:181], v[194:197], v[52:55]
	v_mfma_f32_16x16x32_bf16 v[96:99], v[170:173], v[202:205], v[96:99]
	v_mfma_f32_16x16x32_bf16 v[76:79], v[178:181], v[202:205], v[76:79]
	v_mfma_f32_16x16x32_bf16 v[88:91], v[170:173], v[210:213], v[88:91]
	v_mfma_f32_16x16x32_bf16 v[84:87], v[178:181], v[210:213], v[84:87]
	v_mfma_f32_16x16x32_bf16 v[116:119], v[174:177], v[190:193], v[116:119]
	v_mfma_f32_16x16x32_bf16 v[112:115], v[182:185], v[190:193], v[112:115]
	v_mfma_f32_16x16x32_bf16 v[104:107], v[174:177], v[198:201], v[104:107]
	v_mfma_f32_16x16x32_bf16 v[52:55], v[182:185], v[198:201], v[52:55]
	v_mfma_f32_16x16x32_bf16 v[96:99], v[174:177], v[206:209], v[96:99]
	v_mfma_f32_16x16x32_bf16 v[76:79], v[182:185], v[206:209], v[76:79]
	v_mfma_f32_16x16x32_bf16 v[88:91], v[174:177], v[214:217], v[88:91]
	v_mfma_f32_16x16x32_bf16 v[84:87], v[182:185], v[214:217], v[84:87]
	s_setprio 0
	s_barrier
	s_add_i32 s40, s66, s33
	s_mov_b32 m0, s40
	ds_read_b128 v[186:189], v155 offset:49152
	ds_read_b128 v[190:193], v155 offset:50176
	ds_read_b128 v[194:197], v155 offset:51200
	ds_read_b128 v[198:201], v155 offset:52224
	ds_read_b128 v[202:205], v155 offset:53248
	ds_read_b128 v[206:209], v155 offset:54272
	ds_read_b128 v[210:213], v155 offset:55296
	ds_read_b128 v[214:217], v155 offset:56320
	global_load_lds_dwordx4 v130, s[98:99]
	s_add_i32 m0, s40, 0x2000
	s_add_u32 s38, s38, 0x100080
	s_addc_u32 s39, s39, 0
	s_add_i32 s40, s67, s33
	global_load_lds_dwordx4 v134, s[98:99]
	s_mov_b32 m0, s40
	s_nop 0
	global_load_lds_dwordx4 v130, s[38:39]
	s_add_i32 m0, s40, 0x2000
	s_nop 0
	global_load_lds_dwordx4 v134, s[38:39]
	s_mov_b32 m0, s56
	s_nop 0
	global_load_lds_dwordx4 v128, s[100:101]
	s_mov_b32 m0, s57
	s_nop 0
	global_load_lds_dwordx4 v132, s[100:101]
	s_waitcnt vmcnt(8)
	s_waitcnt lgkmcnt(0)
	s_barrier
	s_setprio 1
	s_waitcnt lgkmcnt(0)
	v_mfma_f32_16x16x32_bf16 v[72:75], v[144:147], v[186:189], v[72:75]
	v_mfma_f32_16x16x32_bf16 v[68:71], v[162:165], v[186:189], v[68:71]
	v_mfma_f32_16x16x32_bf16 v[44:47], v[144:147], v[194:197], v[44:47]
	v_mfma_f32_16x16x32_bf16 v[40:43], v[162:165], v[194:197], v[40:43]
	v_mfma_f32_16x16x32_bf16 v[28:31], v[144:147], v[202:205], v[28:31]
	v_mfma_f32_16x16x32_bf16 v[24:27], v[162:165], v[202:205], v[24:27]
	v_mfma_f32_16x16x32_bf16 v[12:15], v[144:147], v[210:213], v[12:15]
	v_mfma_f32_16x16x32_bf16 v[8:11], v[162:165], v[210:213], v[8:11]
	v_mfma_f32_16x16x32_bf16 v[72:75], v[158:161], v[190:193], v[72:75]
	v_mfma_f32_16x16x32_bf16 v[68:71], v[166:169], v[190:193], v[68:71]
	v_mfma_f32_16x16x32_bf16 v[44:47], v[158:161], v[198:201], v[44:47]
	v_mfma_f32_16x16x32_bf16 v[40:43], v[166:169], v[198:201], v[40:43]
	v_mfma_f32_16x16x32_bf16 v[28:31], v[158:161], v[206:209], v[28:31]
	v_mfma_f32_16x16x32_bf16 v[24:27], v[166:169], v[206:209], v[24:27]
	v_mfma_f32_16x16x32_bf16 v[12:15], v[158:161], v[214:217], v[12:15]
	v_mfma_f32_16x16x32_bf16 v[8:11], v[166:169], v[214:217], v[8:11]
	s_setprio 0
	s_setprio 1
	v_mfma_f32_16x16x32_bf16 v[60:63], v[170:173], v[186:189], v[60:63]
	v_mfma_f32_16x16x32_bf16 v[56:59], v[178:181], v[186:189], v[56:59]
	v_mfma_f32_16x16x32_bf16 v[36:39], v[170:173], v[194:197], v[36:39]
	v_mfma_f32_16x16x32_bf16 v[32:35], v[178:181], v[194:197], v[32:35]
	v_mfma_f32_16x16x32_bf16 v[20:23], v[170:173], v[202:205], v[20:23]
	v_mfma_f32_16x16x32_bf16 v[16:19], v[178:181], v[202:205], v[16:19]
	v_mfma_f32_16x16x32_bf16 v[4:7], v[170:173], v[210:213], v[4:7]
	v_mfma_f32_16x16x32_bf16 v[0:3], v[178:181], v[210:213], v[0:3]
	v_mfma_f32_16x16x32_bf16 v[60:63], v[174:177], v[190:193], v[60:63]
	v_mfma_f32_16x16x32_bf16 v[56:59], v[182:185], v[190:193], v[56:59]
	v_mfma_f32_16x16x32_bf16 v[36:39], v[174:177], v[198:201], v[36:39]
	v_mfma_f32_16x16x32_bf16 v[32:35], v[182:185], v[198:201], v[32:35]
	v_mfma_f32_16x16x32_bf16 v[20:23], v[174:177], v[206:209], v[20:23]
	v_mfma_f32_16x16x32_bf16 v[16:19], v[182:185], v[206:209], v[16:19]
	v_mfma_f32_16x16x32_bf16 v[4:7], v[174:177], v[214:217], v[4:7]
	v_mfma_f32_16x16x32_bf16 v[0:3], v[182:185], v[214:217], v[0:3]
	s_setprio 0
	s_barrier
	s_add_i32 s65, s65, 2
	s_add_u32 s34, s34, 0x100
	s_addc_u32 s35, s35, 0
	s_add_u32 s63, s63, 0x100
	s_addc_u32 s64, s64, 0
	s_cmp_gt_u32 s65, 61
	s_cbranch_scc0 .LBB0_1198
	s_and_b64 vcc, exec, s[16:17]
	s_cbranch_vccz .LBB0_1201
	s_barrier

; #define PG8_STAGE(bufoff, gbase, voff) do { _Pragma("unroll") for (int _i = 0; _i < 2; ++_i) \
;         __builtin_amdgcn_global_load_lds((const unsigned*)((const char*)(gbase) + (voff)[_i]), (PG8_LAS unsigned*)(lds + (bufoff) + ldsw + _i * 8192), 16, 0, 0); } while (0)
; #define PG8_LDA(dst, b, h) do { _Pragma("unroll") for (int m = 0; m < 4; ++m) _Pragma("unroll") for (int k = 0; k < 2; ++k) dst[m][k] = *(const PG8_LAS bf16x8*)(lds + PG8_SA(b, h) + aoff + m * 2048 + k * 1024); } while (0)
; #define PG8_LDB(dst, b, h) do { _Pragma("unroll") for (int n = 0; n < 2; ++n) _Pragma("unroll") for (int k = 0; k < 2; ++k) dst[n][k] = *(const PG8_LAS bf16x8*)(lds + PG8_SB(b, h) + boff + n * 2048 + k * 1024); } while (0)
; #define PG8_MMA(ai, bj, At, Bt) do { __builtin_amdgcn_s_setprio(1); _Pragma("unroll") for (int m = 0; m < 4; ++m) _Pragma("unroll") for (int n = 0; n < 2; ++n) _Pragma("unroll") for (int k = 0; k < 2; ++k) \
;         acc[ai][bj][m][n] = __builtin_amdgcn_mfma_f32_16x16x32_bf16(Bt[n][k], At[m][k], acc[ai][bj][m][n], 0, 0, 0); __builtin_amdgcn_s_setprio(0); } while (0)
; #define PG8_WAIT_V(n) asm volatile("s_waitcnt vmcnt(" #n ")" ::: "memory")
; #define PG8_WAIT_L(n) asm volatile("s_waitcnt lgkmcnt(" #n ")" ::: "memory")
; #define PG8_BAR __builtin_amdgcn_s_barrier()
; #define PG8_SCHED __builtin_amdgcn_sched_barrier(0)
; template <class Epi, class Sched, bool ALIGN_EPI = false, bool SP2 = false>
; __device__ __forceinline__ void gemm_phase(PG8_LAS unsigned char* lds, const Gemm g, const Sched& S, const Epi& E) {
;     ...
;             PG8_LDB(B0, 0, 0); PG8_LDB(B1, 0, 1); PG8_SCHED; PG8_LDA(At, 0, 0); PG8_STAGE(PG8_SA(1, 1), a1 + hstepA, voffA);
;             PG8_WAIT_V(8); PG8_WAIT_L(0); PG8_BAR; PG8_MMA(0, 0, At, B0); PG8_MMA(0, 1, At, B1); PG8_BAR; PG8_SCHED;
;             PG8_LDA(At, 0, 1); PG8_STAGE(PG8_SB(0, 0), b2, voffB); PG8_STAGE(PG8_SB(0, 1), b2 + hstep, voffB); PG8_STAGE(PG8_SA(0, 0), a2, voffA);
;             PG8_WAIT_V(8); PG8_WAIT_L(0); PG8_BAR; PG8_MMA(1, 0, At, B0); PG8_MMA(1, 1, At, B1); PG8_BAR; PG8_SCHED;
.LBB0_1310:
	ds_read_b128 v[128:131], v236
	ds_read_b128 v[132:135], v236 offset:1024
	ds_read_b128 v[136:139], v236 offset:2048
	ds_read_b128 v[140:143], v236 offset:3072
	ds_read_b128 v[144:147], v237
	ds_read_b128 v[148:151], v237 offset:1024
	ds_read_b128 v[152:155], v237 offset:2048
	ds_read_b128 v[156:159], v237 offset:3072
	s_add_u32 s96, s94, 0x100
	s_addc_u32 s97, s95, 0
	s_cmp_eq_u32 s71, 60
	s_cselect_b32 s7, s41, s97
	s_cselect_b32 s6, s52, s96
	s_cselect_b32 vcc_hi, s39, s70
	s_cselect_b32 vcc_lo, s53, s69
	v_lshl_add_u64 v[164:165], s[94:95], 0, v[178:179]
	s_add_i32 m0, s56, 0xc000
	ds_read_b128 v[160:163], v238
	ds_read_b128 v[186:189], v238 offset:1024
	ds_read_b128 v[190:193], v238 offset:2048
	ds_read_b128 v[194:197], v238 offset:3072
	ds_read_b128 v[198:201], v238 offset:4096
	ds_read_b128 v[202:205], v238 offset:5120
	ds_read_b128 v[206:209], v238 offset:6144
	ds_read_b128 v[210:213], v238 offset:7168
	global_load_lds_dwordx4 v[164:165], off
	v_lshl_add_u64 v[164:165], s[94:95], 0, v[180:181]
	s_add_i32 m0, s56, 0xe000
	s_nop 0
	global_load_lds_dwordx4 v[164:165], off
	s_waitcnt vmcnt(8)
	s_waitcnt lgkmcnt(0)
	s_barrier
	s_setprio 1
	s_waitcnt lgkmcnt(0)
	v_mfma_f32_16x16x32_bf16 v[124:127], v[128:131], v[160:163], v[124:127]
	v_mfma_f32_16x16x32_bf16 v[120:123], v[136:139], v[160:163], v[120:123]
	v_mfma_f32_16x16x32_bf16 v[108:111], v[128:131], v[190:193], v[108:111]
	v_mfma_f32_16x16x32_bf16 v[104:107], v[136:139], v[190:193], v[104:107]
	v_mfma_f32_16x16x32_bf16 v[92:95], v[128:131], v[198:201], v[92:95]
	v_mfma_f32_16x16x32_bf16 v[88:91], v[136:139], v[198:201], v[88:91]
	v_mfma_f32_16x16x32_bf16 v[76:79], v[128:131], v[206:209], v[76:79]
	v_mfma_f32_16x16x32_bf16 v[72:75], v[136:139], v[206:209], v[72:75]
	v_mfma_f32_16x16x32_bf16 v[124:127], v[132:135], v[186:189], v[124:127]
	v_mfma_f32_16x16x32_bf16 v[120:123], v[140:143], v[186:189], v[120:123]
	v_mfma_f32_16x16x32_bf16 v[108:111], v[132:135], v[194:197], v[108:111]
	v_mfma_f32_16x16x32_bf16 v[104:107], v[140:143], v[194:197], v[104:107]
	v_mfma_f32_16x16x32_bf16 v[92:95], v[132:135], v[202:205], v[92:95]
	v_mfma_f32_16x16x32_bf16 v[88:91], v[140:143], v[202:205], v[88:91]
	v_mfma_f32_16x16x32_bf16 v[76:79], v[132:135], v[210:213], v[76:79]
	v_mfma_f32_16x16x32_bf16 v[72:75], v[140:143], v[210:213], v[72:75]
	s_setprio 0
	s_setprio 1
	v_mfma_f32_16x16x32_bf16 v[116:119], v[144:147], v[160:163], v[116:119]
	v_mfma_f32_16x16x32_bf16 v[112:115], v[152:155], v[160:163], v[112:115]
	v_mfma_f32_16x16x32_bf16 v[100:103], v[144:147], v[190:193], v[100:103]
	v_mfma_f32_16x16x32_bf16 v[96:99], v[152:155], v[190:193], v[96:99]
	v_mfma_f32_16x16x32_bf16 v[84:87], v[144:147], v[198:201], v[84:87]
	v_mfma_f32_16x16x32_bf16 v[80:83], v[152:155], v[198:201], v[80:83]
	v_mfma_f32_16x16x32_bf16 v[68:71], v[144:147], v[206:209], v[68:71]
	v_mfma_f32_16x16x32_bf16 v[64:67], v[152:155], v[206:209], v[64:67]
	v_mfma_f32_16x16x32_bf16 v[116:119], v[148:151], v[186:189], v[116:119]
	v_mfma_f32_16x16x32_bf16 v[112:115], v[156:159], v[186:189], v[112:115]
	v_mfma_f32_16x16x32_bf16 v[100:103], v[148:151], v[194:197], v[100:103]
	v_mfma_f32_16x16x32_bf16 v[96:99], v[156:159], v[194:197], v[96:99]
	v_mfma_f32_16x16x32_bf16 v[84:87], v[148:151], v[202:205], v[84:87]
	v_mfma_f32_16x16x32_bf16 v[80:83], v[156:159], v[202:205], v[80:83]
	v_mfma_f32_16x16x32_bf16 v[68:71], v[148:151], v[210:213], v[68:71]
	v_mfma_f32_16x16x32_bf16 v[64:67], v[156:159], v[210:213], v[64:67]
	s_setprio 0
	s_barrier
	s_add_u32 s98, vcc_lo, s10
	s_addc_u32 s99, vcc_hi, s11
	s_add_u32 s100, s6, s10
	s_addc_u32 s101, s7, s11
	s_add_i32 s72, s65, s55
	s_mov_b32 m0, s72
	ds_read_b128 v[160:163], v238 offset:16384
	ds_read_b128 v[186:189], v238 offset:17408
	ds_read_b128 v[190:193], v238 offset:18432
	ds_read_b128 v[194:197], v238 offset:19456
	ds_read_b128 v[198:201], v238 offset:20480
	ds_read_b128 v[202:205], v238 offset:21504
	ds_read_b128 v[206:209], v238 offset:22528
	ds_read_b128 v[210:213], v238 offset:23552
	global_load_lds_dwordx4 v168, vcc
	s_add_i32 m0, s72, 0x2000
	s_add_u32 s72, vcc_lo, 0x100000
	s_addc_u32 s73, vcc_hi, 0
	s_add_i32 s74, s66, s55
	global_load_lds_dwordx4 v172, vcc
	s_mov_b32 m0, s74
	s_nop 0
	global_load_lds_dwordx4 v168, s[72:73]
	s_add_i32 m0, s74, 0x2000
	s_nop 0
	global_load_lds_dwordx4 v172, s[72:73]
	s_mov_b32 m0, s56
	s_nop 0
	global_load_lds_dwordx4 v166, s[6:7]
	s_mov_b32 m0, s57
	s_nop 0
	global_load_lds_dwordx4 v170, s[6:7]
	s_waitcnt vmcnt(8)
	s_waitcnt lgkmcnt(0)
	s_barrier
; #define PG8_STAGE(bufoff, gbase, voff) do { _Pragma("unroll") for (int _i = 0; _i < 2; ++_i) \
;         __builtin_amdgcn_global_load_lds((const unsigned*)((const char*)(gbase) + (voff)[_i]), (PG8_LAS unsigned*)(lds + (bufoff) + ldsw + _i * 8192), 16, 0, 0); } while (0)
; #define PG8_LDA(dst, b, h) do { _Pragma("unroll") for (int m = 0; m < 4; ++m) _Pragma("unroll") for (int k = 0; k < 2; ++k) dst[m][k] = *(const PG8_LAS bf16x8*)(lds + PG8_SA(b, h) + aoff + m * 2048 + k * 1024); } while (0)
; #define PG8_LDB(dst, b, h) do { _Pragma("unroll") for (int n = 0; n < 2; ++n) _Pragma("unroll") for (int k = 0; k < 2; ++k) dst[n][k] = *(const PG8_LAS bf16x8*)(lds + PG8_SB(b, h) + boff + n * 2048 + k * 1024); } while (0)
; #define PG8_MMA(ai, bj, At, Bt) do { __builtin_amdgcn_s_setprio(1); _Pragma("unroll") for (int m = 0; m < 4; ++m) _Pragma("unroll") for (int n = 0; n < 2; ++n) _Pragma("unroll") for (int k = 0; k < 2; ++k) \
;         acc[ai][bj][m][n] = __builtin_amdgcn_mfma_f32_16x16x32_bf16(Bt[n][k], At[m][k], acc[ai][bj][m][n], 0, 0, 0); __builtin_amdgcn_s_setprio(0); } while (0)
; #define PG8_WAIT_V(n) asm volatile("s_waitcnt vmcnt(" #n ")" ::: "memory")
; #define PG8_WAIT_L(n) asm volatile("s_waitcnt lgkmcnt(" #n ")" ::: "memory")
; #define PG8_BAR __builtin_amdgcn_s_barrier()
; #define PG8_SCHED __builtin_amdgcn_sched_barrier(0)
; template <class Epi, class Sched, bool ALIGN_EPI = false, bool SP2 = false>
; __device__ __forceinline__ void gemm_phase(PG8_LAS unsigned char* lds, const Gemm g, const Sched& S, const Epi& E) {
;     ...
;             PG8_WAIT_V(8); PG8_WAIT_L(0); PG8_BAR; PG8_MMA(1, 0, At, B0); PG8_MMA(1, 1, At, B1); PG8_BAR; PG8_SCHED;
;             PG8_LDB(B0, 1, 0); PG8_LDB(B1, 1, 1); PG8_SCHED; PG8_LDA(At, 1, 0); PG8_STAGE(PG8_SA(0, 1), a2 + hstepA, voffA);
;             PG8_WAIT_V(8); PG8_WAIT_L(0); PG8_BAR; PG8_MMA(0, 0, At, B0); PG8_MMA(0, 1, At, B1); PG8_BAR; PG8_SCHED;
	s_setprio 1
	s_waitcnt lgkmcnt(0)
	v_mfma_f32_16x16x32_bf16 v[60:63], v[128:131], v[160:163], v[60:63]
	v_mfma_f32_16x16x32_bf16 v[56:59], v[136:139], v[160:163], v[56:59]
	v_mfma_f32_16x16x32_bf16 v[44:47], v[128:131], v[190:193], v[44:47]
	v_mfma_f32_16x16x32_bf16 v[40:43], v[136:139], v[190:193], v[40:43]
	v_mfma_f32_16x16x32_bf16 v[28:31], v[128:131], v[198:201], v[28:31]
	v_mfma_f32_16x16x32_bf16 v[24:27], v[136:139], v[198:201], v[24:27]
	v_mfma_f32_16x16x32_bf16 v[12:15], v[128:131], v[206:209], v[12:15]
	v_mfma_f32_16x16x32_bf16 v[8:11], v[136:139], v[206:209], v[8:11]
	v_mfma_f32_16x16x32_bf16 v[60:63], v[132:135], v[186:189], v[60:63]
	v_mfma_f32_16x16x32_bf16 v[56:59], v[140:143], v[186:189], v[56:59]
	v_mfma_f32_16x16x32_bf16 v[44:47], v[132:135], v[194:197], v[44:47]
	v_mfma_f32_16x16x32_bf16 v[40:43], v[140:143], v[194:197], v[40:43]
	v_mfma_f32_16x16x32_bf16 v[28:31], v[132:135], v[202:205], v[28:31]
	v_mfma_f32_16x16x32_bf16 v[24:27], v[140:143], v[202:205], v[24:27]
	v_mfma_f32_16x16x32_bf16 v[12:15], v[132:135], v[210:213], v[12:15]
	v_mfma_f32_16x16x32_bf16 v[8:11], v[140:143], v[210:213], v[8:11]
	s_setprio 0
	s_setprio 1
	v_mfma_f32_16x16x32_bf16 v[52:55], v[144:147], v[160:163], v[52:55]
	v_mfma_f32_16x16x32_bf16 v[48:51], v[152:155], v[160:163], v[48:51]
	v_mfma_f32_16x16x32_bf16 v[36:39], v[144:147], v[190:193], v[36:39]
	v_mfma_f32_16x16x32_bf16 v[32:35], v[152:155], v[190:193], v[32:35]
	v_mfma_f32_16x16x32_bf16 v[20:23], v[144:147], v[198:201], v[20:23]
	v_mfma_f32_16x16x32_bf16 v[16:19], v[152:155], v[198:201], v[16:19]
	v_mfma_f32_16x16x32_bf16 v[4:7], v[144:147], v[206:209], v[4:7]
	v_mfma_f32_16x16x32_bf16 v[0:3], v[152:155], v[206:209], v[0:3]
	v_mfma_f32_16x16x32_bf16 v[52:55], v[148:151], v[186:189], v[52:55]
	v_mfma_f32_16x16x32_bf16 v[48:51], v[156:159], v[186:189], v[48:51]
	v_mfma_f32_16x16x32_bf16 v[36:39], v[148:151], v[194:197], v[36:39]
	v_mfma_f32_16x16x32_bf16 v[32:35], v[156:159], v[194:197], v[32:35]
	v_mfma_f32_16x16x32_bf16 v[20:23], v[148:151], v[202:205], v[20:23]
	v_mfma_f32_16x16x32_bf16 v[16:19], v[156:159], v[202:205], v[16:19]
	v_mfma_f32_16x16x32_bf16 v[4:7], v[148:151], v[210:213], v[4:7]
	v_mfma_f32_16x16x32_bf16 v[0:3], v[156:159], v[210:213], v[0:3]
	s_setprio 0
	s_barrier
	s_add_i32 s72, 0, 0x18000
	s_add_i32 s73, 0, 0x1c000
	v_add_u32_e32 v140, s72, v234
	v_add_u32_e32 v156, s73, v234
	ds_read_b128 v[128:131], v140
	ds_read_b128 v[132:135], v140 offset:1024
	ds_read_b128 v[136:139], v140 offset:2048
	ds_read_b128 v[140:143], v140 offset:3072
	ds_read_b128 v[144:147], v156
	ds_read_b128 v[148:151], v156 offset:1024
	ds_read_b128 v[152:155], v156 offset:2048
	ds_read_b128 v[156:159], v156 offset:3072
	s_add_u32 s6, s6, 0x100000
	s_addc_u32 s7, s7, 0
	s_mov_b32 m0, s58
	ds_read_b128 v[160:163], v238 offset:32768
	ds_read_b128 v[186:189], v238 offset:33792
	ds_read_b128 v[190:193], v238 offset:34816
	ds_read_b128 v[194:197], v238 offset:35840
	ds_read_b128 v[198:201], v238 offset:36864
	ds_read_b128 v[202:205], v238 offset:37888
	ds_read_b128 v[206:209], v238 offset:38912
	ds_read_b128 v[210:213], v238 offset:39936
	global_load_lds_dwordx4 v166, s[6:7]
	s_mov_b32 m0, s59
	s_nop 0
	global_load_lds_dwordx4 v170, s[6:7]
	s_waitcnt vmcnt(8)
	s_waitcnt lgkmcnt(0)
	s_barrier
	s_setprio 1
	s_waitcnt lgkmcnt(0)
	v_mfma_f32_16x16x32_bf16 v[124:127], v[128:131], v[160:163], v[124:127]
	v_mfma_f32_16x16x32_bf16 v[120:123], v[136:139], v[160:163], v[120:123]
	v_mfma_f32_16x16x32_bf16 v[108:111], v[128:131], v[190:193], v[108:111]
	v_mfma_f32_16x16x32_bf16 v[104:107], v[136:139], v[190:193], v[104:107]
	v_mfma_f32_16x16x32_bf16 v[92:95], v[128:131], v[198:201], v[92:95]
	v_mfma_f32_16x16x32_bf16 v[88:91], v[136:139], v[198:201], v[88:91]
	v_mfma_f32_16x16x32_bf16 v[76:79], v[128:131], v[206:209], v[76:79]
	v_mfma_f32_16x16x32_bf16 v[72:75], v[136:139], v[206:209], v[72:75]
	v_mfma_f32_16x16x32_bf16 v[124:127], v[132:135], v[186:189], v[124:127]
	v_mfma_f32_16x16x32_bf16 v[120:123], v[140:143], v[186:189], v[120:123]
	v_mfma_f32_16x16x32_bf16 v[108:111], v[132:135], v[194:197], v[108:111]
	v_mfma_f32_16x16x32_bf16 v[104:107], v[140:143], v[194:197], v[104:107]
	v_mfma_f32_16x16x32_bf16 v[92:95], v[132:135], v[202:205], v[92:95]
	v_mfma_f32_16x16x32_bf16 v[88:91], v[140:143], v[202:205], v[88:91]
	v_mfma_f32_16x16x32_bf16 v[76:79], v[132:135], v[210:213], v[76:79]
	v_mfma_f32_16x16x32_bf16 v[72:75], v[140:143], v[210:213], v[72:75]
	s_setprio 0
	s_setprio 1
	v_mfma_f32_16x16x32_bf16 v[116:119], v[144:147], v[160:163], v[116:119]
	v_mfma_f32_16x16x32_bf16 v[112:115], v[152:155], v[160:163], v[112:115]
	v_mfma_f32_16x16x32_bf16 v[100:103], v[144:147], v[190:193], v[100:103]
	v_mfma_f32_16x16x32_bf16 v[96:99], v[152:155], v[190:193], v[96:99]
	v_mfma_f32_16x16x32_bf16 v[84:87], v[144:147], v[198:201], v[84:87]
	v_mfma_f32_16x16x32_bf16 v[80:83], v[152:155], v[198:201], v[80:83]
	v_mfma_f32_16x16x32_bf16 v[68:71], v[144:147], v[206:209], v[68:71]
	v_mfma_f32_16x16x32_bf16 v[64:67], v[152:155], v[206:209], v[64:67]
	v_mfma_f32_16x16x32_bf16 v[116:119], v[148:151], v[186:189], v[116:119]
	v_mfma_f32_16x16x32_bf16 v[112:115], v[156:159], v[186:189], v[112:115]
	v_mfma_f32_16x16x32_bf16 v[100:103], v[148:151], v[194:197], v[100:103]
	v_mfma_f32_16x16x32_bf16 v[96:99], v[156:159], v[194:197], v[96:99]
	v_mfma_f32_16x16x32_bf16 v[84:87], v[148:151], v[202:205], v[84:87]
	v_mfma_f32_16x16x32_bf16 v[80:83], v[156:159], v[202:205], v[80:83]
	v_mfma_f32_16x16x32_bf16 v[68:71], v[148:151], v[210:213], v[68:71]
	v_mfma_f32_16x16x32_bf16 v[64:67], v[156:159], v[210:213], v[64:67]
	s_setprio 0
	s_barrier
; #define PG8_STAGE(bufoff, gbase, voff) do { _Pragma("unroll") for (int _i = 0; _i < 2; ++_i) \
;         __builtin_amdgcn_global_load_lds((const unsigned*)((const char*)(gbase) + (voff)[_i]), (PG8_LAS unsigned*)(lds + (bufoff) + ldsw + _i * 8192), 16, 0, 0); } while (0)
; #define PG8_LDA(dst, b, h) do { _Pragma("unroll") for (int m = 0; m < 4; ++m) _Pragma("unroll") for (int k = 0; k < 2; ++k) dst[m][k] = *(const PG8_LAS bf16x8*)(lds + PG8_SA(b, h) + aoff + m * 2048 + k * 1024); } while (0)
; #define PG8_MMA(ai, bj, At, Bt) do { __builtin_amdgcn_s_setprio(1); _Pragma("unroll") for (int m = 0; m < 4; ++m) _Pragma("unroll") for (int n = 0; n < 2; ++n) _Pragma("unroll") for (int k = 0; k < 2; ++k) \
;         acc[ai][bj][m][n] = __builtin_amdgcn_mfma_f32_16x16x32_bf16(Bt[n][k], At[m][k], acc[ai][bj][m][n], 0, 0, 0); __builtin_amdgcn_s_setprio(0); } while (0)
; #define PG8_WAIT_V(n) asm volatile("s_waitcnt vmcnt(" #n ")" ::: "memory")
; #define PG8_WAIT_L(n) asm volatile("s_waitcnt lgkmcnt(" #n ")" ::: "memory")
; #define PG8_BAR __builtin_amdgcn_s_barrier()
; #define PG8_SCHED __builtin_amdgcn_sched_barrier(0)
; template <class Epi, class Sched, bool ALIGN_EPI = false, bool SP2 = false>
; __device__ __forceinline__ void gemm_phase(PG8_LAS unsigned char* lds, const Gemm g, const Sched& S, const Epi& E) {
;     ...
;         for (int t = 0; t < nt; t += 2) {
;     ...
;             PG8_LDA(At, 1, 1); PG8_STAGE(PG8_SB(1, 0), b3, voffB); PG8_STAGE(PG8_SB(1, 1), b3 + hstep, voffB); PG8_STAGE(PG8_SA(1, 0), a3, voffA);
;             PG8_WAIT_V(8); PG8_WAIT_L(0); PG8_BAR; PG8_MMA(1, 0, At, B0); PG8_MMA(1, 1, At, B1); PG8_BAR; PG8_SCHED;
	s_add_i32 s6, s72, s55
	s_mov_b32 m0, s6
	ds_read_b128 v[160:163], v238 offset:49152
	ds_read_b128 v[186:189], v238 offset:50176
	ds_read_b128 v[190:193], v238 offset:51200
	ds_read_b128 v[194:197], v238 offset:52224
	ds_read_b128 v[198:201], v238 offset:53248
	ds_read_b128 v[202:205], v238 offset:54272
	ds_read_b128 v[206:209], v238 offset:55296
	ds_read_b128 v[210:213], v238 offset:56320
	global_load_lds_dwordx4 v168, s[98:99]
	s_add_i32 m0, s6, 0x2000
	s_add_u32 s6, vcc_lo, 0x100080
	s_addc_u32 s7, vcc_hi, 0
	s_add_i32 s72, s73, s55
	global_load_lds_dwordx4 v172, s[98:99]
	s_mov_b32 m0, s72
	s_nop 0
	global_load_lds_dwordx4 v168, s[6:7]
	s_add_i32 m0, s72, 0x2000
	s_nop 0
	global_load_lds_dwordx4 v172, s[6:7]
	s_mov_b32 m0, s63
	s_nop 0
	global_load_lds_dwordx4 v166, s[100:101]
	s_mov_b32 m0, s64
	s_nop 0
	global_load_lds_dwordx4 v170, s[100:101]
	s_waitcnt vmcnt(8)
	s_waitcnt lgkmcnt(0)
	s_barrier
	s_setprio 1
	s_waitcnt lgkmcnt(0)
	v_mfma_f32_16x16x32_bf16 v[60:63], v[128:131], v[160:163], v[60:63]
	v_mfma_f32_16x16x32_bf16 v[56:59], v[136:139], v[160:163], v[56:59]
	v_mfma_f32_16x16x32_bf16 v[44:47], v[128:131], v[190:193], v[44:47]
	v_mfma_f32_16x16x32_bf16 v[40:43], v[136:139], v[190:193], v[40:43]
	v_mfma_f32_16x16x32_bf16 v[28:31], v[128:131], v[198:201], v[28:31]
	v_mfma_f32_16x16x32_bf16 v[24:27], v[136:139], v[198:201], v[24:27]
	v_mfma_f32_16x16x32_bf16 v[12:15], v[128:131], v[206:209], v[12:15]
	v_mfma_f32_16x16x32_bf16 v[8:11], v[136:139], v[206:209], v[8:11]
	v_mfma_f32_16x16x32_bf16 v[60:63], v[132:135], v[186:189], v[60:63]
	v_mfma_f32_16x16x32_bf16 v[56:59], v[140:143], v[186:189], v[56:59]
	v_mfma_f32_16x16x32_bf16 v[44:47], v[132:135], v[194:197], v[44:47]
	v_mfma_f32_16x16x32_bf16 v[40:43], v[140:143], v[194:197], v[40:43]
	v_mfma_f32_16x16x32_bf16 v[28:31], v[132:135], v[202:205], v[28:31]
	v_mfma_f32_16x16x32_bf16 v[24:27], v[140:143], v[202:205], v[24:27]
	v_mfma_f32_16x16x32_bf16 v[12:15], v[132:135], v[210:213], v[12:15]
	v_mfma_f32_16x16x32_bf16 v[8:11], v[140:143], v[210:213], v[8:11]
	s_setprio 0
	s_setprio 1
	v_mfma_f32_16x16x32_bf16 v[52:55], v[144:147], v[160:163], v[52:55]
	v_mfma_f32_16x16x32_bf16 v[48:51], v[152:155], v[160:163], v[48:51]
	v_mfma_f32_16x16x32_bf16 v[36:39], v[144:147], v[190:193], v[36:39]
	v_mfma_f32_16x16x32_bf16 v[32:35], v[152:155], v[190:193], v[32:35]
	v_mfma_f32_16x16x32_bf16 v[20:23], v[144:147], v[198:201], v[20:23]
	v_mfma_f32_16x16x32_bf16 v[16:19], v[152:155], v[198:201], v[16:19]
	v_mfma_f32_16x16x32_bf16 v[4:7], v[144:147], v[206:209], v[4:7]
	v_mfma_f32_16x16x32_bf16 v[0:3], v[152:155], v[206:209], v[0:3]
	v_mfma_f32_16x16x32_bf16 v[52:55], v[148:151], v[186:189], v[52:55]
	v_mfma_f32_16x16x32_bf16 v[48:51], v[156:159], v[186:189], v[48:51]
	v_mfma_f32_16x16x32_bf16 v[36:39], v[148:151], v[194:197], v[36:39]
	v_mfma_f32_16x16x32_bf16 v[32:35], v[156:159], v[194:197], v[32:35]
	v_mfma_f32_16x16x32_bf16 v[20:23], v[148:151], v[202:205], v[20:23]
	v_mfma_f32_16x16x32_bf16 v[16:19], v[156:159], v[202:205], v[16:19]
	v_mfma_f32_16x16x32_bf16 v[4:7], v[148:151], v[210:213], v[4:7]
	v_mfma_f32_16x16x32_bf16 v[0:3], v[156:159], v[210:213], v[0:3]
	s_setprio 0
	s_barrier
	s_add_i32 s71, s71, 2
	s_add_u32 s69, s69, 0x100
	s_addc_u32 s70, s70, 0
	s_cmp_gt_u32 s71, 61
	s_mov_b64 s[94:95], s[96:97]
	s_cbranch_scc0 .LBB0_1310
	s_and_b64 vcc, exec, s[12:13]
	s_cbranch_vccz .LBB0_1313
	s_barrier

; #define PG8_STAGE(bufoff, gbase, voff) do { _Pragma("unroll") for (int _i = 0; _i < 2; ++_i) \
;         __builtin_amdgcn_global_load_lds((const unsigned*)((const char*)(gbase) + (voff)[_i]), (PG8_LAS unsigned*)(lds + (bufoff) + ldsw + _i * 8192), 16, 0, 0); } while (0)
; #define PG8_LDA(dst, b, h) do { _Pragma("unroll") for (int m = 0; m < 4; ++m) _Pragma("unroll") for (int k = 0; k < 2; ++k) dst[m][k] = *(const PG8_LAS bf16x8*)(lds + PG8_SA(b, h) + aoff + m * 2048 + k * 1024); } while (0)
; #define PG8_LDB(dst, b, h) do { _Pragma("unroll") for (int n = 0; n < 2; ++n) _Pragma("unroll") for (int k = 0; k < 2; ++k) dst[n][k] = *(const PG8_LAS bf16x8*)(lds + PG8_SB(b, h) + boff + n * 2048 + k * 1024); } while (0)
; #define PG8_MMA(ai, bj, At, Bt) do { __builtin_amdgcn_s_setprio(1); _Pragma("unroll") for (int m = 0; m < 4; ++m) _Pragma("unroll") for (int n = 0; n < 2; ++n) _Pragma("unroll") for (int k = 0; k < 2; ++k) \
;         acc[ai][bj][m][n] = __builtin_amdgcn_mfma_f32_16x16x32_bf16(Bt[n][k], At[m][k], acc[ai][bj][m][n], 0, 0, 0); __builtin_amdgcn_s_setprio(0); } while (0)
; #define PG8_WAIT_V(n) asm volatile("s_waitcnt vmcnt(" #n ")" ::: "memory")
; #define PG8_WAIT_L(n) asm volatile("s_waitcnt lgkmcnt(" #n ")" ::: "memory")
; #define PG8_BAR __builtin_amdgcn_s_barrier()
; #define PG8_SCHED __builtin_amdgcn_sched_barrier(0)
; template <class Epi, class Sched, bool ALIGN_EPI = false, bool SP2 = false>
; __device__ __forceinline__ void gemm_phase(PG8_LAS unsigned char* lds, const Gemm g, const Sched& S, const Epi& E) {
;     ...
;             PG8_LDB(B0, 0, 0); PG8_LDB(B1, 0, 1); PG8_SCHED; PG8_LDA(At, 0, 0); PG8_STAGE(PG8_SA(1, 1), a1 + hstepA, voffA);
;             PG8_WAIT_V(8); PG8_WAIT_L(0); PG8_BAR; PG8_MMA(0, 0, At, B0); PG8_MMA(0, 1, At, B1); PG8_BAR; PG8_SCHED;
;             PG8_LDA(At, 0, 1); PG8_STAGE(PG8_SB(0, 0), b2, voffB); PG8_STAGE(PG8_SB(0, 1), b2 + hstep, voffB); PG8_STAGE(PG8_SA(0, 0), a2, voffA);
;             PG8_WAIT_V(8); PG8_WAIT_L(0); PG8_BAR; PG8_MMA(1, 0, At, B0); PG8_MMA(1, 1, At, B1); PG8_BAR; PG8_SCHED;
.LBB0_1515:
	ds_read_b128 v[144:147], v153
	ds_read_b128 v[158:161], v153 offset:1024
	ds_read_b128 v[162:165], v153 offset:2048
	ds_read_b128 v[166:169], v153 offset:3072
	ds_read_b128 v[170:173], v154
	ds_read_b128 v[174:177], v154 offset:1024
	ds_read_b128 v[178:181], v154 offset:2048
	ds_read_b128 v[182:185], v154 offset:3072
	s_add_u32 s24, s22, 0x4000
	s_addc_u32 s25, s23, 0
	s_cmpk_eq_i32 s63, 0xa8
	s_cselect_b32 s30, s6, s24
	s_cselect_b32 s31, s7, s25
	s_cselect_b32 s26, s20, s61
	s_cselect_b32 s27, s21, s62
	s_add_u32 s24, s30, 0x8000
	s_addc_u32 s25, s31, 0
	s_add_i32 m0, s34, 0xc000
	ds_read_b128 v[186:189], v155
	ds_read_b128 v[190:193], v155 offset:1024
	ds_read_b128 v[194:197], v155 offset:2048
	ds_read_b128 v[198:201], v155 offset:3072
	ds_read_b128 v[202:205], v155 offset:4096
	ds_read_b128 v[206:209], v155 offset:5120
	ds_read_b128 v[210:213], v155 offset:6144
	ds_read_b128 v[214:217], v155 offset:7168
	global_load_lds_dwordx4 v136, s[22:23]
	s_add_i32 m0, s34, 0xe000
	s_nop 0
	global_load_lds_dwordx4 v138, s[22:23]
	s_waitcnt vmcnt(8)
	s_waitcnt lgkmcnt(0)
	s_barrier
	s_setprio 1
	s_waitcnt lgkmcnt(0)
	v_mfma_f32_16x16x32_bf16 v[124:127], v[144:147], v[186:189], v[124:127]
	v_mfma_f32_16x16x32_bf16 v[120:123], v[162:165], v[186:189], v[120:123]
	v_mfma_f32_16x16x32_bf16 v[108:111], v[144:147], v[194:197], v[108:111]
	v_mfma_f32_16x16x32_bf16 v[48:51], v[162:165], v[194:197], v[48:51]
	v_mfma_f32_16x16x32_bf16 v[100:103], v[144:147], v[202:205], v[100:103]
	v_mfma_f32_16x16x32_bf16 v[64:67], v[162:165], v[202:205], v[64:67]
	v_mfma_f32_16x16x32_bf16 v[92:95], v[144:147], v[210:213], v[92:95]
	v_mfma_f32_16x16x32_bf16 v[80:83], v[162:165], v[210:213], v[80:83]
	v_mfma_f32_16x16x32_bf16 v[124:127], v[158:161], v[190:193], v[124:127]
	v_mfma_f32_16x16x32_bf16 v[120:123], v[166:169], v[190:193], v[120:123]
	v_mfma_f32_16x16x32_bf16 v[108:111], v[158:161], v[198:201], v[108:111]
	v_mfma_f32_16x16x32_bf16 v[48:51], v[166:169], v[198:201], v[48:51]
	v_mfma_f32_16x16x32_bf16 v[100:103], v[158:161], v[206:209], v[100:103]
	v_mfma_f32_16x16x32_bf16 v[64:67], v[166:169], v[206:209], v[64:67]
	v_mfma_f32_16x16x32_bf16 v[92:95], v[158:161], v[214:217], v[92:95]
	v_mfma_f32_16x16x32_bf16 v[80:83], v[166:169], v[214:217], v[80:83]
	s_setprio 0
	s_setprio 1
	v_mfma_f32_16x16x32_bf16 v[116:119], v[170:173], v[186:189], v[116:119]
	v_mfma_f32_16x16x32_bf16 v[112:115], v[178:181], v[186:189], v[112:115]
	v_mfma_f32_16x16x32_bf16 v[104:107], v[170:173], v[194:197], v[104:107]
	v_mfma_f32_16x16x32_bf16 v[52:55], v[178:181], v[194:197], v[52:55]
	v_mfma_f32_16x16x32_bf16 v[96:99], v[170:173], v[202:205], v[96:99]
	v_mfma_f32_16x16x32_bf16 v[76:79], v[178:181], v[202:205], v[76:79]
	v_mfma_f32_16x16x32_bf16 v[88:91], v[170:173], v[210:213], v[88:91]
	v_mfma_f32_16x16x32_bf16 v[84:87], v[178:181], v[210:213], v[84:87]
	v_mfma_f32_16x16x32_bf16 v[116:119], v[174:177], v[190:193], v[116:119]
	v_mfma_f32_16x16x32_bf16 v[112:115], v[182:185], v[190:193], v[112:115]
	v_mfma_f32_16x16x32_bf16 v[104:107], v[174:177], v[198:201], v[104:107]
	v_mfma_f32_16x16x32_bf16 v[52:55], v[182:185], v[198:201], v[52:55]
	v_mfma_f32_16x16x32_bf16 v[96:99], v[174:177], v[206:209], v[96:99]
	v_mfma_f32_16x16x32_bf16 v[76:79], v[182:185], v[206:209], v[76:79]
	v_mfma_f32_16x16x32_bf16 v[88:91], v[174:177], v[214:217], v[88:91]
	v_mfma_f32_16x16x32_bf16 v[84:87], v[182:185], v[214:217], v[84:87]
	s_setprio 0
	s_barrier
	s_add_u32 s98, s26, s16
	s_addc_u32 s99, s27, s17
	s_add_i32 s64, s55, s33
	s_mov_b32 m0, s64
	ds_read_b128 v[186:189], v155 offset:16384
	ds_read_b128 v[190:193], v155 offset:17408
	ds_read_b128 v[194:197], v155 offset:18432
	ds_read_b128 v[198:201], v155 offset:19456
	ds_read_b128 v[202:205], v155 offset:20480
	ds_read_b128 v[206:209], v155 offset:21504
	ds_read_b128 v[210:213], v155 offset:22528
	ds_read_b128 v[214:217], v155 offset:23552
	global_load_lds_dwordx4 v130, s[26:27]
	s_add_i32 m0, s64, 0x2000
	s_add_u32 s64, s26, 0x2b0000
	s_addc_u32 s65, s27, 0
	s_add_i32 s66, s56, s33
	global_load_lds_dwordx4 v134, s[26:27]
	s_mov_b32 m0, s66
	s_nop 0
	global_load_lds_dwordx4 v130, s[64:65]
	s_add_i32 m0, s66, 0x2000
	s_nop 0
	global_load_lds_dwordx4 v134, s[64:65]
	s_mov_b32 m0, s34
	s_nop 0
	global_load_lds_dwordx4 v128, s[30:31]
	s_mov_b32 m0, s35
	s_nop 0
	global_load_lds_dwordx4 v132, s[30:31]
	s_waitcnt vmcnt(8)
	s_waitcnt lgkmcnt(0)
	s_barrier
	s_setprio 1
	s_waitcnt lgkmcnt(0)
	v_mfma_f32_16x16x32_bf16 v[72:75], v[144:147], v[186:189], v[72:75]
	v_mfma_f32_16x16x32_bf16 v[68:71], v[162:165], v[186:189], v[68:71]
	v_mfma_f32_16x16x32_bf16 v[44:47], v[144:147], v[194:197], v[44:47]
	v_mfma_f32_16x16x32_bf16 v[40:43], v[162:165], v[194:197], v[40:43]
	v_mfma_f32_16x16x32_bf16 v[28:31], v[144:147], v[202:205], v[28:31]
	v_mfma_f32_16x16x32_bf16 v[24:27], v[162:165], v[202:205], v[24:27]
	v_mfma_f32_16x16x32_bf16 v[12:15], v[144:147], v[210:213], v[12:15]
	v_mfma_f32_16x16x32_bf16 v[8:11], v[162:165], v[210:213], v[8:11]
	v_mfma_f32_16x16x32_bf16 v[72:75], v[158:161], v[190:193], v[72:75]
	v_mfma_f32_16x16x32_bf16 v[68:71], v[166:169], v[190:193], v[68:71]
	v_mfma_f32_16x16x32_bf16 v[44:47], v[158:161], v[198:201], v[44:47]
	v_mfma_f32_16x16x32_bf16 v[40:43], v[166:169], v[198:201], v[40:43]
	v_mfma_f32_16x16x32_bf16 v[28:31], v[158:161], v[206:209], v[28:31]
	v_mfma_f32_16x16x32_bf16 v[24:27], v[166:169], v[206:209], v[24:27]
	v_mfma_f32_16x16x32_bf16 v[12:15], v[158:161], v[214:217], v[12:15]
	v_mfma_f32_16x16x32_bf16 v[8:11], v[166:169], v[214:217], v[8:11]
	s_setprio 0
	s_setprio 1
	v_mfma_f32_16x16x32_bf16 v[60:63], v[170:173], v[186:189], v[60:63]
	v_mfma_f32_16x16x32_bf16 v[56:59], v[178:181], v[186:189], v[56:59]
	v_mfma_f32_16x16x32_bf16 v[36:39], v[170:173], v[194:197], v[36:39]
	v_mfma_f32_16x16x32_bf16 v[32:35], v[178:181], v[194:197], v[32:35]
	v_mfma_f32_16x16x32_bf16 v[20:23], v[170:173], v[202:205], v[20:23]
	v_mfma_f32_16x16x32_bf16 v[16:19], v[178:181], v[202:205], v[16:19]
	v_mfma_f32_16x16x32_bf16 v[4:7], v[170:173], v[210:213], v[4:7]
	v_mfma_f32_16x16x32_bf16 v[0:3], v[178:181], v[210:213], v[0:3]
	v_mfma_f32_16x16x32_bf16 v[60:63], v[174:177], v[190:193], v[60:63]
	v_mfma_f32_16x16x32_bf16 v[56:59], v[182:185], v[190:193], v[56:59]
	v_mfma_f32_16x16x32_bf16 v[36:39], v[174:177], v[198:201], v[36:39]
	v_mfma_f32_16x16x32_bf16 v[32:35], v[182:185], v[198:201], v[32:35]
	v_mfma_f32_16x16x32_bf16 v[20:23], v[174:177], v[206:209], v[20:23]
	v_mfma_f32_16x16x32_bf16 v[16:19], v[182:185], v[206:209], v[16:19]
	v_mfma_f32_16x16x32_bf16 v[4:7], v[174:177], v[214:217], v[4:7]
	v_mfma_f32_16x16x32_bf16 v[0:3], v[182:185], v[214:217], v[0:3]
	s_setprio 0
	s_barrier
; #define PG8_STAGE(bufoff, gbase, voff) do { _Pragma("unroll") for (int _i = 0; _i < 2; ++_i) \
;         __builtin_amdgcn_global_load_lds((const unsigned*)((const char*)(gbase) + (voff)[_i]), (PG8_LAS unsigned*)(lds + (bufoff) + ldsw + _i * 8192), 16, 0, 0); } while (0)
; #define PG8_LDA(dst, b, h) do { _Pragma("unroll") for (int m = 0; m < 4; ++m) _Pragma("unroll") for (int k = 0; k < 2; ++k) dst[m][k] = *(const PG8_LAS bf16x8*)(lds + PG8_SA(b, h) + aoff + m * 2048 + k * 1024); } while (0)
; #define PG8_LDB(dst, b, h) do { _Pragma("unroll") for (int n = 0; n < 2; ++n) _Pragma("unroll") for (int k = 0; k < 2; ++k) dst[n][k] = *(const PG8_LAS bf16x8*)(lds + PG8_SB(b, h) + boff + n * 2048 + k * 1024); } while (0)
; #define PG8_MMA(ai, bj, At, Bt) do { __builtin_amdgcn_s_setprio(1); _Pragma("unroll") for (int m = 0; m < 4; ++m) _Pragma("unroll") for (int n = 0; n < 2; ++n) _Pragma("unroll") for (int k = 0; k < 2; ++k) \
;         acc[ai][bj][m][n] = __builtin_amdgcn_mfma_f32_16x16x32_bf16(Bt[n][k], At[m][k], acc[ai][bj][m][n], 0, 0, 0); __builtin_amdgcn_s_setprio(0); } while (0)
; #define PG8_WAIT_V(n) asm volatile("s_waitcnt vmcnt(" #n ")" ::: "memory")
; #define PG8_WAIT_L(n) asm volatile("s_waitcnt lgkmcnt(" #n ")" ::: "memory")
; #define PG8_BAR __builtin_amdgcn_s_barrier()
; #define PG8_SCHED __builtin_amdgcn_sched_barrier(0)
; template <class Epi, class Sched, bool ALIGN_EPI = false, bool SP2 = false>
; __device__ __forceinline__ void gemm_phase(PG8_LAS unsigned char* lds, const Gemm g, const Sched& S, const Epi& E) {
;     ...
;         for (int t = 0; t < nt; t += 2) {
;     ...
;             PG8_LDB(B0, 1, 0); PG8_LDB(B1, 1, 1); PG8_SCHED; PG8_LDA(At, 1, 0); PG8_STAGE(PG8_SA(0, 1), a2 + hstepA, voffA);
;             PG8_WAIT_V(8); PG8_WAIT_L(0); PG8_BAR; PG8_MMA(0, 0, At, B0); PG8_MMA(0, 1, At, B1); PG8_BAR; PG8_SCHED;
;             PG8_LDA(At, 1, 1); PG8_STAGE(PG8_SB(1, 0), b3, voffB); PG8_STAGE(PG8_SB(1, 1), b3 + hstep, voffB); PG8_STAGE(PG8_SA(1, 0), a3, voffA);
;             PG8_WAIT_V(8); PG8_WAIT_L(0); PG8_BAR; PG8_MMA(1, 0, At, B0); PG8_MMA(1, 1, At, B1); PG8_BAR; PG8_SCHED;
	s_add_i32 s64, 0, 0x18000
	v_add_u32_e32 v157, s64, v151
	s_add_i32 s65, 0, 0x1c000
	ds_read_b128 v[144:147], v157
	ds_read_b128 v[158:161], v157 offset:1024
	ds_read_b128 v[162:165], v157 offset:2048
	ds_read_b128 v[166:169], v157 offset:3072
	v_add_u32_e32 v157, s65, v151
	ds_read_b128 v[170:173], v157
	ds_read_b128 v[174:177], v157 offset:1024
	ds_read_b128 v[178:181], v157 offset:2048
	ds_read_b128 v[182:185], v157 offset:3072
	s_add_u32 s30, s30, 0x4000
	s_addc_u32 s31, s31, 0
	s_mov_b32 m0, s38
	ds_read_b128 v[186:189], v155 offset:32768
	ds_read_b128 v[190:193], v155 offset:33792
	ds_read_b128 v[194:197], v155 offset:34816
	ds_read_b128 v[198:201], v155 offset:35840
	ds_read_b128 v[202:205], v155 offset:36864
	ds_read_b128 v[206:209], v155 offset:37888
	ds_read_b128 v[210:213], v155 offset:38912
	ds_read_b128 v[214:217], v155 offset:39936
	global_load_lds_dwordx4 v128, s[30:31]
	s_mov_b32 m0, s39
	s_nop 0
	global_load_lds_dwordx4 v132, s[30:31]
	s_waitcnt vmcnt(8)
	s_waitcnt lgkmcnt(0)
	s_barrier
	s_setprio 1
	s_waitcnt lgkmcnt(0)
	v_mfma_f32_16x16x32_bf16 v[124:127], v[144:147], v[186:189], v[124:127]
	v_mfma_f32_16x16x32_bf16 v[120:123], v[162:165], v[186:189], v[120:123]
	v_mfma_f32_16x16x32_bf16 v[108:111], v[144:147], v[194:197], v[108:111]
	v_mfma_f32_16x16x32_bf16 v[48:51], v[162:165], v[194:197], v[48:51]
	v_mfma_f32_16x16x32_bf16 v[100:103], v[144:147], v[202:205], v[100:103]
	v_mfma_f32_16x16x32_bf16 v[64:67], v[162:165], v[202:205], v[64:67]
	v_mfma_f32_16x16x32_bf16 v[92:95], v[144:147], v[210:213], v[92:95]
	v_mfma_f32_16x16x32_bf16 v[80:83], v[162:165], v[210:213], v[80:83]
	v_mfma_f32_16x16x32_bf16 v[124:127], v[158:161], v[190:193], v[124:127]
	v_mfma_f32_16x16x32_bf16 v[120:123], v[166:169], v[190:193], v[120:123]
	v_mfma_f32_16x16x32_bf16 v[108:111], v[158:161], v[198:201], v[108:111]
	v_mfma_f32_16x16x32_bf16 v[48:51], v[166:169], v[198:201], v[48:51]
	v_mfma_f32_16x16x32_bf16 v[100:103], v[158:161], v[206:209], v[100:103]
	v_mfma_f32_16x16x32_bf16 v[64:67], v[166:169], v[206:209], v[64:67]
	v_mfma_f32_16x16x32_bf16 v[92:95], v[158:161], v[214:217], v[92:95]
	v_mfma_f32_16x16x32_bf16 v[80:83], v[166:169], v[214:217], v[80:83]
	s_setprio 0
	s_setprio 1
	v_mfma_f32_16x16x32_bf16 v[116:119], v[170:173], v[186:189], v[116:119]
	v_mfma_f32_16x16x32_bf16 v[112:115], v[178:181], v[186:189], v[112:115]
	v_mfma_f32_16x16x32_bf16 v[104:107], v[170:173], v[194:197], v[104:107]
	v_mfma_f32_16x16x32_bf16 v[52:55], v[178:181], v[194:197], v[52:55]
	v_mfma_f32_16x16x32_bf16 v[96:99], v[170:173], v[202:205], v[96:99]
	v_mfma_f32_16x16x32_bf16 v[76:79], v[178:181], v[202:205], v[76:79]
	v_mfma_f32_16x16x32_bf16 v[88:91], v[170:173], v[210:213], v[88:91]
	v_mfma_f32_16x16x32_bf16 v[84:87], v[178:181], v[210:213], v[84:87]
	v_mfma_f32_16x16x32_bf16 v[116:119], v[174:177], v[190:193], v[116:119]
	v_mfma_f32_16x16x32_bf16 v[112:115], v[182:185], v[190:193], v[112:115]
	v_mfma_f32_16x16x32_bf16 v[104:107], v[174:177], v[198:201], v[104:107]
	v_mfma_f32_16x16x32_bf16 v[52:55], v[182:185], v[198:201], v[52:55]
	v_mfma_f32_16x16x32_bf16 v[96:99], v[174:177], v[206:209], v[96:99]
	v_mfma_f32_16x16x32_bf16 v[76:79], v[182:185], v[206:209], v[76:79]
	v_mfma_f32_16x16x32_bf16 v[88:91], v[174:177], v[214:217], v[88:91]
	v_mfma_f32_16x16x32_bf16 v[84:87], v[182:185], v[214:217], v[84:87]
	s_setprio 0
	s_barrier
	s_add_i32 s30, s64, s33
	s_mov_b32 m0, s30
	ds_read_b128 v[186:189], v155 offset:49152
	ds_read_b128 v[190:193], v155 offset:50176
	ds_read_b128 v[194:197], v155 offset:51200
	ds_read_b128 v[198:201], v155 offset:52224
	ds_read_b128 v[202:205], v155 offset:53248
	ds_read_b128 v[206:209], v155 offset:54272
	ds_read_b128 v[210:213], v155 offset:55296
	ds_read_b128 v[214:217], v155 offset:56320
	global_load_lds_dwordx4 v130, s[98:99]
	s_add_i32 m0, s30, 0x2000
	s_add_u32 s26, s26, 0x2b0080
	s_addc_u32 s27, s27, 0
	s_add_i32 s30, s65, s33
	global_load_lds_dwordx4 v134, s[98:99]
	s_mov_b32 m0, s30
	s_nop 0
	global_load_lds_dwordx4 v130, s[26:27]
	s_add_i32 m0, s30, 0x2000
	s_nop 0
	global_load_lds_dwordx4 v134, s[26:27]
	s_mov_b32 m0, s41
	s_nop 0
	global_load_lds_dwordx4 v128, s[24:25]
	s_mov_b32 m0, s52
	s_nop 0
	global_load_lds_dwordx4 v132, s[24:25]
	s_waitcnt vmcnt(8)
	s_waitcnt lgkmcnt(0)
	s_barrier
	s_setprio 1
	s_waitcnt lgkmcnt(0)
	v_mfma_f32_16x16x32_bf16 v[72:75], v[144:147], v[186:189], v[72:75]
	v_mfma_f32_16x16x32_bf16 v[68:71], v[162:165], v[186:189], v[68:71]
	v_mfma_f32_16x16x32_bf16 v[44:47], v[144:147], v[194:197], v[44:47]
	v_mfma_f32_16x16x32_bf16 v[40:43], v[162:165], v[194:197], v[40:43]
	v_mfma_f32_16x16x32_bf16 v[28:31], v[144:147], v[202:205], v[28:31]
	v_mfma_f32_16x16x32_bf16 v[24:27], v[162:165], v[202:205], v[24:27]
	v_mfma_f32_16x16x32_bf16 v[12:15], v[144:147], v[210:213], v[12:15]
	v_mfma_f32_16x16x32_bf16 v[8:11], v[162:165], v[210:213], v[8:11]
	v_mfma_f32_16x16x32_bf16 v[72:75], v[158:161], v[190:193], v[72:75]
	v_mfma_f32_16x16x32_bf16 v[68:71], v[166:169], v[190:193], v[68:71]
	v_mfma_f32_16x16x32_bf16 v[44:47], v[158:161], v[198:201], v[44:47]
	v_mfma_f32_16x16x32_bf16 v[40:43], v[166:169], v[198:201], v[40:43]
	v_mfma_f32_16x16x32_bf16 v[28:31], v[158:161], v[206:209], v[28:31]
	v_mfma_f32_16x16x32_bf16 v[24:27], v[166:169], v[206:209], v[24:27]
	v_mfma_f32_16x16x32_bf16 v[12:15], v[158:161], v[214:217], v[12:15]
	v_mfma_f32_16x16x32_bf16 v[8:11], v[166:169], v[214:217], v[8:11]
	s_setprio 0
	s_setprio 1
	v_mfma_f32_16x16x32_bf16 v[60:63], v[170:173], v[186:189], v[60:63]
	v_mfma_f32_16x16x32_bf16 v[56:59], v[178:181], v[186:189], v[56:59]
	v_mfma_f32_16x16x32_bf16 v[36:39], v[170:173], v[194:197], v[36:39]
	v_mfma_f32_16x16x32_bf16 v[32:35], v[178:181], v[194:197], v[32:35]
	v_mfma_f32_16x16x32_bf16 v[20:23], v[170:173], v[202:205], v[20:23]
	v_mfma_f32_16x16x32_bf16 v[16:19], v[178:181], v[202:205], v[16:19]
	v_mfma_f32_16x16x32_bf16 v[4:7], v[170:173], v[210:213], v[4:7]
	v_mfma_f32_16x16x32_bf16 v[0:3], v[178:181], v[210:213], v[0:3]
	v_mfma_f32_16x16x32_bf16 v[60:63], v[174:177], v[190:193], v[60:63]
	v_mfma_f32_16x16x32_bf16 v[56:59], v[182:185], v[190:193], v[56:59]
	v_mfma_f32_16x16x32_bf16 v[36:39], v[174:177], v[198:201], v[36:39]
	v_mfma_f32_16x16x32_bf16 v[32:35], v[182:185], v[198:201], v[32:35]
	v_mfma_f32_16x16x32_bf16 v[20:23], v[174:177], v[206:209], v[20:23]
	v_mfma_f32_16x16x32_bf16 v[16:19], v[182:185], v[206:209], v[16:19]
	v_mfma_f32_16x16x32_bf16 v[4:7], v[174:177], v[214:217], v[4:7]
	v_mfma_f32_16x16x32_bf16 v[0:3], v[182:185], v[214:217], v[0:3]
	s_setprio 0
	s_barrier
	s_add_i32 s63, s63, 2
	s_add_u32 s61, s61, 0x100
	s_addc_u32 s62, s62, 0
	s_add_u32 s22, s22, 0x10000
	s_addc_u32 s23, s23, 0
	s_cmpk_gt_u32 s63, 0xa9
	s_cbranch_scc0 .LBB0_1515
	s_and_b64 vcc, exec, s[18:19]
	s_cbranch_vccz .LBB0_1518
	s_barrier

; #define PG8_STAGE(bufoff, gbase, voff) do { _Pragma("unroll") for (int _i = 0; _i < 2; ++_i) \
;         __builtin_amdgcn_global_load_lds((const unsigned*)((const char*)(gbase) + (voff)[_i]), (PG8_LAS unsigned*)(lds + (bufoff) + ldsw + _i * 8192), 16, 0, 0); } while (0)
; #define PG8_LDA(dst, b, h) do { _Pragma("unroll") for (int m = 0; m < 4; ++m) _Pragma("unroll") for (int k = 0; k < 2; ++k) dst[m][k] = *(const PG8_LAS bf16x8*)(lds + PG8_SA(b, h) + aoff + m * 2048 + k * 1024); } while (0)
; #define PG8_LDB(dst, b, h) do { _Pragma("unroll") for (int n = 0; n < 2; ++n) _Pragma("unroll") for (int k = 0; k < 2; ++k) dst[n][k] = *(const PG8_LAS bf16x8*)(lds + PG8_SB(b, h) + boff + n * 2048 + k * 1024); } while (0)
; #define PG8_MMA(ai, bj, At, Bt) do { __builtin_amdgcn_s_setprio(1); _Pragma("unroll") for (int m = 0; m < 4; ++m) _Pragma("unroll") for (int n = 0; n < 2; ++n) _Pragma("unroll") for (int k = 0; k < 2; ++k) \
;         acc[ai][bj][m][n] = __builtin_amdgcn_mfma_f32_16x16x32_bf16(Bt[n][k], At[m][k], acc[ai][bj][m][n], 0, 0, 0); __builtin_amdgcn_s_setprio(0); } while (0)
; #define PG8_WAIT_V(n) asm volatile("s_waitcnt vmcnt(" #n ")" ::: "memory")
; #define PG8_WAIT_L(n) asm volatile("s_waitcnt lgkmcnt(" #n ")" ::: "memory")
; #define PG8_BAR __builtin_amdgcn_s_barrier()
; #define PG8_SCHED __builtin_amdgcn_sched_barrier(0)
; template <class Epi, class Sched, bool ALIGN_EPI = false, bool SP2 = false>
; __device__ __forceinline__ void gemm_phase(PG8_LAS unsigned char* lds, const Gemm g, const Sched& S, const Epi& E) {
;     ...
;             PG8_LDB(B0, 0, 0); PG8_LDB(B1, 0, 1); PG8_SCHED; PG8_LDA(At, 0, 0); PG8_STAGE(PG8_SA(1, 1), a1 + hstepA, voffA);
;             PG8_WAIT_V(8); PG8_WAIT_L(0); PG8_BAR; PG8_MMA(0, 0, At, B0); PG8_MMA(0, 1, At, B1); PG8_BAR; PG8_SCHED;
;             PG8_LDA(At, 0, 1); PG8_STAGE(PG8_SB(0, 0), b2, voffB); PG8_STAGE(PG8_SB(0, 1), b2 + hstep, voffB); PG8_STAGE(PG8_SA(0, 0), a2, voffA);
;             PG8_WAIT_V(8); PG8_WAIT_L(0); PG8_BAR; PG8_MMA(1, 0, At, B0); PG8_MMA(1, 1, At, B1); PG8_BAR; PG8_SCHED;
.LBB0_1631:
	ds_read_b128 v[144:147], v155
	ds_read_b128 v[148:151], v155 offset:1024
	ds_read_b128 v[160:163], v155 offset:2048
	ds_read_b128 v[164:167], v155 offset:3072
	ds_read_b128 v[168:171], v156
	ds_read_b128 v[172:175], v156 offset:1024
	ds_read_b128 v[176:179], v156 offset:2048
	ds_read_b128 v[180:183], v156 offset:3072
	s_add_u32 s65, s84, 0xfff00080
	s_addc_u32 s66, s85, -1
	s_cmp_eq_u32 s64, 60
	s_cselect_b32 s89, s25, s66
	s_cselect_b32 s88, s35, s65
	s_cselect_b32 s87, s23, s63
	s_cselect_b32 s86, s61, s62
	s_add_i32 m0, s29, 0xc000
	ds_read_b128 v[184:187], v157
	ds_read_b128 v[188:191], v157 offset:1024
	ds_read_b128 v[192:195], v157 offset:2048
	ds_read_b128 v[196:199], v157 offset:3072
	ds_read_b128 v[200:203], v157 offset:4096
	ds_read_b128 v[204:207], v157 offset:5120
	ds_read_b128 v[208:211], v157 offset:6144
	ds_read_b128 v[212:215], v157 offset:7168
	global_load_lds_dwordx4 v136, s[84:85]
	s_add_i32 m0, s29, 0xe000
	s_nop 0
	global_load_lds_dwordx4 v138, s[84:85]
	s_waitcnt vmcnt(8)
	s_waitcnt lgkmcnt(0)
	s_barrier
	s_setprio 1
	s_waitcnt lgkmcnt(0)
	v_mfma_f32_16x16x32_bf16 v[124:127], v[144:147], v[184:187], v[124:127]
	v_mfma_f32_16x16x32_bf16 v[120:123], v[160:163], v[184:187], v[120:123]
	v_mfma_f32_16x16x32_bf16 v[108:111], v[144:147], v[192:195], v[108:111]
	v_mfma_f32_16x16x32_bf16 v[32:35], v[160:163], v[192:195], v[32:35]
	v_mfma_f32_16x16x32_bf16 v[100:103], v[144:147], v[200:203], v[100:103]
	v_mfma_f32_16x16x32_bf16 v[52:55], v[160:163], v[200:203], v[52:55]
	v_mfma_f32_16x16x32_bf16 v[92:95], v[144:147], v[208:211], v[92:95]
	v_mfma_f32_16x16x32_bf16 v[72:75], v[160:163], v[208:211], v[72:75]
	v_mfma_f32_16x16x32_bf16 v[124:127], v[148:151], v[188:191], v[124:127]
	v_mfma_f32_16x16x32_bf16 v[120:123], v[164:167], v[188:191], v[120:123]
	v_mfma_f32_16x16x32_bf16 v[108:111], v[148:151], v[196:199], v[108:111]
	v_mfma_f32_16x16x32_bf16 v[32:35], v[164:167], v[196:199], v[32:35]
	v_mfma_f32_16x16x32_bf16 v[100:103], v[148:151], v[204:207], v[100:103]
	v_mfma_f32_16x16x32_bf16 v[52:55], v[164:167], v[204:207], v[52:55]
	v_mfma_f32_16x16x32_bf16 v[92:95], v[148:151], v[212:215], v[92:95]
	v_mfma_f32_16x16x32_bf16 v[72:75], v[164:167], v[212:215], v[72:75]
	s_setprio 0
	s_setprio 1
	v_mfma_f32_16x16x32_bf16 v[116:119], v[168:171], v[184:187], v[116:119]
	v_mfma_f32_16x16x32_bf16 v[112:115], v[176:179], v[184:187], v[112:115]
	v_mfma_f32_16x16x32_bf16 v[104:107], v[168:171], v[192:195], v[104:107]
	v_mfma_f32_16x16x32_bf16 v[44:47], v[176:179], v[192:195], v[44:47]
	v_mfma_f32_16x16x32_bf16 v[96:99], v[168:171], v[200:203], v[96:99]
	v_mfma_f32_16x16x32_bf16 v[68:71], v[176:179], v[200:203], v[68:71]
	v_mfma_f32_16x16x32_bf16 v[88:91], v[168:171], v[208:211], v[88:91]
	v_mfma_f32_16x16x32_bf16 v[84:87], v[176:179], v[208:211], v[84:87]
	v_mfma_f32_16x16x32_bf16 v[116:119], v[172:175], v[188:191], v[116:119]
	v_mfma_f32_16x16x32_bf16 v[112:115], v[180:183], v[188:191], v[112:115]
	v_mfma_f32_16x16x32_bf16 v[104:107], v[172:175], v[196:199], v[104:107]
	v_mfma_f32_16x16x32_bf16 v[44:47], v[180:183], v[196:199], v[44:47]
	v_mfma_f32_16x16x32_bf16 v[96:99], v[172:175], v[204:207], v[96:99]
	v_mfma_f32_16x16x32_bf16 v[68:71], v[180:183], v[204:207], v[68:71]
	v_mfma_f32_16x16x32_bf16 v[88:91], v[172:175], v[212:215], v[88:91]
	v_mfma_f32_16x16x32_bf16 v[84:87], v[180:183], v[212:215], v[84:87]
	s_setprio 0
	s_barrier
	s_add_u32 s98, s86, s18
	s_addc_u32 s99, s87, s19
	s_add_u32 s100, s88, s18
	s_addc_u32 s101, s89, s19
	s_add_i32 s65, s58, s3
	s_mov_b32 m0, s65
	ds_read_b128 v[184:187], v157 offset:16384
	ds_read_b128 v[188:191], v157 offset:17408
	ds_read_b128 v[192:195], v157 offset:18432
	ds_read_b128 v[196:199], v157 offset:19456
	ds_read_b128 v[200:203], v157 offset:20480
	ds_read_b128 v[204:207], v157 offset:21504
	ds_read_b128 v[208:211], v157 offset:22528
	ds_read_b128 v[212:215], v157 offset:23552
	global_load_lds_dwordx4 v130, s[86:87]
	s_add_i32 m0, s65, 0x2000
	s_add_u32 s66, s86, 0x100000
	s_addc_u32 s67, s87, 0
	s_add_i32 s65, s59, s3
	global_load_lds_dwordx4 v134, s[86:87]
	s_mov_b32 m0, s65
	s_nop 0
	global_load_lds_dwordx4 v130, s[66:67]
	s_add_i32 m0, s65, 0x2000
	s_nop 0
	global_load_lds_dwordx4 v134, s[66:67]
	s_mov_b32 m0, s29
	s_nop 0
	global_load_lds_dwordx4 v128, s[88:89]
	s_mov_b32 m0, s33
	s_nop 0
	global_load_lds_dwordx4 v132, s[88:89]
	s_waitcnt vmcnt(8)
	s_waitcnt lgkmcnt(0)
	s_barrier
	s_setprio 1
	s_waitcnt lgkmcnt(0)
	v_mfma_f32_16x16x32_bf16 v[80:83], v[144:147], v[184:187], v[80:83]
	v_mfma_f32_16x16x32_bf16 v[76:79], v[160:163], v[184:187], v[76:79]
	v_mfma_f32_16x16x32_bf16 v[56:59], v[144:147], v[192:195], v[56:59]
	v_mfma_f32_16x16x32_bf16 v[48:51], v[160:163], v[192:195], v[48:51]
	v_mfma_f32_16x16x32_bf16 v[28:31], v[144:147], v[200:203], v[28:31]
	v_mfma_f32_16x16x32_bf16 v[24:27], v[160:163], v[200:203], v[24:27]
	v_mfma_f32_16x16x32_bf16 v[12:15], v[144:147], v[208:211], v[12:15]
	v_mfma_f32_16x16x32_bf16 v[8:11], v[160:163], v[208:211], v[8:11]
	v_mfma_f32_16x16x32_bf16 v[80:83], v[148:151], v[188:191], v[80:83]
	v_mfma_f32_16x16x32_bf16 v[76:79], v[164:167], v[188:191], v[76:79]
	v_mfma_f32_16x16x32_bf16 v[56:59], v[148:151], v[196:199], v[56:59]
	v_mfma_f32_16x16x32_bf16 v[48:51], v[164:167], v[196:199], v[48:51]
	v_mfma_f32_16x16x32_bf16 v[28:31], v[148:151], v[204:207], v[28:31]
	v_mfma_f32_16x16x32_bf16 v[24:27], v[164:167], v[204:207], v[24:27]
	v_mfma_f32_16x16x32_bf16 v[12:15], v[148:151], v[212:215], v[12:15]
	v_mfma_f32_16x16x32_bf16 v[8:11], v[164:167], v[212:215], v[8:11]
	s_setprio 0
	s_setprio 1
	v_mfma_f32_16x16x32_bf16 v[64:67], v[168:171], v[184:187], v[64:67]
	v_mfma_f32_16x16x32_bf16 v[60:63], v[176:179], v[184:187], v[60:63]
	v_mfma_f32_16x16x32_bf16 v[40:43], v[168:171], v[192:195], v[40:43]
	v_mfma_f32_16x16x32_bf16 v[36:39], v[176:179], v[192:195], v[36:39]
	v_mfma_f32_16x16x32_bf16 v[20:23], v[168:171], v[200:203], v[20:23]
	v_mfma_f32_16x16x32_bf16 v[16:19], v[176:179], v[200:203], v[16:19]
	v_mfma_f32_16x16x32_bf16 v[4:7], v[168:171], v[208:211], v[4:7]
	v_mfma_f32_16x16x32_bf16 v[0:3], v[176:179], v[208:211], v[0:3]
	v_mfma_f32_16x16x32_bf16 v[64:67], v[172:175], v[188:191], v[64:67]
	v_mfma_f32_16x16x32_bf16 v[60:63], v[180:183], v[188:191], v[60:63]
	v_mfma_f32_16x16x32_bf16 v[40:43], v[172:175], v[196:199], v[40:43]
	v_mfma_f32_16x16x32_bf16 v[36:39], v[180:183], v[196:199], v[36:39]
	v_mfma_f32_16x16x32_bf16 v[20:23], v[172:175], v[204:207], v[20:23]
	v_mfma_f32_16x16x32_bf16 v[16:19], v[180:183], v[204:207], v[16:19]
	v_mfma_f32_16x16x32_bf16 v[4:7], v[172:175], v[212:215], v[4:7]
	v_mfma_f32_16x16x32_bf16 v[0:3], v[180:183], v[212:215], v[0:3]
	s_setprio 0
	s_barrier
; #define PG8_STAGE(bufoff, gbase, voff) do { _Pragma("unroll") for (int _i = 0; _i < 2; ++_i) \
;         __builtin_amdgcn_global_load_lds((const unsigned*)((const char*)(gbase) + (voff)[_i]), (PG8_LAS unsigned*)(lds + (bufoff) + ldsw + _i * 8192), 16, 0, 0); } while (0)
; #define PG8_LDA(dst, b, h) do { _Pragma("unroll") for (int m = 0; m < 4; ++m) _Pragma("unroll") for (int k = 0; k < 2; ++k) dst[m][k] = *(const PG8_LAS bf16x8*)(lds + PG8_SA(b, h) + aoff + m * 2048 + k * 1024); } while (0)
; #define PG8_LDB(dst, b, h) do { _Pragma("unroll") for (int n = 0; n < 2; ++n) _Pragma("unroll") for (int k = 0; k < 2; ++k) dst[n][k] = *(const PG8_LAS bf16x8*)(lds + PG8_SB(b, h) + boff + n * 2048 + k * 1024); } while (0)
; #define PG8_MMA(ai, bj, At, Bt) do { __builtin_amdgcn_s_setprio(1); _Pragma("unroll") for (int m = 0; m < 4; ++m) _Pragma("unroll") for (int n = 0; n < 2; ++n) _Pragma("unroll") for (int k = 0; k < 2; ++k) \
;         acc[ai][bj][m][n] = __builtin_amdgcn_mfma_f32_16x16x32_bf16(Bt[n][k], At[m][k], acc[ai][bj][m][n], 0, 0, 0); __builtin_amdgcn_s_setprio(0); } while (0)
; #define PG8_WAIT_V(n) asm volatile("s_waitcnt vmcnt(" #n ")" ::: "memory")
; #define PG8_WAIT_L(n) asm volatile("s_waitcnt lgkmcnt(" #n ")" ::: "memory")
; #define PG8_BAR __builtin_amdgcn_s_barrier()
; #define PG8_SCHED __builtin_amdgcn_sched_barrier(0)
; template <class Epi, class Sched, bool ALIGN_EPI = false, bool SP2 = false>
; __device__ __forceinline__ void gemm_phase(PG8_LAS unsigned char* lds, const Gemm g, const Sched& S, const Epi& E) {
;     ...
;         for (int t = 0; t < nt; t += 2) {
;     ...
;             PG8_LDB(B0, 1, 0); PG8_LDB(B1, 1, 1); PG8_SCHED; PG8_LDA(At, 1, 0); PG8_STAGE(PG8_SA(0, 1), a2 + hstepA, voffA);
;             PG8_WAIT_V(8); PG8_WAIT_L(0); PG8_BAR; PG8_MMA(0, 0, At, B0); PG8_MMA(0, 1, At, B1); PG8_BAR; PG8_SCHED;
;             PG8_LDA(At, 1, 1); PG8_STAGE(PG8_SB(1, 0), b3, voffB); PG8_STAGE(PG8_SB(1, 1), b3 + hstep, voffB); PG8_STAGE(PG8_SA(1, 0), a3, voffA);
;             PG8_WAIT_V(8); PG8_WAIT_L(0); PG8_BAR; PG8_MMA(1, 0, At, B0); PG8_MMA(1, 1, At, B1); PG8_BAR; PG8_SCHED;
	s_add_i32 s65, 0, 0x18000
	s_add_i32 s68, 0, 0x1c000
	v_add_u32_e32 v164, s65, v153
	v_add_u32_e32 v180, s68, v153
	ds_read_b128 v[144:147], v164
	ds_read_b128 v[148:151], v164 offset:1024
	ds_read_b128 v[160:163], v164 offset:2048
	ds_read_b128 v[164:167], v164 offset:3072
	ds_read_b128 v[168:171], v180
	ds_read_b128 v[172:175], v180 offset:1024
	ds_read_b128 v[176:179], v180 offset:2048
	ds_read_b128 v[180:183], v180 offset:3072
	s_add_u32 s66, s88, 0x100000
	s_addc_u32 s67, s89, 0
	s_mov_b32 m0, s41
	ds_read_b128 v[184:187], v157 offset:32768
	ds_read_b128 v[188:191], v157 offset:33792
	ds_read_b128 v[192:195], v157 offset:34816
	ds_read_b128 v[196:199], v157 offset:35840
	ds_read_b128 v[200:203], v157 offset:36864
	ds_read_b128 v[204:207], v157 offset:37888
	ds_read_b128 v[208:211], v157 offset:38912
	ds_read_b128 v[212:215], v157 offset:39936
	global_load_lds_dwordx4 v128, s[66:67]
	s_mov_b32 m0, s52
	s_nop 0
	global_load_lds_dwordx4 v132, s[66:67]
	s_waitcnt vmcnt(8)
	s_waitcnt lgkmcnt(0)
	s_barrier
	s_setprio 1
	s_waitcnt lgkmcnt(0)
	v_mfma_f32_16x16x32_bf16 v[124:127], v[144:147], v[184:187], v[124:127]
	v_mfma_f32_16x16x32_bf16 v[120:123], v[160:163], v[184:187], v[120:123]
	v_mfma_f32_16x16x32_bf16 v[108:111], v[144:147], v[192:195], v[108:111]
	v_mfma_f32_16x16x32_bf16 v[32:35], v[160:163], v[192:195], v[32:35]
	v_mfma_f32_16x16x32_bf16 v[100:103], v[144:147], v[200:203], v[100:103]
	v_mfma_f32_16x16x32_bf16 v[52:55], v[160:163], v[200:203], v[52:55]
	v_mfma_f32_16x16x32_bf16 v[92:95], v[144:147], v[208:211], v[92:95]
	v_mfma_f32_16x16x32_bf16 v[72:75], v[160:163], v[208:211], v[72:75]
	v_mfma_f32_16x16x32_bf16 v[124:127], v[148:151], v[188:191], v[124:127]
	v_mfma_f32_16x16x32_bf16 v[120:123], v[164:167], v[188:191], v[120:123]
	v_mfma_f32_16x16x32_bf16 v[108:111], v[148:151], v[196:199], v[108:111]
	v_mfma_f32_16x16x32_bf16 v[32:35], v[164:167], v[196:199], v[32:35]
	v_mfma_f32_16x16x32_bf16 v[100:103], v[148:151], v[204:207], v[100:103]
	v_mfma_f32_16x16x32_bf16 v[52:55], v[164:167], v[204:207], v[52:55]
	v_mfma_f32_16x16x32_bf16 v[92:95], v[148:151], v[212:215], v[92:95]
	v_mfma_f32_16x16x32_bf16 v[72:75], v[164:167], v[212:215], v[72:75]
	s_setprio 0
	s_setprio 1
	v_mfma_f32_16x16x32_bf16 v[116:119], v[168:171], v[184:187], v[116:119]
	v_mfma_f32_16x16x32_bf16 v[112:115], v[176:179], v[184:187], v[112:115]
	v_mfma_f32_16x16x32_bf16 v[104:107], v[168:171], v[192:195], v[104:107]
	v_mfma_f32_16x16x32_bf16 v[44:47], v[176:179], v[192:195], v[44:47]
	v_mfma_f32_16x16x32_bf16 v[96:99], v[168:171], v[200:203], v[96:99]
	v_mfma_f32_16x16x32_bf16 v[68:71], v[176:179], v[200:203], v[68:71]
	v_mfma_f32_16x16x32_bf16 v[88:91], v[168:171], v[208:211], v[88:91]
	v_mfma_f32_16x16x32_bf16 v[84:87], v[176:179], v[208:211], v[84:87]
	v_mfma_f32_16x16x32_bf16 v[116:119], v[172:175], v[188:191], v[116:119]
	v_mfma_f32_16x16x32_bf16 v[112:115], v[180:183], v[188:191], v[112:115]
	v_mfma_f32_16x16x32_bf16 v[104:107], v[172:175], v[196:199], v[104:107]
	v_mfma_f32_16x16x32_bf16 v[44:47], v[180:183], v[196:199], v[44:47]
	v_mfma_f32_16x16x32_bf16 v[96:99], v[172:175], v[204:207], v[96:99]
	v_mfma_f32_16x16x32_bf16 v[68:71], v[180:183], v[204:207], v[68:71]
	v_mfma_f32_16x16x32_bf16 v[88:91], v[172:175], v[212:215], v[88:91]
	v_mfma_f32_16x16x32_bf16 v[84:87], v[180:183], v[212:215], v[84:87]
	s_setprio 0
	s_barrier
	s_add_i32 s65, s65, s3
	s_mov_b32 m0, s65
	ds_read_b128 v[184:187], v157 offset:49152
	ds_read_b128 v[188:191], v157 offset:50176
	ds_read_b128 v[192:195], v157 offset:51200
	ds_read_b128 v[196:199], v157 offset:52224
	ds_read_b128 v[200:203], v157 offset:53248
	ds_read_b128 v[204:207], v157 offset:54272
	ds_read_b128 v[208:211], v157 offset:55296
	ds_read_b128 v[212:215], v157 offset:56320
	global_load_lds_dwordx4 v130, s[98:99]
	s_add_i32 m0, s65, 0x2000
	s_add_u32 s66, s86, 0x100080
	s_addc_u32 s67, s87, 0
	s_add_i32 s65, s68, s3
	global_load_lds_dwordx4 v134, s[98:99]
	s_mov_b32 m0, s65
	s_nop 0
	global_load_lds_dwordx4 v130, s[66:67]
	s_add_i32 m0, s65, 0x2000
	s_nop 0
	global_load_lds_dwordx4 v134, s[66:67]
	s_mov_b32 m0, s54
	s_nop 0
	global_load_lds_dwordx4 v128, s[100:101]
	s_mov_b32 m0, s55
	s_nop 0
	global_load_lds_dwordx4 v132, s[100:101]
	s_waitcnt vmcnt(8)
	s_waitcnt lgkmcnt(0)
	s_barrier
	s_setprio 1
	s_waitcnt lgkmcnt(0)
	v_mfma_f32_16x16x32_bf16 v[80:83], v[144:147], v[184:187], v[80:83]
	v_mfma_f32_16x16x32_bf16 v[76:79], v[160:163], v[184:187], v[76:79]
	v_mfma_f32_16x16x32_bf16 v[56:59], v[144:147], v[192:195], v[56:59]
	v_mfma_f32_16x16x32_bf16 v[48:51], v[160:163], v[192:195], v[48:51]
	v_mfma_f32_16x16x32_bf16 v[28:31], v[144:147], v[200:203], v[28:31]
	v_mfma_f32_16x16x32_bf16 v[24:27], v[160:163], v[200:203], v[24:27]
	v_mfma_f32_16x16x32_bf16 v[12:15], v[144:147], v[208:211], v[12:15]
	v_mfma_f32_16x16x32_bf16 v[8:11], v[160:163], v[208:211], v[8:11]
	v_mfma_f32_16x16x32_bf16 v[80:83], v[148:151], v[188:191], v[80:83]
	v_mfma_f32_16x16x32_bf16 v[76:79], v[164:167], v[188:191], v[76:79]
	v_mfma_f32_16x16x32_bf16 v[56:59], v[148:151], v[196:199], v[56:59]
	v_mfma_f32_16x16x32_bf16 v[48:51], v[164:167], v[196:199], v[48:51]
	v_mfma_f32_16x16x32_bf16 v[28:31], v[148:151], v[204:207], v[28:31]
	v_mfma_f32_16x16x32_bf16 v[24:27], v[164:167], v[204:207], v[24:27]
	v_mfma_f32_16x16x32_bf16 v[12:15], v[148:151], v[212:215], v[12:15]
	v_mfma_f32_16x16x32_bf16 v[8:11], v[164:167], v[212:215], v[8:11]
	s_setprio 0
	s_setprio 1
	v_mfma_f32_16x16x32_bf16 v[64:67], v[168:171], v[184:187], v[64:67]
	v_mfma_f32_16x16x32_bf16 v[60:63], v[176:179], v[184:187], v[60:63]
	v_mfma_f32_16x16x32_bf16 v[40:43], v[168:171], v[192:195], v[40:43]
	v_mfma_f32_16x16x32_bf16 v[36:39], v[176:179], v[192:195], v[36:39]
	v_mfma_f32_16x16x32_bf16 v[20:23], v[168:171], v[200:203], v[20:23]
	v_mfma_f32_16x16x32_bf16 v[16:19], v[176:179], v[200:203], v[16:19]
	v_mfma_f32_16x16x32_bf16 v[4:7], v[168:171], v[208:211], v[4:7]
	v_mfma_f32_16x16x32_bf16 v[0:3], v[176:179], v[208:211], v[0:3]
	v_mfma_f32_16x16x32_bf16 v[64:67], v[172:175], v[188:191], v[64:67]
	v_mfma_f32_16x16x32_bf16 v[60:63], v[180:183], v[188:191], v[60:63]
	v_mfma_f32_16x16x32_bf16 v[40:43], v[172:175], v[196:199], v[40:43]
	v_mfma_f32_16x16x32_bf16 v[36:39], v[180:183], v[196:199], v[36:39]
	v_mfma_f32_16x16x32_bf16 v[20:23], v[172:175], v[204:207], v[20:23]
	v_mfma_f32_16x16x32_bf16 v[16:19], v[180:183], v[204:207], v[16:19]
	v_mfma_f32_16x16x32_bf16 v[4:7], v[172:175], v[212:215], v[4:7]
	v_mfma_f32_16x16x32_bf16 v[0:3], v[180:183], v[212:215], v[0:3]
	s_setprio 0
	s_barrier
	s_add_i32 s64, s64, 2
	s_add_u32 s84, s84, 0x100
	s_addc_u32 s85, s85, 0
	s_add_u32 s62, s62, 0x100
	s_addc_u32 s63, s63, 0
	s_cmp_gt_u32 s64, 61
	s_cbranch_scc0 .LBB0_1631
	s_and_b64 vcc, exec, s[20:21]
	s_cbranch_vccz .LBB0_1634
	s_barrier

; #define PG8_STAGE(bufoff, gbase, voff) do { _Pragma("unroll") for (int _i = 0; _i < 2; ++_i) \
;         __builtin_amdgcn_global_load_lds((const unsigned*)((const char*)(gbase) + (voff)[_i]), (PG8_LAS unsigned*)(lds + (bufoff) + ldsw + _i * 8192), 16, 0, 0); } while (0)
; #define PG8_LDA(dst, b, h) do { _Pragma("unroll") for (int m = 0; m < 4; ++m) _Pragma("unroll") for (int k = 0; k < 2; ++k) dst[m][k] = *(const PG8_LAS bf16x8*)(lds + PG8_SA(b, h) + aoff + m * 2048 + k * 1024); } while (0)
; #define PG8_LDB(dst, b, h) do { _Pragma("unroll") for (int n = 0; n < 2; ++n) _Pragma("unroll") for (int k = 0; k < 2; ++k) dst[n][k] = *(const PG8_LAS bf16x8*)(lds + PG8_SB(b, h) + boff + n * 2048 + k * 1024); } while (0)
; #define PG8_MMA(ai, bj, At, Bt) do { __builtin_amdgcn_s_setprio(1); _Pragma("unroll") for (int m = 0; m < 4; ++m) _Pragma("unroll") for (int n = 0; n < 2; ++n) _Pragma("unroll") for (int k = 0; k < 2; ++k) \
;         acc[ai][bj][m][n] = __builtin_amdgcn_mfma_f32_16x16x32_bf16(Bt[n][k], At[m][k], acc[ai][bj][m][n], 0, 0, 0); __builtin_amdgcn_s_setprio(0); } while (0)
; #define PG8_WAIT_V(n) asm volatile("s_waitcnt vmcnt(" #n ")" ::: "memory")
; #define PG8_WAIT_L(n) asm volatile("s_waitcnt lgkmcnt(" #n ")" ::: "memory")
; #define PG8_BAR __builtin_amdgcn_s_barrier()
; #define PG8_SCHED __builtin_amdgcn_sched_barrier(0)
; template <class Epi, class Sched, bool ALIGN_EPI = false, bool SP2 = false>
; __device__ __forceinline__ void gemm_phase(PG8_LAS unsigned char* lds, const Gemm g, const Sched& S, const Epi& E) {
;     ...
;             PG8_LDB(B0, 0, 0); PG8_LDB(B1, 0, 1); PG8_SCHED; PG8_LDA(At, 0, 0); PG8_STAGE(PG8_SA(1, 1), a1 + hstepA, voffA);
;             PG8_WAIT_V(8); PG8_WAIT_L(0); PG8_BAR; PG8_MMA(0, 0, At, B0); PG8_MMA(0, 1, At, B1); PG8_BAR; PG8_SCHED;
;             PG8_LDA(At, 0, 1); PG8_STAGE(PG8_SB(0, 0), b2, voffB); PG8_STAGE(PG8_SB(0, 1), b2 + hstep, voffB); PG8_STAGE(PG8_SA(0, 0), a2, voffA);
;             PG8_WAIT_V(8); PG8_WAIT_L(0); PG8_BAR; PG8_MMA(1, 0, At, B0); PG8_MMA(1, 1, At, B1); PG8_BAR; PG8_SCHED;
.LBB0_1741:
	ds_read_b128 v[150:153], v158
	ds_read_b128 v[162:165], v158 offset:1024
	ds_read_b128 v[166:169], v158 offset:2048
	ds_read_b128 v[170:173], v158 offset:3072
	ds_read_b128 v[174:177], v159
	ds_read_b128 v[178:181], v159 offset:1024
	ds_read_b128 v[182:185], v159 offset:2048
	ds_read_b128 v[186:189], v159 offset:3072
	s_add_u32 s40, s34, 0xfff00080
	s_addc_u32 s41, s35, -1
	s_cmp_eq_u32 s67, 60
	s_cselect_b32 s85, s21, s41
	s_cselect_b32 s84, s27, s40
	s_cselect_b32 s41, s19, s66
	s_cselect_b32 s40, s31, s65
	s_add_i32 m0, s53, 0xc000
	ds_read_b128 v[190:193], v160
	ds_read_b128 v[194:197], v160 offset:1024
	ds_read_b128 v[198:201], v160 offset:2048
	ds_read_b128 v[202:205], v160 offset:3072
	ds_read_b128 v[206:209], v160 offset:4096
	ds_read_b128 v[210:213], v160 offset:5120
	ds_read_b128 v[214:217], v160 offset:6144
	ds_read_b128 v[218:221], v160 offset:7168
	global_load_lds_dwordx4 v140, s[34:35]
	s_add_i32 m0, s53, 0xe000
	s_nop 0
	global_load_lds_dwordx4 v142, s[34:35]
	s_waitcnt vmcnt(8)
	s_waitcnt lgkmcnt(0)
	s_barrier
	s_setprio 1
	s_waitcnt lgkmcnt(0)
	v_mfma_f32_16x16x32_bf16 v[124:127], v[150:153], v[190:193], v[124:127]
	v_mfma_f32_16x16x32_bf16 v[120:123], v[166:169], v[190:193], v[120:123]
	v_mfma_f32_16x16x32_bf16 v[108:111], v[150:153], v[198:201], v[108:111]
	v_mfma_f32_16x16x32_bf16 v[104:107], v[166:169], v[198:201], v[104:107]
	v_mfma_f32_16x16x32_bf16 v[92:95], v[150:153], v[206:209], v[92:95]
	v_mfma_f32_16x16x32_bf16 v[88:91], v[166:169], v[206:209], v[88:91]
	v_mfma_f32_16x16x32_bf16 v[76:79], v[150:153], v[214:217], v[76:79]
	v_mfma_f32_16x16x32_bf16 v[72:75], v[166:169], v[214:217], v[72:75]
	v_mfma_f32_16x16x32_bf16 v[124:127], v[162:165], v[194:197], v[124:127]
	v_mfma_f32_16x16x32_bf16 v[120:123], v[170:173], v[194:197], v[120:123]
	v_mfma_f32_16x16x32_bf16 v[108:111], v[162:165], v[202:205], v[108:111]
	v_mfma_f32_16x16x32_bf16 v[104:107], v[170:173], v[202:205], v[104:107]
	v_mfma_f32_16x16x32_bf16 v[92:95], v[162:165], v[210:213], v[92:95]
	v_mfma_f32_16x16x32_bf16 v[88:91], v[170:173], v[210:213], v[88:91]
	v_mfma_f32_16x16x32_bf16 v[76:79], v[162:165], v[218:221], v[76:79]
	v_mfma_f32_16x16x32_bf16 v[72:75], v[170:173], v[218:221], v[72:75]
	s_setprio 0
	s_setprio 1
	v_mfma_f32_16x16x32_bf16 v[116:119], v[174:177], v[190:193], v[116:119]
	v_mfma_f32_16x16x32_bf16 v[112:115], v[182:185], v[190:193], v[112:115]
	v_mfma_f32_16x16x32_bf16 v[100:103], v[174:177], v[198:201], v[100:103]
	v_mfma_f32_16x16x32_bf16 v[96:99], v[182:185], v[198:201], v[96:99]
	v_mfma_f32_16x16x32_bf16 v[84:87], v[174:177], v[206:209], v[84:87]
	v_mfma_f32_16x16x32_bf16 v[80:83], v[182:185], v[206:209], v[80:83]
	v_mfma_f32_16x16x32_bf16 v[68:71], v[174:177], v[214:217], v[68:71]
	v_mfma_f32_16x16x32_bf16 v[64:67], v[182:185], v[214:217], v[64:67]
	v_mfma_f32_16x16x32_bf16 v[116:119], v[178:181], v[194:197], v[116:119]
	v_mfma_f32_16x16x32_bf16 v[112:115], v[186:189], v[194:197], v[112:115]
	v_mfma_f32_16x16x32_bf16 v[100:103], v[178:181], v[202:205], v[100:103]
	v_mfma_f32_16x16x32_bf16 v[96:99], v[186:189], v[202:205], v[96:99]
	v_mfma_f32_16x16x32_bf16 v[84:87], v[178:181], v[210:213], v[84:87]
	v_mfma_f32_16x16x32_bf16 v[80:83], v[186:189], v[210:213], v[80:83]
	v_mfma_f32_16x16x32_bf16 v[68:71], v[178:181], v[218:221], v[68:71]
	v_mfma_f32_16x16x32_bf16 v[64:67], v[186:189], v[218:221], v[64:67]
	s_setprio 0
	s_barrier
	s_add_u32 s98, s40, s12
	s_addc_u32 s99, s41, s13
	s_add_u32 s100, s84, s12
	s_addc_u32 s101, s85, s13
	s_add_i32 s68, s62, s33
	s_mov_b32 m0, s68
	ds_read_b128 v[190:193], v160 offset:16384
	ds_read_b128 v[194:197], v160 offset:17408
	ds_read_b128 v[198:201], v160 offset:18432
	ds_read_b128 v[202:205], v160 offset:19456
	ds_read_b128 v[206:209], v160 offset:20480
	ds_read_b128 v[210:213], v160 offset:21504
	ds_read_b128 v[214:217], v160 offset:22528
	ds_read_b128 v[218:221], v160 offset:23552
	global_load_lds_dwordx4 v132, s[40:41]
	s_add_i32 m0, s68, 0x2000
	s_add_u32 s68, s40, 0x100000
	s_addc_u32 s69, s41, 0
	s_add_i32 s70, s63, s33
	global_load_lds_dwordx4 v128, s[40:41]
	s_mov_b32 m0, s70
	s_nop 0
	global_load_lds_dwordx4 v132, s[68:69]
	s_add_i32 m0, s70, 0x2000
	s_nop 0
	global_load_lds_dwordx4 v128, s[68:69]
	s_mov_b32 m0, s53
	s_nop 0
	global_load_lds_dwordx4 v134, s[84:85]
	s_mov_b32 m0, s54
	s_nop 0
	global_load_lds_dwordx4 v130, s[84:85]
	s_waitcnt vmcnt(8)
	s_waitcnt lgkmcnt(0)
	s_barrier
	s_setprio 1
	s_waitcnt lgkmcnt(0)
	v_mfma_f32_16x16x32_bf16 v[60:63], v[150:153], v[190:193], v[60:63]
	v_mfma_f32_16x16x32_bf16 v[56:59], v[166:169], v[190:193], v[56:59]
	v_mfma_f32_16x16x32_bf16 v[44:47], v[150:153], v[198:201], v[44:47]
	v_mfma_f32_16x16x32_bf16 v[40:43], v[166:169], v[198:201], v[40:43]
	v_mfma_f32_16x16x32_bf16 v[28:31], v[150:153], v[206:209], v[28:31]
	v_mfma_f32_16x16x32_bf16 v[24:27], v[166:169], v[206:209], v[24:27]
	v_mfma_f32_16x16x32_bf16 v[12:15], v[150:153], v[214:217], v[12:15]
	v_mfma_f32_16x16x32_bf16 v[8:11], v[166:169], v[214:217], v[8:11]
	v_mfma_f32_16x16x32_bf16 v[60:63], v[162:165], v[194:197], v[60:63]
	v_mfma_f32_16x16x32_bf16 v[56:59], v[170:173], v[194:197], v[56:59]
	v_mfma_f32_16x16x32_bf16 v[44:47], v[162:165], v[202:205], v[44:47]
	v_mfma_f32_16x16x32_bf16 v[40:43], v[170:173], v[202:205], v[40:43]
	v_mfma_f32_16x16x32_bf16 v[28:31], v[162:165], v[210:213], v[28:31]
	v_mfma_f32_16x16x32_bf16 v[24:27], v[170:173], v[210:213], v[24:27]
	v_mfma_f32_16x16x32_bf16 v[12:15], v[162:165], v[218:221], v[12:15]
	v_mfma_f32_16x16x32_bf16 v[8:11], v[170:173], v[218:221], v[8:11]
	s_setprio 0
	s_setprio 1
	v_mfma_f32_16x16x32_bf16 v[52:55], v[174:177], v[190:193], v[52:55]
	v_mfma_f32_16x16x32_bf16 v[48:51], v[182:185], v[190:193], v[48:51]
	v_mfma_f32_16x16x32_bf16 v[36:39], v[174:177], v[198:201], v[36:39]
	v_mfma_f32_16x16x32_bf16 v[32:35], v[182:185], v[198:201], v[32:35]
	v_mfma_f32_16x16x32_bf16 v[20:23], v[174:177], v[206:209], v[20:23]
	v_mfma_f32_16x16x32_bf16 v[16:19], v[182:185], v[206:209], v[16:19]
	v_mfma_f32_16x16x32_bf16 v[4:7], v[174:177], v[214:217], v[4:7]
	v_mfma_f32_16x16x32_bf16 v[0:3], v[182:185], v[214:217], v[0:3]
	v_mfma_f32_16x16x32_bf16 v[52:55], v[178:181], v[194:197], v[52:55]
	v_mfma_f32_16x16x32_bf16 v[48:51], v[186:189], v[194:197], v[48:51]
	v_mfma_f32_16x16x32_bf16 v[36:39], v[178:181], v[202:205], v[36:39]
	v_mfma_f32_16x16x32_bf16 v[32:35], v[186:189], v[202:205], v[32:35]
	v_mfma_f32_16x16x32_bf16 v[20:23], v[178:181], v[210:213], v[20:23]
	v_mfma_f32_16x16x32_bf16 v[16:19], v[186:189], v[210:213], v[16:19]
	v_mfma_f32_16x16x32_bf16 v[4:7], v[178:181], v[218:221], v[4:7]
	v_mfma_f32_16x16x32_bf16 v[0:3], v[186:189], v[218:221], v[0:3]
	s_setprio 0
	s_barrier
; #define PG8_STAGE(bufoff, gbase, voff) do { _Pragma("unroll") for (int _i = 0; _i < 2; ++_i) \
;         __builtin_amdgcn_global_load_lds((const unsigned*)((const char*)(gbase) + (voff)[_i]), (PG8_LAS unsigned*)(lds + (bufoff) + ldsw + _i * 8192), 16, 0, 0); } while (0)
; #define PG8_LDA(dst, b, h) do { _Pragma("unroll") for (int m = 0; m < 4; ++m) _Pragma("unroll") for (int k = 0; k < 2; ++k) dst[m][k] = *(const PG8_LAS bf16x8*)(lds + PG8_SA(b, h) + aoff + m * 2048 + k * 1024); } while (0)
; #define PG8_LDB(dst, b, h) do { _Pragma("unroll") for (int n = 0; n < 2; ++n) _Pragma("unroll") for (int k = 0; k < 2; ++k) dst[n][k] = *(const PG8_LAS bf16x8*)(lds + PG8_SB(b, h) + boff + n * 2048 + k * 1024); } while (0)
; #define PG8_MMA(ai, bj, At, Bt) do { __builtin_amdgcn_s_setprio(1); _Pragma("unroll") for (int m = 0; m < 4; ++m) _Pragma("unroll") for (int n = 0; n < 2; ++n) _Pragma("unroll") for (int k = 0; k < 2; ++k) \
;         acc[ai][bj][m][n] = __builtin_amdgcn_mfma_f32_16x16x32_bf16(Bt[n][k], At[m][k], acc[ai][bj][m][n], 0, 0, 0); __builtin_amdgcn_s_setprio(0); } while (0)
; #define PG8_WAIT_V(n) asm volatile("s_waitcnt vmcnt(" #n ")" ::: "memory")
; #define PG8_WAIT_L(n) asm volatile("s_waitcnt lgkmcnt(" #n ")" ::: "memory")
; #define PG8_BAR __builtin_amdgcn_s_barrier()
; #define PG8_SCHED __builtin_amdgcn_sched_barrier(0)
; template <class Epi, class Sched, bool ALIGN_EPI = false, bool SP2 = false>
; __device__ __forceinline__ void gemm_phase(PG8_LAS unsigned char* lds, const Gemm g, const Sched& S, const Epi& E) {
;     ...
;         for (int t = 0; t < nt; t += 2) {
;     ...
;             PG8_LDB(B0, 1, 0); PG8_LDB(B1, 1, 1); PG8_SCHED; PG8_LDA(At, 1, 0); PG8_STAGE(PG8_SA(0, 1), a2 + hstepA, voffA);
;             PG8_WAIT_V(8); PG8_WAIT_L(0); PG8_BAR; PG8_MMA(0, 0, At, B0); PG8_MMA(0, 1, At, B1); PG8_BAR; PG8_SCHED;
;             PG8_LDA(At, 1, 1); PG8_STAGE(PG8_SB(1, 0), b3, voffB); PG8_STAGE(PG8_SB(1, 1), b3 + hstep, voffB); PG8_STAGE(PG8_SA(1, 0), a3, voffA);
;             PG8_WAIT_V(8); PG8_WAIT_L(0); PG8_BAR; PG8_MMA(1, 0, At, B0); PG8_MMA(1, 1, At, B1); PG8_BAR; PG8_SCHED;
	s_add_i32 s70, 0, 0x18000
	v_add_u32_e32 v136, s70, v157
	s_add_i32 s71, 0, 0x1c000
	ds_read_b128 v[150:153], v136
	ds_read_b128 v[162:165], v136 offset:1024
	ds_read_b128 v[166:169], v136 offset:2048
	ds_read_b128 v[170:173], v136 offset:3072
	v_add_u32_e32 v136, s71, v157
	ds_read_b128 v[174:177], v136
	ds_read_b128 v[178:181], v136 offset:1024
	ds_read_b128 v[182:185], v136 offset:2048
	ds_read_b128 v[186:189], v136 offset:3072
	s_add_u32 s68, s84, 0x100000
	s_addc_u32 s69, s85, 0
	s_mov_b32 m0, s55
	ds_read_b128 v[190:193], v160 offset:32768
	ds_read_b128 v[194:197], v160 offset:33792
	ds_read_b128 v[198:201], v160 offset:34816
	ds_read_b128 v[202:205], v160 offset:35840
	ds_read_b128 v[206:209], v160 offset:36864
	ds_read_b128 v[210:213], v160 offset:37888
	ds_read_b128 v[214:217], v160 offset:38912
	ds_read_b128 v[218:221], v160 offset:39936
	global_load_lds_dwordx4 v134, s[68:69]
	s_mov_b32 m0, s56
	s_nop 0
	global_load_lds_dwordx4 v130, s[68:69]
	s_waitcnt vmcnt(8)
	s_waitcnt lgkmcnt(0)
	s_barrier
	s_setprio 1
	s_waitcnt lgkmcnt(0)
	v_mfma_f32_16x16x32_bf16 v[124:127], v[150:153], v[190:193], v[124:127]
	v_mfma_f32_16x16x32_bf16 v[120:123], v[166:169], v[190:193], v[120:123]
	v_mfma_f32_16x16x32_bf16 v[108:111], v[150:153], v[198:201], v[108:111]
	v_mfma_f32_16x16x32_bf16 v[104:107], v[166:169], v[198:201], v[104:107]
	v_mfma_f32_16x16x32_bf16 v[92:95], v[150:153], v[206:209], v[92:95]
	v_mfma_f32_16x16x32_bf16 v[88:91], v[166:169], v[206:209], v[88:91]
	v_mfma_f32_16x16x32_bf16 v[76:79], v[150:153], v[214:217], v[76:79]
	v_mfma_f32_16x16x32_bf16 v[72:75], v[166:169], v[214:217], v[72:75]
	v_mfma_f32_16x16x32_bf16 v[124:127], v[162:165], v[194:197], v[124:127]
	v_mfma_f32_16x16x32_bf16 v[120:123], v[170:173], v[194:197], v[120:123]
	v_mfma_f32_16x16x32_bf16 v[108:111], v[162:165], v[202:205], v[108:111]
	v_mfma_f32_16x16x32_bf16 v[104:107], v[170:173], v[202:205], v[104:107]
	v_mfma_f32_16x16x32_bf16 v[92:95], v[162:165], v[210:213], v[92:95]
	v_mfma_f32_16x16x32_bf16 v[88:91], v[170:173], v[210:213], v[88:91]
	v_mfma_f32_16x16x32_bf16 v[76:79], v[162:165], v[218:221], v[76:79]
	v_mfma_f32_16x16x32_bf16 v[72:75], v[170:173], v[218:221], v[72:75]
	s_setprio 0
	s_setprio 1
	v_mfma_f32_16x16x32_bf16 v[116:119], v[174:177], v[190:193], v[116:119]
	v_mfma_f32_16x16x32_bf16 v[112:115], v[182:185], v[190:193], v[112:115]
	v_mfma_f32_16x16x32_bf16 v[100:103], v[174:177], v[198:201], v[100:103]
	v_mfma_f32_16x16x32_bf16 v[96:99], v[182:185], v[198:201], v[96:99]
	v_mfma_f32_16x16x32_bf16 v[84:87], v[174:177], v[206:209], v[84:87]
	v_mfma_f32_16x16x32_bf16 v[80:83], v[182:185], v[206:209], v[80:83]
	v_mfma_f32_16x16x32_bf16 v[68:71], v[174:177], v[214:217], v[68:71]
	v_mfma_f32_16x16x32_bf16 v[64:67], v[182:185], v[214:217], v[64:67]
	v_mfma_f32_16x16x32_bf16 v[116:119], v[178:181], v[194:197], v[116:119]
	v_mfma_f32_16x16x32_bf16 v[112:115], v[186:189], v[194:197], v[112:115]
	v_mfma_f32_16x16x32_bf16 v[100:103], v[178:181], v[202:205], v[100:103]
	v_mfma_f32_16x16x32_bf16 v[96:99], v[186:189], v[202:205], v[96:99]
	v_mfma_f32_16x16x32_bf16 v[84:87], v[178:181], v[210:213], v[84:87]
	v_mfma_f32_16x16x32_bf16 v[80:83], v[186:189], v[210:213], v[80:83]
	v_mfma_f32_16x16x32_bf16 v[68:71], v[178:181], v[218:221], v[68:71]
	v_mfma_f32_16x16x32_bf16 v[64:67], v[186:189], v[218:221], v[64:67]
	s_setprio 0
	s_barrier
	s_add_i32 s68, s70, s33
	s_mov_b32 m0, s68
	ds_read_b128 v[190:193], v160 offset:49152
	ds_read_b128 v[194:197], v160 offset:50176
	ds_read_b128 v[198:201], v160 offset:51200
	ds_read_b128 v[202:205], v160 offset:52224
	ds_read_b128 v[206:209], v160 offset:53248
	ds_read_b128 v[210:213], v160 offset:54272
	ds_read_b128 v[214:217], v160 offset:55296
	ds_read_b128 v[218:221], v160 offset:56320
	global_load_lds_dwordx4 v132, s[98:99]
	s_add_i32 m0, s68, 0x2000
	s_add_u32 s40, s40, 0x100080
	s_addc_u32 s41, s41, 0
	s_add_i32 s68, s71, s33
	global_load_lds_dwordx4 v128, s[98:99]
	s_mov_b32 m0, s68
	s_nop 0
	global_load_lds_dwordx4 v132, s[40:41]
	s_add_i32 m0, s68, 0x2000
	s_nop 0
	global_load_lds_dwordx4 v128, s[40:41]
	s_mov_b32 m0, s60
	s_nop 0
	global_load_lds_dwordx4 v134, s[100:101]
	s_mov_b32 m0, s61
	s_nop 0
	global_load_lds_dwordx4 v130, s[100:101]
	s_waitcnt vmcnt(8)
	s_waitcnt lgkmcnt(0)
	s_barrier
	s_setprio 1
	s_waitcnt lgkmcnt(0)
	v_mfma_f32_16x16x32_bf16 v[60:63], v[150:153], v[190:193], v[60:63]
	v_mfma_f32_16x16x32_bf16 v[56:59], v[166:169], v[190:193], v[56:59]
	v_mfma_f32_16x16x32_bf16 v[44:47], v[150:153], v[198:201], v[44:47]
	v_mfma_f32_16x16x32_bf16 v[40:43], v[166:169], v[198:201], v[40:43]
	v_mfma_f32_16x16x32_bf16 v[28:31], v[150:153], v[206:209], v[28:31]
	v_mfma_f32_16x16x32_bf16 v[24:27], v[166:169], v[206:209], v[24:27]
	v_mfma_f32_16x16x32_bf16 v[12:15], v[150:153], v[214:217], v[12:15]
	v_mfma_f32_16x16x32_bf16 v[8:11], v[166:169], v[214:217], v[8:11]
	v_mfma_f32_16x16x32_bf16 v[60:63], v[162:165], v[194:197], v[60:63]
	v_mfma_f32_16x16x32_bf16 v[56:59], v[170:173], v[194:197], v[56:59]
	v_mfma_f32_16x16x32_bf16 v[44:47], v[162:165], v[202:205], v[44:47]
	v_mfma_f32_16x16x32_bf16 v[40:43], v[170:173], v[202:205], v[40:43]
	v_mfma_f32_16x16x32_bf16 v[28:31], v[162:165], v[210:213], v[28:31]
	v_mfma_f32_16x16x32_bf16 v[24:27], v[170:173], v[210:213], v[24:27]
	v_mfma_f32_16x16x32_bf16 v[12:15], v[162:165], v[218:221], v[12:15]
	v_mfma_f32_16x16x32_bf16 v[8:11], v[170:173], v[218:221], v[8:11]
	s_setprio 0
	s_setprio 1
	v_mfma_f32_16x16x32_bf16 v[52:55], v[174:177], v[190:193], v[52:55]
	v_mfma_f32_16x16x32_bf16 v[48:51], v[182:185], v[190:193], v[48:51]
	v_mfma_f32_16x16x32_bf16 v[36:39], v[174:177], v[198:201], v[36:39]
	v_mfma_f32_16x16x32_bf16 v[32:35], v[182:185], v[198:201], v[32:35]
	v_mfma_f32_16x16x32_bf16 v[20:23], v[174:177], v[206:209], v[20:23]
	v_mfma_f32_16x16x32_bf16 v[16:19], v[182:185], v[206:209], v[16:19]
	v_mfma_f32_16x16x32_bf16 v[4:7], v[174:177], v[214:217], v[4:7]
	v_mfma_f32_16x16x32_bf16 v[0:3], v[182:185], v[214:217], v[0:3]
	v_mfma_f32_16x16x32_bf16 v[52:55], v[178:181], v[194:197], v[52:55]
	v_mfma_f32_16x16x32_bf16 v[48:51], v[186:189], v[194:197], v[48:51]
	v_mfma_f32_16x16x32_bf16 v[36:39], v[178:181], v[202:205], v[36:39]
	v_mfma_f32_16x16x32_bf16 v[32:35], v[186:189], v[202:205], v[32:35]
	v_mfma_f32_16x16x32_bf16 v[20:23], v[178:181], v[210:213], v[20:23]
	v_mfma_f32_16x16x32_bf16 v[16:19], v[186:189], v[210:213], v[16:19]
	v_mfma_f32_16x16x32_bf16 v[4:7], v[178:181], v[218:221], v[4:7]
	v_mfma_f32_16x16x32_bf16 v[0:3], v[186:189], v[218:221], v[0:3]
	s_setprio 0
	s_barrier
	s_add_i32 s67, s67, 2
	s_add_u32 s34, s34, 0x100
	s_addc_u32 s35, s35, 0
	s_add_u32 s65, s65, 0x100
	s_addc_u32 s66, s66, 0
	s_cmp_gt_u32 s67, 61
	s_cbranch_scc0 .LBB0_1741
	s_and_b64 vcc, exec, s[14:15]
	s_cbranch_vccz .LBB0_1744
	s_barrier

; #define PG8_STAGE(bufoff, gbase, voff) do { _Pragma("unroll") for (int _i = 0; _i < 2; ++_i) \
;         __builtin_amdgcn_global_load_lds((const unsigned*)((const char*)(gbase) + (voff)[_i]), (PG8_LAS unsigned*)(lds + (bufoff) + ldsw + _i * 8192), 16, 0, 0); } while (0)
; #define PG8_LDA(dst, b, h) do { _Pragma("unroll") for (int m = 0; m < 4; ++m) _Pragma("unroll") for (int k = 0; k < 2; ++k) dst[m][k] = *(const PG8_LAS bf16x8*)(lds + PG8_SA(b, h) + aoff + m * 2048 + k * 1024); } while (0)
; #define PG8_LDB(dst, b, h) do { _Pragma("unroll") for (int n = 0; n < 2; ++n) _Pragma("unroll") for (int k = 0; k < 2; ++k) dst[n][k] = *(const PG8_LAS bf16x8*)(lds + PG8_SB(b, h) + boff + n * 2048 + k * 1024); } while (0)
; #define PG8_MMA(ai, bj, At, Bt) do { __builtin_amdgcn_s_setprio(1); _Pragma("unroll") for (int m = 0; m < 4; ++m) _Pragma("unroll") for (int n = 0; n < 2; ++n) _Pragma("unroll") for (int k = 0; k < 2; ++k) \
;         acc[ai][bj][m][n] = __builtin_amdgcn_mfma_f32_16x16x32_bf16(Bt[n][k], At[m][k], acc[ai][bj][m][n], 0, 0, 0); __builtin_amdgcn_s_setprio(0); } while (0)
; #define PG8_WAIT_V(n) asm volatile("s_waitcnt vmcnt(" #n ")" ::: "memory")
; #define PG8_WAIT_L(n) asm volatile("s_waitcnt lgkmcnt(" #n ")" ::: "memory")
; #define PG8_BAR __builtin_amdgcn_s_barrier()
; #define PG8_SCHED __builtin_amdgcn_sched_barrier(0)
; template <class Epi, class Sched, bool ALIGN_EPI = false, bool SP2 = false>
; __device__ __forceinline__ void gemm_phase(PG8_LAS unsigned char* lds, const Gemm g, const Sched& S, const Epi& E) {
;     ...
;             PG8_LDB(B0, 0, 0); PG8_LDB(B1, 0, 1); PG8_SCHED; PG8_LDA(At, 0, 0); PG8_STAGE(PG8_SA(1, 1), a1 + hstepA, voffA);
;             PG8_WAIT_V(8); PG8_WAIT_L(0); PG8_BAR; PG8_MMA(0, 0, At, B0); PG8_MMA(0, 1, At, B1); PG8_BAR; PG8_SCHED;
;             PG8_LDA(At, 0, 1); PG8_STAGE(PG8_SB(0, 0), b2, voffB); PG8_STAGE(PG8_SB(0, 1), b2 + hstep, voffB); PG8_STAGE(PG8_SA(0, 0), a2, voffA);
;             PG8_WAIT_V(8); PG8_WAIT_L(0); PG8_BAR; PG8_MMA(1, 0, At, B0); PG8_MMA(1, 1, At, B1); PG8_BAR; PG8_SCHED;
.LBB0_2770:
	ds_read_b128 v[144:147], v153
	ds_read_b128 v[158:161], v153 offset:1024
	ds_read_b128 v[162:165], v153 offset:2048
	ds_read_b128 v[166:169], v153 offset:3072
	ds_read_b128 v[170:173], v154
	ds_read_b128 v[174:177], v154 offset:1024
	ds_read_b128 v[178:181], v154 offset:2048
	ds_read_b128 v[182:185], v154 offset:3072
	s_add_u32 s48, s46, 0xfff00080
	s_addc_u32 s49, s47, -1
	s_cmp_eq_u32 s69, 60
	s_cselect_b32 s51, s31, s49
	s_cselect_b32 s50, s43, s48
	s_cselect_b32 s49, s27, s68
	s_cselect_b32 s48, s66, s67
	s_add_i32 m0, s45, 0xc000
	ds_read_b128 v[186:189], v155
	ds_read_b128 v[190:193], v155 offset:1024
	ds_read_b128 v[194:197], v155 offset:2048
	ds_read_b128 v[198:201], v155 offset:3072
	ds_read_b128 v[202:205], v155 offset:4096
	ds_read_b128 v[206:209], v155 offset:5120
	ds_read_b128 v[210:213], v155 offset:6144
	ds_read_b128 v[214:217], v155 offset:7168
	global_load_lds_dwordx4 v136, s[46:47]
	s_add_i32 m0, s45, 0xe000
	s_nop 0
	global_load_lds_dwordx4 v138, s[46:47]
	s_waitcnt vmcnt(8)
	s_waitcnt lgkmcnt(0)
	s_barrier
	s_setprio 1
	s_waitcnt lgkmcnt(0)
	v_mfma_f32_16x16x32_bf16 v[124:127], v[144:147], v[186:189], v[124:127]
	v_mfma_f32_16x16x32_bf16 v[120:123], v[162:165], v[186:189], v[120:123]
	v_mfma_f32_16x16x32_bf16 v[108:111], v[144:147], v[194:197], v[108:111]
	v_mfma_f32_16x16x32_bf16 v[104:107], v[162:165], v[194:197], v[104:107]
	v_mfma_f32_16x16x32_bf16 v[92:95], v[144:147], v[202:205], v[92:95]
	v_mfma_f32_16x16x32_bf16 v[88:91], v[162:165], v[202:205], v[88:91]
	v_mfma_f32_16x16x32_bf16 v[76:79], v[144:147], v[210:213], v[76:79]
	v_mfma_f32_16x16x32_bf16 v[72:75], v[162:165], v[210:213], v[72:75]
	v_mfma_f32_16x16x32_bf16 v[124:127], v[158:161], v[190:193], v[124:127]
	v_mfma_f32_16x16x32_bf16 v[120:123], v[166:169], v[190:193], v[120:123]
	v_mfma_f32_16x16x32_bf16 v[108:111], v[158:161], v[198:201], v[108:111]
	v_mfma_f32_16x16x32_bf16 v[104:107], v[166:169], v[198:201], v[104:107]
	v_mfma_f32_16x16x32_bf16 v[92:95], v[158:161], v[206:209], v[92:95]
	v_mfma_f32_16x16x32_bf16 v[88:91], v[166:169], v[206:209], v[88:91]
	v_mfma_f32_16x16x32_bf16 v[76:79], v[158:161], v[214:217], v[76:79]
	v_mfma_f32_16x16x32_bf16 v[72:75], v[166:169], v[214:217], v[72:75]
	s_setprio 0
	s_setprio 1
	v_mfma_f32_16x16x32_bf16 v[116:119], v[170:173], v[186:189], v[116:119]
	v_mfma_f32_16x16x32_bf16 v[112:115], v[178:181], v[186:189], v[112:115]
	v_mfma_f32_16x16x32_bf16 v[100:103], v[170:173], v[194:197], v[100:103]
	v_mfma_f32_16x16x32_bf16 v[96:99], v[178:181], v[194:197], v[96:99]
	v_mfma_f32_16x16x32_bf16 v[84:87], v[170:173], v[202:205], v[84:87]
	v_mfma_f32_16x16x32_bf16 v[80:83], v[178:181], v[202:205], v[80:83]
	v_mfma_f32_16x16x32_bf16 v[68:71], v[170:173], v[210:213], v[68:71]
	v_mfma_f32_16x16x32_bf16 v[64:67], v[178:181], v[210:213], v[64:67]
	v_mfma_f32_16x16x32_bf16 v[116:119], v[174:177], v[190:193], v[116:119]
	v_mfma_f32_16x16x32_bf16 v[112:115], v[182:185], v[190:193], v[112:115]
	v_mfma_f32_16x16x32_bf16 v[100:103], v[174:177], v[198:201], v[100:103]
	v_mfma_f32_16x16x32_bf16 v[96:99], v[182:185], v[198:201], v[96:99]
	v_mfma_f32_16x16x32_bf16 v[84:87], v[174:177], v[206:209], v[84:87]
	v_mfma_f32_16x16x32_bf16 v[80:83], v[182:185], v[206:209], v[80:83]
	v_mfma_f32_16x16x32_bf16 v[68:71], v[174:177], v[214:217], v[68:71]
	v_mfma_f32_16x16x32_bf16 v[64:67], v[182:185], v[214:217], v[64:67]
	s_setprio 0
	s_barrier
	s_add_u32 s98, s48, s16
	s_addc_u32 s99, s49, s17
	s_add_u32 s100, s50, s16
	s_addc_u32 s101, s51, s17
	s_add_i32 s70, s60, s33
	s_mov_b32 m0, s70
	ds_read_b128 v[186:189], v155 offset:16384
	ds_read_b128 v[190:193], v155 offset:17408
	ds_read_b128 v[194:197], v155 offset:18432
	ds_read_b128 v[198:201], v155 offset:19456
	ds_read_b128 v[202:205], v155 offset:20480
	ds_read_b128 v[206:209], v155 offset:21504
	ds_read_b128 v[210:213], v155 offset:22528
	ds_read_b128 v[214:217], v155 offset:23552
	global_load_lds_dwordx4 v130, s[48:49]
	s_add_i32 m0, s70, 0x2000
	s_add_u32 s70, s48, 0x100000
	s_addc_u32 s71, s49, 0
	s_add_i32 s72, s61, s33
	global_load_lds_dwordx4 v134, s[48:49]
	s_mov_b32 m0, s72
	s_nop 0
	global_load_lds_dwordx4 v130, s[70:71]
	s_add_i32 m0, s72, 0x2000
	s_nop 0
	global_load_lds_dwordx4 v134, s[70:71]
	s_mov_b32 m0, s45
	s_nop 0
	global_load_lds_dwordx4 v128, s[50:51]
	s_mov_b32 m0, s52
	s_nop 0
	global_load_lds_dwordx4 v132, s[50:51]
	s_waitcnt vmcnt(8)
	s_waitcnt lgkmcnt(0)
	s_barrier
	s_setprio 1
	s_waitcnt lgkmcnt(0)
	v_mfma_f32_16x16x32_bf16 v[60:63], v[144:147], v[186:189], v[60:63]
	v_mfma_f32_16x16x32_bf16 v[56:59], v[162:165], v[186:189], v[56:59]
	v_mfma_f32_16x16x32_bf16 v[44:47], v[144:147], v[194:197], v[44:47]
	v_mfma_f32_16x16x32_bf16 v[40:43], v[162:165], v[194:197], v[40:43]
	v_mfma_f32_16x16x32_bf16 v[28:31], v[144:147], v[202:205], v[28:31]
	v_mfma_f32_16x16x32_bf16 v[24:27], v[162:165], v[202:205], v[24:27]
	v_mfma_f32_16x16x32_bf16 v[12:15], v[144:147], v[210:213], v[12:15]
	v_mfma_f32_16x16x32_bf16 v[8:11], v[162:165], v[210:213], v[8:11]
	v_mfma_f32_16x16x32_bf16 v[60:63], v[158:161], v[190:193], v[60:63]
	v_mfma_f32_16x16x32_bf16 v[56:59], v[166:169], v[190:193], v[56:59]
	v_mfma_f32_16x16x32_bf16 v[44:47], v[158:161], v[198:201], v[44:47]
	v_mfma_f32_16x16x32_bf16 v[40:43], v[166:169], v[198:201], v[40:43]
	v_mfma_f32_16x16x32_bf16 v[28:31], v[158:161], v[206:209], v[28:31]
	v_mfma_f32_16x16x32_bf16 v[24:27], v[166:169], v[206:209], v[24:27]
	v_mfma_f32_16x16x32_bf16 v[12:15], v[158:161], v[214:217], v[12:15]
	v_mfma_f32_16x16x32_bf16 v[8:11], v[166:169], v[214:217], v[8:11]
	s_setprio 0
	s_setprio 1
	v_mfma_f32_16x16x32_bf16 v[52:55], v[170:173], v[186:189], v[52:55]
	v_mfma_f32_16x16x32_bf16 v[48:51], v[178:181], v[186:189], v[48:51]
	v_mfma_f32_16x16x32_bf16 v[36:39], v[170:173], v[194:197], v[36:39]
	v_mfma_f32_16x16x32_bf16 v[32:35], v[178:181], v[194:197], v[32:35]
	v_mfma_f32_16x16x32_bf16 v[20:23], v[170:173], v[202:205], v[20:23]
	v_mfma_f32_16x16x32_bf16 v[16:19], v[178:181], v[202:205], v[16:19]
	v_mfma_f32_16x16x32_bf16 v[4:7], v[170:173], v[210:213], v[4:7]
	v_mfma_f32_16x16x32_bf16 v[0:3], v[178:181], v[210:213], v[0:3]
	v_mfma_f32_16x16x32_bf16 v[52:55], v[174:177], v[190:193], v[52:55]
	v_mfma_f32_16x16x32_bf16 v[48:51], v[182:185], v[190:193], v[48:51]
	v_mfma_f32_16x16x32_bf16 v[36:39], v[174:177], v[198:201], v[36:39]
	v_mfma_f32_16x16x32_bf16 v[32:35], v[182:185], v[198:201], v[32:35]
	v_mfma_f32_16x16x32_bf16 v[20:23], v[174:177], v[206:209], v[20:23]
	v_mfma_f32_16x16x32_bf16 v[16:19], v[182:185], v[206:209], v[16:19]
	v_mfma_f32_16x16x32_bf16 v[4:7], v[174:177], v[214:217], v[4:7]
	v_mfma_f32_16x16x32_bf16 v[0:3], v[182:185], v[214:217], v[0:3]
	s_setprio 0
	s_barrier
; #define PG8_STAGE(bufoff, gbase, voff) do { _Pragma("unroll") for (int _i = 0; _i < 2; ++_i) \
;         __builtin_amdgcn_global_load_lds((const unsigned*)((const char*)(gbase) + (voff)[_i]), (PG8_LAS unsigned*)(lds + (bufoff) + ldsw + _i * 8192), 16, 0, 0); } while (0)
; #define PG8_LDA(dst, b, h) do { _Pragma("unroll") for (int m = 0; m < 4; ++m) _Pragma("unroll") for (int k = 0; k < 2; ++k) dst[m][k] = *(const PG8_LAS bf16x8*)(lds + PG8_SA(b, h) + aoff + m * 2048 + k * 1024); } while (0)
; #define PG8_LDB(dst, b, h) do { _Pragma("unroll") for (int n = 0; n < 2; ++n) _Pragma("unroll") for (int k = 0; k < 2; ++k) dst[n][k] = *(const PG8_LAS bf16x8*)(lds + PG8_SB(b, h) + boff + n * 2048 + k * 1024); } while (0)
; #define PG8_MMA(ai, bj, At, Bt) do { __builtin_amdgcn_s_setprio(1); _Pragma("unroll") for (int m = 0; m < 4; ++m) _Pragma("unroll") for (int n = 0; n < 2; ++n) _Pragma("unroll") for (int k = 0; k < 2; ++k) \
;         acc[ai][bj][m][n] = __builtin_amdgcn_mfma_f32_16x16x32_bf16(Bt[n][k], At[m][k], acc[ai][bj][m][n], 0, 0, 0); __builtin_amdgcn_s_setprio(0); } while (0)
; #define PG8_WAIT_V(n) asm volatile("s_waitcnt vmcnt(" #n ")" ::: "memory")
; #define PG8_WAIT_L(n) asm volatile("s_waitcnt lgkmcnt(" #n ")" ::: "memory")
; #define PG8_BAR __builtin_amdgcn_s_barrier()
; #define PG8_SCHED __builtin_amdgcn_sched_barrier(0)
; template <class Epi, class Sched, bool ALIGN_EPI = false, bool SP2 = false>
; __device__ __forceinline__ void gemm_phase(PG8_LAS unsigned char* lds, const Gemm g, const Sched& S, const Epi& E) {
;     ...
;         for (int t = 0; t < nt; t += 2) {
;     ...
;             PG8_LDB(B0, 1, 0); PG8_LDB(B1, 1, 1); PG8_SCHED; PG8_LDA(At, 1, 0); PG8_STAGE(PG8_SA(0, 1), a2 + hstepA, voffA);
;             PG8_WAIT_V(8); PG8_WAIT_L(0); PG8_BAR; PG8_MMA(0, 0, At, B0); PG8_MMA(0, 1, At, B1); PG8_BAR; PG8_SCHED;
;             PG8_LDA(At, 1, 1); PG8_STAGE(PG8_SB(1, 0), b3, voffB); PG8_STAGE(PG8_SB(1, 1), b3 + hstep, voffB); PG8_STAGE(PG8_SA(1, 0), a3, voffA);
;             PG8_WAIT_V(8); PG8_WAIT_L(0); PG8_BAR; PG8_MMA(1, 0, At, B0); PG8_MMA(1, 1, At, B1); PG8_BAR; PG8_SCHED;
	s_add_i32 s70, 0, 0x18000
	v_add_u32_e32 v157, s70, v151
	s_add_i32 s71, 0, 0x1c000
	ds_read_b128 v[144:147], v157
	ds_read_b128 v[158:161], v157 offset:1024
	ds_read_b128 v[162:165], v157 offset:2048
	ds_read_b128 v[166:169], v157 offset:3072
	v_add_u32_e32 v157, s71, v151
	ds_read_b128 v[170:173], v157
	ds_read_b128 v[174:177], v157 offset:1024
	ds_read_b128 v[178:181], v157 offset:2048
	ds_read_b128 v[182:185], v157 offset:3072
	s_add_u32 s50, s50, 0x100000
	s_addc_u32 s51, s51, 0
	s_mov_b32 m0, s53
	ds_read_b128 v[186:189], v155 offset:32768
	ds_read_b128 v[190:193], v155 offset:33792
	ds_read_b128 v[194:197], v155 offset:34816
	ds_read_b128 v[198:201], v155 offset:35840
	ds_read_b128 v[202:205], v155 offset:36864
	ds_read_b128 v[206:209], v155 offset:37888
	ds_read_b128 v[210:213], v155 offset:38912
	ds_read_b128 v[214:217], v155 offset:39936
	global_load_lds_dwordx4 v128, s[50:51]
	s_mov_b32 m0, s54
	s_nop 0
	global_load_lds_dwordx4 v132, s[50:51]
	s_waitcnt vmcnt(8)
	s_waitcnt lgkmcnt(0)
	s_barrier
	s_setprio 1
	s_waitcnt lgkmcnt(0)
	v_mfma_f32_16x16x32_bf16 v[124:127], v[144:147], v[186:189], v[124:127]
	v_mfma_f32_16x16x32_bf16 v[120:123], v[162:165], v[186:189], v[120:123]
	v_mfma_f32_16x16x32_bf16 v[108:111], v[144:147], v[194:197], v[108:111]
	v_mfma_f32_16x16x32_bf16 v[104:107], v[162:165], v[194:197], v[104:107]
	v_mfma_f32_16x16x32_bf16 v[92:95], v[144:147], v[202:205], v[92:95]
	v_mfma_f32_16x16x32_bf16 v[88:91], v[162:165], v[202:205], v[88:91]
	v_mfma_f32_16x16x32_bf16 v[76:79], v[144:147], v[210:213], v[76:79]
	v_mfma_f32_16x16x32_bf16 v[72:75], v[162:165], v[210:213], v[72:75]
	v_mfma_f32_16x16x32_bf16 v[124:127], v[158:161], v[190:193], v[124:127]
	v_mfma_f32_16x16x32_bf16 v[120:123], v[166:169], v[190:193], v[120:123]
	v_mfma_f32_16x16x32_bf16 v[108:111], v[158:161], v[198:201], v[108:111]
	v_mfma_f32_16x16x32_bf16 v[104:107], v[166:169], v[198:201], v[104:107]
	v_mfma_f32_16x16x32_bf16 v[92:95], v[158:161], v[206:209], v[92:95]
	v_mfma_f32_16x16x32_bf16 v[88:91], v[166:169], v[206:209], v[88:91]
	v_mfma_f32_16x16x32_bf16 v[76:79], v[158:161], v[214:217], v[76:79]
	v_mfma_f32_16x16x32_bf16 v[72:75], v[166:169], v[214:217], v[72:75]
	s_setprio 0
	s_setprio 1
	v_mfma_f32_16x16x32_bf16 v[116:119], v[170:173], v[186:189], v[116:119]
	v_mfma_f32_16x16x32_bf16 v[112:115], v[178:181], v[186:189], v[112:115]
	v_mfma_f32_16x16x32_bf16 v[100:103], v[170:173], v[194:197], v[100:103]
	v_mfma_f32_16x16x32_bf16 v[96:99], v[178:181], v[194:197], v[96:99]
	v_mfma_f32_16x16x32_bf16 v[84:87], v[170:173], v[202:205], v[84:87]
	v_mfma_f32_16x16x32_bf16 v[80:83], v[178:181], v[202:205], v[80:83]
	v_mfma_f32_16x16x32_bf16 v[68:71], v[170:173], v[210:213], v[68:71]
	v_mfma_f32_16x16x32_bf16 v[64:67], v[178:181], v[210:213], v[64:67]
	v_mfma_f32_16x16x32_bf16 v[116:119], v[174:177], v[190:193], v[116:119]
	v_mfma_f32_16x16x32_bf16 v[112:115], v[182:185], v[190:193], v[112:115]
	v_mfma_f32_16x16x32_bf16 v[100:103], v[174:177], v[198:201], v[100:103]
	v_mfma_f32_16x16x32_bf16 v[96:99], v[182:185], v[198:201], v[96:99]
	v_mfma_f32_16x16x32_bf16 v[84:87], v[174:177], v[206:209], v[84:87]
	v_mfma_f32_16x16x32_bf16 v[80:83], v[182:185], v[206:209], v[80:83]
	v_mfma_f32_16x16x32_bf16 v[68:71], v[174:177], v[214:217], v[68:71]
	v_mfma_f32_16x16x32_bf16 v[64:67], v[182:185], v[214:217], v[64:67]
	s_setprio 0
	s_barrier
	s_add_i32 s50, s70, s33
	s_mov_b32 m0, s50
	ds_read_b128 v[186:189], v155 offset:49152
	ds_read_b128 v[190:193], v155 offset:50176
	ds_read_b128 v[194:197], v155 offset:51200
	ds_read_b128 v[198:201], v155 offset:52224
	ds_read_b128 v[202:205], v155 offset:53248
	ds_read_b128 v[206:209], v155 offset:54272
	ds_read_b128 v[210:213], v155 offset:55296
	ds_read_b128 v[214:217], v155 offset:56320
	global_load_lds_dwordx4 v130, s[98:99]
	s_add_i32 m0, s50, 0x2000
	s_add_u32 s48, s48, 0x100080
	s_addc_u32 s49, s49, 0
	s_add_i32 s50, s71, s33
	global_load_lds_dwordx4 v134, s[98:99]
	s_mov_b32 m0, s50
	s_nop 0
	global_load_lds_dwordx4 v130, s[48:49]
	s_add_i32 m0, s50, 0x2000
	s_nop 0
	global_load_lds_dwordx4 v134, s[48:49]
	s_mov_b32 m0, s56
	s_nop 0
	global_load_lds_dwordx4 v128, s[100:101]
	s_mov_b32 m0, s57
	s_nop 0
	global_load_lds_dwordx4 v132, s[100:101]
	s_waitcnt vmcnt(8)
	s_waitcnt lgkmcnt(0)
	s_barrier
	s_setprio 1
	s_waitcnt lgkmcnt(0)
	v_mfma_f32_16x16x32_bf16 v[60:63], v[144:147], v[186:189], v[60:63]
	v_mfma_f32_16x16x32_bf16 v[56:59], v[162:165], v[186:189], v[56:59]
	v_mfma_f32_16x16x32_bf16 v[44:47], v[144:147], v[194:197], v[44:47]
	v_mfma_f32_16x16x32_bf16 v[40:43], v[162:165], v[194:197], v[40:43]
	v_mfma_f32_16x16x32_bf16 v[28:31], v[144:147], v[202:205], v[28:31]
	v_mfma_f32_16x16x32_bf16 v[24:27], v[162:165], v[202:205], v[24:27]
	v_mfma_f32_16x16x32_bf16 v[12:15], v[144:147], v[210:213], v[12:15]
	v_mfma_f32_16x16x32_bf16 v[8:11], v[162:165], v[210:213], v[8:11]
	v_mfma_f32_16x16x32_bf16 v[60:63], v[158:161], v[190:193], v[60:63]
	v_mfma_f32_16x16x32_bf16 v[56:59], v[166:169], v[190:193], v[56:59]
	v_mfma_f32_16x16x32_bf16 v[44:47], v[158:161], v[198:201], v[44:47]
	v_mfma_f32_16x16x32_bf16 v[40:43], v[166:169], v[198:201], v[40:43]
	v_mfma_f32_16x16x32_bf16 v[28:31], v[158:161], v[206:209], v[28:31]
	v_mfma_f32_16x16x32_bf16 v[24:27], v[166:169], v[206:209], v[24:27]
	v_mfma_f32_16x16x32_bf16 v[12:15], v[158:161], v[214:217], v[12:15]
	v_mfma_f32_16x16x32_bf16 v[8:11], v[166:169], v[214:217], v[8:11]
	s_setprio 0
	s_setprio 1
	v_mfma_f32_16x16x32_bf16 v[52:55], v[170:173], v[186:189], v[52:55]
	v_mfma_f32_16x16x32_bf16 v[48:51], v[178:181], v[186:189], v[48:51]
	v_mfma_f32_16x16x32_bf16 v[36:39], v[170:173], v[194:197], v[36:39]
	v_mfma_f32_16x16x32_bf16 v[32:35], v[178:181], v[194:197], v[32:35]
	v_mfma_f32_16x16x32_bf16 v[20:23], v[170:173], v[202:205], v[20:23]
	v_mfma_f32_16x16x32_bf16 v[16:19], v[178:181], v[202:205], v[16:19]
	v_mfma_f32_16x16x32_bf16 v[4:7], v[170:173], v[210:213], v[4:7]
	v_mfma_f32_16x16x32_bf16 v[0:3], v[178:181], v[210:213], v[0:3]
	v_mfma_f32_16x16x32_bf16 v[52:55], v[174:177], v[190:193], v[52:55]
	v_mfma_f32_16x16x32_bf16 v[48:51], v[182:185], v[190:193], v[48:51]
	v_mfma_f32_16x16x32_bf16 v[36:39], v[174:177], v[198:201], v[36:39]
	v_mfma_f32_16x16x32_bf16 v[32:35], v[182:185], v[198:201], v[32:35]
	v_mfma_f32_16x16x32_bf16 v[20:23], v[174:177], v[206:209], v[20:23]
	v_mfma_f32_16x16x32_bf16 v[16:19], v[182:185], v[206:209], v[16:19]
	v_mfma_f32_16x16x32_bf16 v[4:7], v[174:177], v[214:217], v[4:7]
	v_mfma_f32_16x16x32_bf16 v[0:3], v[182:185], v[214:217], v[0:3]
	s_setprio 0
	s_barrier
	s_add_i32 s69, s69, 2
	s_add_u32 s46, s46, 0x100
	s_addc_u32 s47, s47, 0
	s_add_u32 s67, s67, 0x100
	s_addc_u32 s68, s68, 0
	s_cmp_gt_u32 s69, 61
	s_cbranch_scc0 .LBB0_2770
	s_and_b64 vcc, exec, s[18:19]
	s_cbranch_vccz .LBB0_2773
	s_barrier

; #define PG8_STAGE(bufoff, gbase, voff) do { _Pragma("unroll") for (int _i = 0; _i < 2; ++_i) \
;         __builtin_amdgcn_global_load_lds((const unsigned*)((const char*)(gbase) + (voff)[_i]), (PG8_LAS unsigned*)(lds + (bufoff) + ldsw + _i * 8192), 16, 0, 0); } while (0)
; #define PG8_LDA(dst, b, h) do { _Pragma("unroll") for (int m = 0; m < 4; ++m) _Pragma("unroll") for (int k = 0; k < 2; ++k) dst[m][k] = *(const PG8_LAS bf16x8*)(lds + PG8_SA(b, h) + aoff + m * 2048 + k * 1024); } while (0)
; #define PG8_LDB(dst, b, h) do { _Pragma("unroll") for (int n = 0; n < 2; ++n) _Pragma("unroll") for (int k = 0; k < 2; ++k) dst[n][k] = *(const PG8_LAS bf16x8*)(lds + PG8_SB(b, h) + boff + n * 2048 + k * 1024); } while (0)
; #define PG8_MMA(ai, bj, At, Bt) do { __builtin_amdgcn_s_setprio(1); _Pragma("unroll") for (int m = 0; m < 4; ++m) _Pragma("unroll") for (int n = 0; n < 2; ++n) _Pragma("unroll") for (int k = 0; k < 2; ++k) \
;         acc[ai][bj][m][n] = __builtin_amdgcn_mfma_f32_16x16x32_bf16(Bt[n][k], At[m][k], acc[ai][bj][m][n], 0, 0, 0); __builtin_amdgcn_s_setprio(0); } while (0)
; #define PG8_WAIT_V(n) asm volatile("s_waitcnt vmcnt(" #n ")" ::: "memory")
; #define PG8_WAIT_L(n) asm volatile("s_waitcnt lgkmcnt(" #n ")" ::: "memory")
; #define PG8_BAR __builtin_amdgcn_s_barrier()
; #define PG8_SCHED __builtin_amdgcn_sched_barrier(0)
; template <class Epi, class Sched, bool ALIGN_EPI = false, bool SP2 = false>
; __device__ __forceinline__ void gemm_phase(PG8_LAS unsigned char* lds, const Gemm g, const Sched& S, const Epi& E) {
;     ...
;             PG8_LDB(B0, 0, 0); PG8_LDB(B1, 0, 1); PG8_SCHED; PG8_LDA(At, 0, 0); PG8_STAGE(PG8_SA(1, 1), a1 + hstepA, voffA);
;             PG8_WAIT_V(8); PG8_WAIT_L(0); PG8_BAR; PG8_MMA(0, 0, At, B0); PG8_MMA(0, 1, At, B1); PG8_BAR; PG8_SCHED;
;             PG8_LDA(At, 0, 1); PG8_STAGE(PG8_SB(0, 0), b2, voffB); PG8_STAGE(PG8_SB(0, 1), b2 + hstep, voffB); PG8_STAGE(PG8_SA(0, 0), a2, voffA);
;             PG8_WAIT_V(8); PG8_WAIT_L(0); PG8_BAR; PG8_MMA(1, 0, At, B0); PG8_MMA(1, 1, At, B1); PG8_BAR; PG8_SCHED;
.LBB0_2882:
	ds_read_b128 v[128:131], v236
	ds_read_b128 v[132:135], v236 offset:1024
	ds_read_b128 v[136:139], v236 offset:2048
	ds_read_b128 v[140:143], v236 offset:3072
	ds_read_b128 v[144:147], v237
	ds_read_b128 v[148:151], v237 offset:1024
	ds_read_b128 v[152:155], v237 offset:2048
	ds_read_b128 v[156:159], v237 offset:3072
	s_add_u32 s10, s8, 0x100
	s_addc_u32 s11, s9, 0
	s_cmp_eq_u32 s88, 60
	s_cselect_b32 s61, s7, s11
	s_cselect_b32 s60, s51, s10
	s_cselect_b32 s59, s49, s87
	s_cselect_b32 s58, s85, s86
	v_lshl_add_u64 v[164:165], s[8:9], 0, v[178:179]
	s_add_i32 m0, s57, 0xc000
	ds_read_b128 v[160:163], v238
	ds_read_b128 v[186:189], v238 offset:1024
	ds_read_b128 v[190:193], v238 offset:2048
	ds_read_b128 v[194:197], v238 offset:3072
	ds_read_b128 v[198:201], v238 offset:4096
	ds_read_b128 v[202:205], v238 offset:5120
	ds_read_b128 v[206:209], v238 offset:6144
	ds_read_b128 v[210:213], v238 offset:7168
	global_load_lds_dwordx4 v[164:165], off
	v_lshl_add_u64 v[164:165], s[8:9], 0, v[180:181]
	s_add_i32 m0, s57, 0xe000
	s_nop 0
	global_load_lds_dwordx4 v[164:165], off
	s_waitcnt vmcnt(8)
	s_waitcnt lgkmcnt(0)
	s_barrier
	s_setprio 1
	s_waitcnt lgkmcnt(0)
	v_mfma_f32_16x16x32_bf16 v[124:127], v[128:131], v[160:163], v[124:127]
	v_mfma_f32_16x16x32_bf16 v[120:123], v[136:139], v[160:163], v[120:123]
	v_mfma_f32_16x16x32_bf16 v[108:111], v[128:131], v[190:193], v[108:111]
	v_mfma_f32_16x16x32_bf16 v[104:107], v[136:139], v[190:193], v[104:107]
	v_mfma_f32_16x16x32_bf16 v[92:95], v[128:131], v[198:201], v[92:95]
	v_mfma_f32_16x16x32_bf16 v[88:91], v[136:139], v[198:201], v[88:91]
	v_mfma_f32_16x16x32_bf16 v[76:79], v[128:131], v[206:209], v[76:79]
	v_mfma_f32_16x16x32_bf16 v[72:75], v[136:139], v[206:209], v[72:75]
	v_mfma_f32_16x16x32_bf16 v[124:127], v[132:135], v[186:189], v[124:127]
	v_mfma_f32_16x16x32_bf16 v[120:123], v[140:143], v[186:189], v[120:123]
	v_mfma_f32_16x16x32_bf16 v[108:111], v[132:135], v[194:197], v[108:111]
	v_mfma_f32_16x16x32_bf16 v[104:107], v[140:143], v[194:197], v[104:107]
	v_mfma_f32_16x16x32_bf16 v[92:95], v[132:135], v[202:205], v[92:95]
	v_mfma_f32_16x16x32_bf16 v[88:91], v[140:143], v[202:205], v[88:91]
	v_mfma_f32_16x16x32_bf16 v[76:79], v[132:135], v[210:213], v[76:79]
	v_mfma_f32_16x16x32_bf16 v[72:75], v[140:143], v[210:213], v[72:75]
	s_setprio 0
	s_setprio 1
	v_mfma_f32_16x16x32_bf16 v[116:119], v[144:147], v[160:163], v[116:119]
	v_mfma_f32_16x16x32_bf16 v[112:115], v[152:155], v[160:163], v[112:115]
	v_mfma_f32_16x16x32_bf16 v[100:103], v[144:147], v[190:193], v[100:103]
	v_mfma_f32_16x16x32_bf16 v[96:99], v[152:155], v[190:193], v[96:99]
	v_mfma_f32_16x16x32_bf16 v[84:87], v[144:147], v[198:201], v[84:87]
	v_mfma_f32_16x16x32_bf16 v[80:83], v[152:155], v[198:201], v[80:83]
	v_mfma_f32_16x16x32_bf16 v[68:71], v[144:147], v[206:209], v[68:71]
	v_mfma_f32_16x16x32_bf16 v[64:67], v[152:155], v[206:209], v[64:67]
	v_mfma_f32_16x16x32_bf16 v[116:119], v[148:151], v[186:189], v[116:119]
	v_mfma_f32_16x16x32_bf16 v[112:115], v[156:159], v[186:189], v[112:115]
	v_mfma_f32_16x16x32_bf16 v[100:103], v[148:151], v[194:197], v[100:103]
	v_mfma_f32_16x16x32_bf16 v[96:99], v[156:159], v[194:197], v[96:99]
	v_mfma_f32_16x16x32_bf16 v[84:87], v[148:151], v[202:205], v[84:87]
	v_mfma_f32_16x16x32_bf16 v[80:83], v[156:159], v[202:205], v[80:83]
	v_mfma_f32_16x16x32_bf16 v[68:71], v[148:151], v[210:213], v[68:71]
	v_mfma_f32_16x16x32_bf16 v[64:67], v[156:159], v[210:213], v[64:67]
	s_setprio 0
	s_barrier
	s_add_u32 s98, s58, s16
	s_addc_u32 s99, s59, s17
	s_add_u32 s100, s60, s16
	s_addc_u32 s101, s61, s17
	s_add_i32 s8, s72, s63
	s_mov_b32 m0, s8
	ds_read_b128 v[160:163], v238 offset:16384
	ds_read_b128 v[186:189], v238 offset:17408
	ds_read_b128 v[190:193], v238 offset:18432
	ds_read_b128 v[194:197], v238 offset:19456
	ds_read_b128 v[198:201], v238 offset:20480
	ds_read_b128 v[202:205], v238 offset:21504
	ds_read_b128 v[206:209], v238 offset:22528
	ds_read_b128 v[210:213], v238 offset:23552
	global_load_lds_dwordx4 v168, s[58:59]
	s_add_i32 m0, s8, 0x2000
	s_add_u32 s8, s58, 0x100000
	s_addc_u32 s9, s59, 0
	s_add_i32 s89, s73, s63
	global_load_lds_dwordx4 v172, s[58:59]
	s_mov_b32 m0, s89
	s_nop 0
	global_load_lds_dwordx4 v168, s[8:9]
	s_add_i32 m0, s89, 0x2000
	s_nop 0
	global_load_lds_dwordx4 v172, s[8:9]
	s_mov_b32 m0, s57
	s_nop 0
	global_load_lds_dwordx4 v166, s[60:61]
	s_mov_b32 m0, s64
	s_nop 0
	global_load_lds_dwordx4 v170, s[60:61]
	s_waitcnt vmcnt(8)
	s_waitcnt lgkmcnt(0)
	s_barrier
; #define PG8_STAGE(bufoff, gbase, voff) do { _Pragma("unroll") for (int _i = 0; _i < 2; ++_i) \
;         __builtin_amdgcn_global_load_lds((const unsigned*)((const char*)(gbase) + (voff)[_i]), (PG8_LAS unsigned*)(lds + (bufoff) + ldsw + _i * 8192), 16, 0, 0); } while (0)
; #define PG8_LDA(dst, b, h) do { _Pragma("unroll") for (int m = 0; m < 4; ++m) _Pragma("unroll") for (int k = 0; k < 2; ++k) dst[m][k] = *(const PG8_LAS bf16x8*)(lds + PG8_SA(b, h) + aoff + m * 2048 + k * 1024); } while (0)
; #define PG8_LDB(dst, b, h) do { _Pragma("unroll") for (int n = 0; n < 2; ++n) _Pragma("unroll") for (int k = 0; k < 2; ++k) dst[n][k] = *(const PG8_LAS bf16x8*)(lds + PG8_SB(b, h) + boff + n * 2048 + k * 1024); } while (0)
; #define PG8_MMA(ai, bj, At, Bt) do { __builtin_amdgcn_s_setprio(1); _Pragma("unroll") for (int m = 0; m < 4; ++m) _Pragma("unroll") for (int n = 0; n < 2; ++n) _Pragma("unroll") for (int k = 0; k < 2; ++k) \
;         acc[ai][bj][m][n] = __builtin_amdgcn_mfma_f32_16x16x32_bf16(Bt[n][k], At[m][k], acc[ai][bj][m][n], 0, 0, 0); __builtin_amdgcn_s_setprio(0); } while (0)
; #define PG8_WAIT_V(n) asm volatile("s_waitcnt vmcnt(" #n ")" ::: "memory")
; #define PG8_WAIT_L(n) asm volatile("s_waitcnt lgkmcnt(" #n ")" ::: "memory")
; #define PG8_BAR __builtin_amdgcn_s_barrier()
; #define PG8_SCHED __builtin_amdgcn_sched_barrier(0)
; template <class Epi, class Sched, bool ALIGN_EPI = false, bool SP2 = false>
; __device__ __forceinline__ void gemm_phase(PG8_LAS unsigned char* lds, const Gemm g, const Sched& S, const Epi& E) {
;     ...
;             PG8_LDB(B0, 1, 0); PG8_LDB(B1, 1, 1); PG8_SCHED; PG8_LDA(At, 1, 0); PG8_STAGE(PG8_SA(0, 1), a2 + hstepA, voffA);
;             PG8_WAIT_V(8); PG8_WAIT_L(0); PG8_BAR; PG8_MMA(0, 0, At, B0); PG8_MMA(0, 1, At, B1); PG8_BAR; PG8_SCHED;
;             PG8_LDA(At, 1, 1); PG8_STAGE(PG8_SB(1, 0), b3, voffB); PG8_STAGE(PG8_SB(1, 1), b3 + hstep, voffB); PG8_STAGE(PG8_SA(1, 0), a3, voffA);
;             PG8_WAIT_V(8); PG8_WAIT_L(0); PG8_BAR; PG8_MMA(1, 0, At, B0); PG8_MMA(1, 1, At, B1); PG8_BAR; PG8_SCHED;
	s_setprio 1
	s_waitcnt lgkmcnt(0)
	v_mfma_f32_16x16x32_bf16 v[60:63], v[128:131], v[160:163], v[60:63]
	v_mfma_f32_16x16x32_bf16 v[56:59], v[136:139], v[160:163], v[56:59]
	v_mfma_f32_16x16x32_bf16 v[44:47], v[128:131], v[190:193], v[44:47]
	v_mfma_f32_16x16x32_bf16 v[40:43], v[136:139], v[190:193], v[40:43]
	v_mfma_f32_16x16x32_bf16 v[28:31], v[128:131], v[198:201], v[28:31]
	v_mfma_f32_16x16x32_bf16 v[24:27], v[136:139], v[198:201], v[24:27]
	v_mfma_f32_16x16x32_bf16 v[12:15], v[128:131], v[206:209], v[12:15]
	v_mfma_f32_16x16x32_bf16 v[8:11], v[136:139], v[206:209], v[8:11]
	v_mfma_f32_16x16x32_bf16 v[60:63], v[132:135], v[186:189], v[60:63]
	v_mfma_f32_16x16x32_bf16 v[56:59], v[140:143], v[186:189], v[56:59]
	v_mfma_f32_16x16x32_bf16 v[44:47], v[132:135], v[194:197], v[44:47]
	v_mfma_f32_16x16x32_bf16 v[40:43], v[140:143], v[194:197], v[40:43]
	v_mfma_f32_16x16x32_bf16 v[28:31], v[132:135], v[202:205], v[28:31]
	v_mfma_f32_16x16x32_bf16 v[24:27], v[140:143], v[202:205], v[24:27]
	v_mfma_f32_16x16x32_bf16 v[12:15], v[132:135], v[210:213], v[12:15]
	v_mfma_f32_16x16x32_bf16 v[8:11], v[140:143], v[210:213], v[8:11]
	s_setprio 0
	s_setprio 1
	v_mfma_f32_16x16x32_bf16 v[52:55], v[144:147], v[160:163], v[52:55]
	v_mfma_f32_16x16x32_bf16 v[48:51], v[152:155], v[160:163], v[48:51]
	v_mfma_f32_16x16x32_bf16 v[36:39], v[144:147], v[190:193], v[36:39]
	v_mfma_f32_16x16x32_bf16 v[32:35], v[152:155], v[190:193], v[32:35]
	v_mfma_f32_16x16x32_bf16 v[20:23], v[144:147], v[198:201], v[20:23]
	v_mfma_f32_16x16x32_bf16 v[16:19], v[152:155], v[198:201], v[16:19]
	v_mfma_f32_16x16x32_bf16 v[4:7], v[144:147], v[206:209], v[4:7]
	v_mfma_f32_16x16x32_bf16 v[0:3], v[152:155], v[206:209], v[0:3]
	v_mfma_f32_16x16x32_bf16 v[52:55], v[148:151], v[186:189], v[52:55]
	v_mfma_f32_16x16x32_bf16 v[48:51], v[156:159], v[186:189], v[48:51]
	v_mfma_f32_16x16x32_bf16 v[36:39], v[148:151], v[194:197], v[36:39]
	v_mfma_f32_16x16x32_bf16 v[32:35], v[156:159], v[194:197], v[32:35]
	v_mfma_f32_16x16x32_bf16 v[20:23], v[148:151], v[202:205], v[20:23]
	v_mfma_f32_16x16x32_bf16 v[16:19], v[156:159], v[202:205], v[16:19]
	v_mfma_f32_16x16x32_bf16 v[4:7], v[148:151], v[210:213], v[4:7]
	v_mfma_f32_16x16x32_bf16 v[0:3], v[156:159], v[210:213], v[0:3]
	s_setprio 0
	s_barrier
	s_add_i32 s89, 0, 0x18000
	s_add_i32 s90, 0, 0x1c000
	v_add_u32_e32 v140, s89, v234
	v_add_u32_e32 v156, s90, v234
	ds_read_b128 v[128:131], v140
	ds_read_b128 v[132:135], v140 offset:1024
	ds_read_b128 v[136:139], v140 offset:2048
	ds_read_b128 v[140:143], v140 offset:3072
	ds_read_b128 v[144:147], v156
	ds_read_b128 v[148:151], v156 offset:1024
	ds_read_b128 v[152:155], v156 offset:2048
	ds_read_b128 v[156:159], v156 offset:3072
	s_add_u32 s8, s60, 0x100000
	s_addc_u32 s9, s61, 0
	s_mov_b32 m0, s65
	ds_read_b128 v[160:163], v238 offset:32768
	ds_read_b128 v[186:189], v238 offset:33792
	ds_read_b128 v[190:193], v238 offset:34816
	ds_read_b128 v[194:197], v238 offset:35840
	ds_read_b128 v[198:201], v238 offset:36864
	ds_read_b128 v[202:205], v238 offset:37888
	ds_read_b128 v[206:209], v238 offset:38912
	ds_read_b128 v[210:213], v238 offset:39936
	global_load_lds_dwordx4 v166, s[8:9]
	s_mov_b32 m0, s66
	s_nop 0
	global_load_lds_dwordx4 v170, s[8:9]
	s_waitcnt vmcnt(8)
	s_waitcnt lgkmcnt(0)
	s_barrier
	s_setprio 1
	s_waitcnt lgkmcnt(0)
	v_mfma_f32_16x16x32_bf16 v[124:127], v[128:131], v[160:163], v[124:127]
	v_mfma_f32_16x16x32_bf16 v[120:123], v[136:139], v[160:163], v[120:123]
	v_mfma_f32_16x16x32_bf16 v[108:111], v[128:131], v[190:193], v[108:111]
	v_mfma_f32_16x16x32_bf16 v[104:107], v[136:139], v[190:193], v[104:107]
	v_mfma_f32_16x16x32_bf16 v[92:95], v[128:131], v[198:201], v[92:95]
	v_mfma_f32_16x16x32_bf16 v[88:91], v[136:139], v[198:201], v[88:91]
	v_mfma_f32_16x16x32_bf16 v[76:79], v[128:131], v[206:209], v[76:79]
	v_mfma_f32_16x16x32_bf16 v[72:75], v[136:139], v[206:209], v[72:75]
	v_mfma_f32_16x16x32_bf16 v[124:127], v[132:135], v[186:189], v[124:127]
	v_mfma_f32_16x16x32_bf16 v[120:123], v[140:143], v[186:189], v[120:123]
	v_mfma_f32_16x16x32_bf16 v[108:111], v[132:135], v[194:197], v[108:111]
	v_mfma_f32_16x16x32_bf16 v[104:107], v[140:143], v[194:197], v[104:107]
	v_mfma_f32_16x16x32_bf16 v[92:95], v[132:135], v[202:205], v[92:95]
	v_mfma_f32_16x16x32_bf16 v[88:91], v[140:143], v[202:205], v[88:91]
	v_mfma_f32_16x16x32_bf16 v[76:79], v[132:135], v[210:213], v[76:79]
	v_mfma_f32_16x16x32_bf16 v[72:75], v[140:143], v[210:213], v[72:75]
	s_setprio 0
	s_setprio 1
	v_mfma_f32_16x16x32_bf16 v[116:119], v[144:147], v[160:163], v[116:119]
	v_mfma_f32_16x16x32_bf16 v[112:115], v[152:155], v[160:163], v[112:115]
	v_mfma_f32_16x16x32_bf16 v[100:103], v[144:147], v[190:193], v[100:103]
	v_mfma_f32_16x16x32_bf16 v[96:99], v[152:155], v[190:193], v[96:99]
	v_mfma_f32_16x16x32_bf16 v[84:87], v[144:147], v[198:201], v[84:87]
	v_mfma_f32_16x16x32_bf16 v[80:83], v[152:155], v[198:201], v[80:83]
	v_mfma_f32_16x16x32_bf16 v[68:71], v[144:147], v[206:209], v[68:71]
	v_mfma_f32_16x16x32_bf16 v[64:67], v[152:155], v[206:209], v[64:67]
	v_mfma_f32_16x16x32_bf16 v[116:119], v[148:151], v[186:189], v[116:119]
	v_mfma_f32_16x16x32_bf16 v[112:115], v[156:159], v[186:189], v[112:115]
	v_mfma_f32_16x16x32_bf16 v[100:103], v[148:151], v[194:197], v[100:103]
	v_mfma_f32_16x16x32_bf16 v[96:99], v[156:159], v[194:197], v[96:99]
	v_mfma_f32_16x16x32_bf16 v[84:87], v[148:151], v[202:205], v[84:87]
	v_mfma_f32_16x16x32_bf16 v[80:83], v[156:159], v[202:205], v[80:83]
	v_mfma_f32_16x16x32_bf16 v[68:71], v[148:151], v[210:213], v[68:71]
	v_mfma_f32_16x16x32_bf16 v[64:67], v[156:159], v[210:213], v[64:67]
	s_setprio 0
	s_barrier
; #define PG8_STAGE(bufoff, gbase, voff) do { _Pragma("unroll") for (int _i = 0; _i < 2; ++_i) \
;         __builtin_amdgcn_global_load_lds((const unsigned*)((const char*)(gbase) + (voff)[_i]), (PG8_LAS unsigned*)(lds + (bufoff) + ldsw + _i * 8192), 16, 0, 0); } while (0)
; #define PG8_LDA(dst, b, h) do { _Pragma("unroll") for (int m = 0; m < 4; ++m) _Pragma("unroll") for (int k = 0; k < 2; ++k) dst[m][k] = *(const PG8_LAS bf16x8*)(lds + PG8_SA(b, h) + aoff + m * 2048 + k * 1024); } while (0)
; #define PG8_MMA(ai, bj, At, Bt) do { __builtin_amdgcn_s_setprio(1); _Pragma("unroll") for (int m = 0; m < 4; ++m) _Pragma("unroll") for (int n = 0; n < 2; ++n) _Pragma("unroll") for (int k = 0; k < 2; ++k) \
;         acc[ai][bj][m][n] = __builtin_amdgcn_mfma_f32_16x16x32_bf16(Bt[n][k], At[m][k], acc[ai][bj][m][n], 0, 0, 0); __builtin_amdgcn_s_setprio(0); } while (0)
; #define PG8_WAIT_V(n) asm volatile("s_waitcnt vmcnt(" #n ")" ::: "memory")
; #define PG8_WAIT_L(n) asm volatile("s_waitcnt lgkmcnt(" #n ")" ::: "memory")
; #define PG8_BAR __builtin_amdgcn_s_barrier()
; #define PG8_SCHED __builtin_amdgcn_sched_barrier(0)
; template <class Epi, class Sched, bool ALIGN_EPI = false, bool SP2 = false>
; __device__ __forceinline__ void gemm_phase(PG8_LAS unsigned char* lds, const Gemm g, const Sched& S, const Epi& E) {
;     ...
;         for (int t = 0; t < nt; t += 2) {
;     ...
;             PG8_LDA(At, 1, 1); PG8_STAGE(PG8_SB(1, 0), b3, voffB); PG8_STAGE(PG8_SB(1, 1), b3 + hstep, voffB); PG8_STAGE(PG8_SA(1, 0), a3, voffA);
;             PG8_WAIT_V(8); PG8_WAIT_L(0); PG8_BAR; PG8_MMA(1, 0, At, B0); PG8_MMA(1, 1, At, B1); PG8_BAR; PG8_SCHED;
	s_add_i32 s8, s89, s63
	s_mov_b32 m0, s8
	ds_read_b128 v[160:163], v238 offset:49152
	ds_read_b128 v[186:189], v238 offset:50176
	ds_read_b128 v[190:193], v238 offset:51200
	ds_read_b128 v[194:197], v238 offset:52224
	ds_read_b128 v[198:201], v238 offset:53248
	ds_read_b128 v[202:205], v238 offset:54272
	ds_read_b128 v[206:209], v238 offset:55296
	ds_read_b128 v[210:213], v238 offset:56320
	global_load_lds_dwordx4 v168, s[98:99]
	s_add_i32 m0, s8, 0x2000
	s_add_u32 s8, s58, 0x100080
	s_addc_u32 s9, s59, 0
	s_add_i32 s58, s90, s63
	global_load_lds_dwordx4 v172, s[98:99]
	s_mov_b32 m0, s58
	s_nop 0
	global_load_lds_dwordx4 v168, s[8:9]
	s_add_i32 m0, s58, 0x2000
	s_nop 0
	global_load_lds_dwordx4 v172, s[8:9]
	s_mov_b32 m0, s70
	s_nop 0
	global_load_lds_dwordx4 v166, s[100:101]
	s_mov_b32 m0, s71
	s_nop 0
	global_load_lds_dwordx4 v170, s[100:101]
	s_waitcnt vmcnt(8)
	s_waitcnt lgkmcnt(0)
	s_barrier
	s_setprio 1
	s_waitcnt lgkmcnt(0)
	v_mfma_f32_16x16x32_bf16 v[60:63], v[128:131], v[160:163], v[60:63]
	v_mfma_f32_16x16x32_bf16 v[56:59], v[136:139], v[160:163], v[56:59]
	v_mfma_f32_16x16x32_bf16 v[44:47], v[128:131], v[190:193], v[44:47]
	v_mfma_f32_16x16x32_bf16 v[40:43], v[136:139], v[190:193], v[40:43]
	v_mfma_f32_16x16x32_bf16 v[28:31], v[128:131], v[198:201], v[28:31]
	v_mfma_f32_16x16x32_bf16 v[24:27], v[136:139], v[198:201], v[24:27]
	v_mfma_f32_16x16x32_bf16 v[12:15], v[128:131], v[206:209], v[12:15]
	v_mfma_f32_16x16x32_bf16 v[8:11], v[136:139], v[206:209], v[8:11]
	v_mfma_f32_16x16x32_bf16 v[60:63], v[132:135], v[186:189], v[60:63]
	v_mfma_f32_16x16x32_bf16 v[56:59], v[140:143], v[186:189], v[56:59]
	v_mfma_f32_16x16x32_bf16 v[44:47], v[132:135], v[194:197], v[44:47]
	v_mfma_f32_16x16x32_bf16 v[40:43], v[140:143], v[194:197], v[40:43]
	v_mfma_f32_16x16x32_bf16 v[28:31], v[132:135], v[202:205], v[28:31]
	v_mfma_f32_16x16x32_bf16 v[24:27], v[140:143], v[202:205], v[24:27]
	v_mfma_f32_16x16x32_bf16 v[12:15], v[132:135], v[210:213], v[12:15]
	v_mfma_f32_16x16x32_bf16 v[8:11], v[140:143], v[210:213], v[8:11]
	s_setprio 0
	s_setprio 1
	v_mfma_f32_16x16x32_bf16 v[52:55], v[144:147], v[160:163], v[52:55]
	v_mfma_f32_16x16x32_bf16 v[48:51], v[152:155], v[160:163], v[48:51]
	v_mfma_f32_16x16x32_bf16 v[36:39], v[144:147], v[190:193], v[36:39]
	v_mfma_f32_16x16x32_bf16 v[32:35], v[152:155], v[190:193], v[32:35]
	v_mfma_f32_16x16x32_bf16 v[20:23], v[144:147], v[198:201], v[20:23]
	v_mfma_f32_16x16x32_bf16 v[16:19], v[152:155], v[198:201], v[16:19]
	v_mfma_f32_16x16x32_bf16 v[4:7], v[144:147], v[206:209], v[4:7]
	v_mfma_f32_16x16x32_bf16 v[0:3], v[152:155], v[206:209], v[0:3]
	v_mfma_f32_16x16x32_bf16 v[52:55], v[148:151], v[186:189], v[52:55]
	v_mfma_f32_16x16x32_bf16 v[48:51], v[156:159], v[186:189], v[48:51]
	v_mfma_f32_16x16x32_bf16 v[36:39], v[148:151], v[194:197], v[36:39]
	v_mfma_f32_16x16x32_bf16 v[32:35], v[156:159], v[194:197], v[32:35]
	v_mfma_f32_16x16x32_bf16 v[20:23], v[148:151], v[202:205], v[20:23]
	v_mfma_f32_16x16x32_bf16 v[16:19], v[156:159], v[202:205], v[16:19]
	v_mfma_f32_16x16x32_bf16 v[4:7], v[148:151], v[210:213], v[4:7]
	v_mfma_f32_16x16x32_bf16 v[0:3], v[156:159], v[210:213], v[0:3]
	s_setprio 0
	s_barrier
	s_add_i32 s88, s88, 2
	s_add_u32 s86, s86, 0x100
	s_addc_u32 s87, s87, 0
	s_cmp_gt_u32 s88, 61
	s_mov_b64 s[8:9], s[10:11]
	s_cbranch_scc0 .LBB0_2882
	s_and_b64 vcc, exec, s[18:19]
	s_cbranch_vccz .LBB0_2885
	s_barrier

; #define PG8_STAGE(bufoff, gbase, voff) do { _Pragma("unroll") for (int _i = 0; _i < 2; ++_i) \
;         __builtin_amdgcn_global_load_lds((const unsigned*)((const char*)(gbase) + (voff)[_i]), (PG8_LAS unsigned*)(lds + (bufoff) + ldsw + _i * 8192), 16, 0, 0); } while (0)
; #define PG8_LDA(dst, b, h) do { _Pragma("unroll") for (int m = 0; m < 4; ++m) _Pragma("unroll") for (int k = 0; k < 2; ++k) dst[m][k] = *(const PG8_LAS bf16x8*)(lds + PG8_SA(b, h) + aoff + m * 2048 + k * 1024); } while (0)
; #define PG8_LDB(dst, b, h) do { _Pragma("unroll") for (int n = 0; n < 2; ++n) _Pragma("unroll") for (int k = 0; k < 2; ++k) dst[n][k] = *(const PG8_LAS bf16x8*)(lds + PG8_SB(b, h) + boff + n * 2048 + k * 1024); } while (0)
; #define PG8_MMA(ai, bj, At, Bt) do { __builtin_amdgcn_s_setprio(1); _Pragma("unroll") for (int m = 0; m < 4; ++m) _Pragma("unroll") for (int n = 0; n < 2; ++n) _Pragma("unroll") for (int k = 0; k < 2; ++k) \
;         acc[ai][bj][m][n] = __builtin_amdgcn_mfma_f32_16x16x32_bf16(Bt[n][k], At[m][k], acc[ai][bj][m][n], 0, 0, 0); __builtin_amdgcn_s_setprio(0); } while (0)
; #define PG8_WAIT_V(n) asm volatile("s_waitcnt vmcnt(" #n ")" ::: "memory")
; #define PG8_WAIT_L(n) asm volatile("s_waitcnt lgkmcnt(" #n ")" ::: "memory")
; #define PG8_BAR __builtin_amdgcn_s_barrier()
; #define PG8_SCHED __builtin_amdgcn_sched_barrier(0)
; template <class Epi, class Sched, bool ALIGN_EPI = false, bool SP2 = false>
; __device__ __forceinline__ void gemm_phase(PG8_LAS unsigned char* lds, const Gemm g, const Sched& S, const Epi& E) {
;     ...
;             PG8_LDB(B0, 0, 0); PG8_LDB(B1, 0, 1); PG8_SCHED; PG8_LDA(At, 0, 0); PG8_STAGE(PG8_SA(1, 1), a1 + hstepA, voffA);
;             PG8_WAIT_V(8); PG8_WAIT_L(0); PG8_BAR; PG8_MMA(0, 0, At, B0); PG8_MMA(0, 1, At, B1); PG8_BAR; PG8_SCHED;
;             PG8_LDA(At, 0, 1); PG8_STAGE(PG8_SB(0, 0), b2, voffB); PG8_STAGE(PG8_SB(0, 1), b2 + hstep, voffB); PG8_STAGE(PG8_SA(0, 0), a2, voffA);
;             PG8_WAIT_V(8); PG8_WAIT_L(0); PG8_BAR; PG8_MMA(1, 0, At, B0); PG8_MMA(1, 1, At, B1); PG8_BAR; PG8_SCHED;
.LBB0_3087:
	ds_read_b128 v[144:147], v153
	ds_read_b128 v[158:161], v153 offset:1024
	ds_read_b128 v[162:165], v153 offset:2048
	ds_read_b128 v[166:169], v153 offset:3072
	ds_read_b128 v[170:173], v154
	ds_read_b128 v[174:177], v154 offset:1024
	ds_read_b128 v[178:181], v154 offset:2048
	ds_read_b128 v[182:185], v154 offset:3072
	s_add_u32 s36, s34, 0x4000
	s_addc_u32 s37, s35, 0
	s_cmpk_eq_i32 s65, 0xa8
	s_cselect_b32 s42, s6, s36
	s_cselect_b32 s43, s7, s37
	s_cselect_b32 s40, s30, s63
	s_cselect_b32 s41, s31, s64
	s_add_u32 s36, s42, 0x8000
	s_addc_u32 s37, s43, 0
	s_add_i32 m0, s44, 0xc000
	ds_read_b128 v[186:189], v155
	ds_read_b128 v[190:193], v155 offset:1024
	ds_read_b128 v[194:197], v155 offset:2048
	ds_read_b128 v[198:201], v155 offset:3072
	ds_read_b128 v[202:205], v155 offset:4096
	ds_read_b128 v[206:209], v155 offset:5120
	ds_read_b128 v[210:213], v155 offset:6144
	ds_read_b128 v[214:217], v155 offset:7168
	global_load_lds_dwordx4 v136, s[34:35]
	s_add_i32 m0, s44, 0xe000
	s_nop 0
	global_load_lds_dwordx4 v138, s[34:35]
	s_waitcnt vmcnt(8)
	s_waitcnt lgkmcnt(0)
	s_barrier
	s_setprio 1
	s_waitcnt lgkmcnt(0)
	v_mfma_f32_16x16x32_bf16 v[124:127], v[144:147], v[186:189], v[124:127]
	v_mfma_f32_16x16x32_bf16 v[120:123], v[162:165], v[186:189], v[120:123]
	v_mfma_f32_16x16x32_bf16 v[108:111], v[144:147], v[194:197], v[108:111]
	v_mfma_f32_16x16x32_bf16 v[104:107], v[162:165], v[194:197], v[104:107]
	v_mfma_f32_16x16x32_bf16 v[92:95], v[144:147], v[202:205], v[92:95]
	v_mfma_f32_16x16x32_bf16 v[88:91], v[162:165], v[202:205], v[88:91]
	v_mfma_f32_16x16x32_bf16 v[76:79], v[144:147], v[210:213], v[76:79]
	v_mfma_f32_16x16x32_bf16 v[72:75], v[162:165], v[210:213], v[72:75]
	v_mfma_f32_16x16x32_bf16 v[124:127], v[158:161], v[190:193], v[124:127]
	v_mfma_f32_16x16x32_bf16 v[120:123], v[166:169], v[190:193], v[120:123]
	v_mfma_f32_16x16x32_bf16 v[108:111], v[158:161], v[198:201], v[108:111]
	v_mfma_f32_16x16x32_bf16 v[104:107], v[166:169], v[198:201], v[104:107]
	v_mfma_f32_16x16x32_bf16 v[92:95], v[158:161], v[206:209], v[92:95]
	v_mfma_f32_16x16x32_bf16 v[88:91], v[166:169], v[206:209], v[88:91]
	v_mfma_f32_16x16x32_bf16 v[76:79], v[158:161], v[214:217], v[76:79]
	v_mfma_f32_16x16x32_bf16 v[72:75], v[166:169], v[214:217], v[72:75]
	s_setprio 0
	s_setprio 1
	v_mfma_f32_16x16x32_bf16 v[116:119], v[170:173], v[186:189], v[116:119]
	v_mfma_f32_16x16x32_bf16 v[112:115], v[178:181], v[186:189], v[112:115]
	v_mfma_f32_16x16x32_bf16 v[100:103], v[170:173], v[194:197], v[100:103]
	v_mfma_f32_16x16x32_bf16 v[96:99], v[178:181], v[194:197], v[96:99]
	v_mfma_f32_16x16x32_bf16 v[84:87], v[170:173], v[202:205], v[84:87]
	v_mfma_f32_16x16x32_bf16 v[80:83], v[178:181], v[202:205], v[80:83]
	v_mfma_f32_16x16x32_bf16 v[68:71], v[170:173], v[210:213], v[68:71]
	v_mfma_f32_16x16x32_bf16 v[64:67], v[178:181], v[210:213], v[64:67]
	v_mfma_f32_16x16x32_bf16 v[116:119], v[174:177], v[190:193], v[116:119]
	v_mfma_f32_16x16x32_bf16 v[112:115], v[182:185], v[190:193], v[112:115]
	v_mfma_f32_16x16x32_bf16 v[100:103], v[174:177], v[198:201], v[100:103]
	v_mfma_f32_16x16x32_bf16 v[96:99], v[182:185], v[198:201], v[96:99]
	v_mfma_f32_16x16x32_bf16 v[84:87], v[174:177], v[206:209], v[84:87]
	v_mfma_f32_16x16x32_bf16 v[80:83], v[182:185], v[206:209], v[80:83]
	v_mfma_f32_16x16x32_bf16 v[68:71], v[174:177], v[214:217], v[68:71]
	v_mfma_f32_16x16x32_bf16 v[64:67], v[182:185], v[214:217], v[64:67]
	s_setprio 0
	s_barrier
	s_add_u32 s98, s40, s16
	s_addc_u32 s99, s41, s17
	s_add_i32 s66, s53, s33
	s_mov_b32 m0, s66
	ds_read_b128 v[186:189], v155 offset:16384
	ds_read_b128 v[190:193], v155 offset:17408
	ds_read_b128 v[194:197], v155 offset:18432
	ds_read_b128 v[198:201], v155 offset:19456
	ds_read_b128 v[202:205], v155 offset:20480
	ds_read_b128 v[206:209], v155 offset:21504
	ds_read_b128 v[210:213], v155 offset:22528
	ds_read_b128 v[214:217], v155 offset:23552
	global_load_lds_dwordx4 v130, s[40:41]
	s_add_i32 m0, s66, 0x2000
	s_add_u32 s66, s40, 0x2b0000
	s_addc_u32 s67, s41, 0
	s_add_i32 s68, s54, s33
	global_load_lds_dwordx4 v134, s[40:41]
	s_mov_b32 m0, s68
	s_nop 0
	global_load_lds_dwordx4 v130, s[66:67]
	s_add_i32 m0, s68, 0x2000
	s_nop 0
	global_load_lds_dwordx4 v134, s[66:67]
	s_mov_b32 m0, s44
	s_nop 0
	global_load_lds_dwordx4 v128, s[42:43]
	s_mov_b32 m0, s45
	s_nop 0
	global_load_lds_dwordx4 v132, s[42:43]
	s_waitcnt vmcnt(8)
	s_waitcnt lgkmcnt(0)
	s_barrier
	s_setprio 1
	s_waitcnt lgkmcnt(0)
	v_mfma_f32_16x16x32_bf16 v[60:63], v[144:147], v[186:189], v[60:63]
	v_mfma_f32_16x16x32_bf16 v[56:59], v[162:165], v[186:189], v[56:59]
	v_mfma_f32_16x16x32_bf16 v[44:47], v[144:147], v[194:197], v[44:47]
	v_mfma_f32_16x16x32_bf16 v[40:43], v[162:165], v[194:197], v[40:43]
	v_mfma_f32_16x16x32_bf16 v[28:31], v[144:147], v[202:205], v[28:31]
	v_mfma_f32_16x16x32_bf16 v[24:27], v[162:165], v[202:205], v[24:27]
	v_mfma_f32_16x16x32_bf16 v[12:15], v[144:147], v[210:213], v[12:15]
	v_mfma_f32_16x16x32_bf16 v[8:11], v[162:165], v[210:213], v[8:11]
	v_mfma_f32_16x16x32_bf16 v[60:63], v[158:161], v[190:193], v[60:63]
	v_mfma_f32_16x16x32_bf16 v[56:59], v[166:169], v[190:193], v[56:59]
	v_mfma_f32_16x16x32_bf16 v[44:47], v[158:161], v[198:201], v[44:47]
	v_mfma_f32_16x16x32_bf16 v[40:43], v[166:169], v[198:201], v[40:43]
	v_mfma_f32_16x16x32_bf16 v[28:31], v[158:161], v[206:209], v[28:31]
	v_mfma_f32_16x16x32_bf16 v[24:27], v[166:169], v[206:209], v[24:27]
	v_mfma_f32_16x16x32_bf16 v[12:15], v[158:161], v[214:217], v[12:15]
	v_mfma_f32_16x16x32_bf16 v[8:11], v[166:169], v[214:217], v[8:11]
	s_setprio 0
	s_setprio 1
	v_mfma_f32_16x16x32_bf16 v[52:55], v[170:173], v[186:189], v[52:55]
	v_mfma_f32_16x16x32_bf16 v[48:51], v[178:181], v[186:189], v[48:51]
	v_mfma_f32_16x16x32_bf16 v[36:39], v[170:173], v[194:197], v[36:39]
	v_mfma_f32_16x16x32_bf16 v[32:35], v[178:181], v[194:197], v[32:35]
	v_mfma_f32_16x16x32_bf16 v[20:23], v[170:173], v[202:205], v[20:23]
	v_mfma_f32_16x16x32_bf16 v[16:19], v[178:181], v[202:205], v[16:19]
	v_mfma_f32_16x16x32_bf16 v[4:7], v[170:173], v[210:213], v[4:7]
	v_mfma_f32_16x16x32_bf16 v[0:3], v[178:181], v[210:213], v[0:3]
	v_mfma_f32_16x16x32_bf16 v[52:55], v[174:177], v[190:193], v[52:55]
	v_mfma_f32_16x16x32_bf16 v[48:51], v[182:185], v[190:193], v[48:51]
	v_mfma_f32_16x16x32_bf16 v[36:39], v[174:177], v[198:201], v[36:39]
	v_mfma_f32_16x16x32_bf16 v[32:35], v[182:185], v[198:201], v[32:35]
	v_mfma_f32_16x16x32_bf16 v[20:23], v[174:177], v[206:209], v[20:23]
	v_mfma_f32_16x16x32_bf16 v[16:19], v[182:185], v[206:209], v[16:19]
	v_mfma_f32_16x16x32_bf16 v[4:7], v[174:177], v[214:217], v[4:7]
	v_mfma_f32_16x16x32_bf16 v[0:3], v[182:185], v[214:217], v[0:3]
	s_setprio 0
	s_barrier
; #define PG8_STAGE(bufoff, gbase, voff) do { _Pragma("unroll") for (int _i = 0; _i < 2; ++_i) \
;         __builtin_amdgcn_global_load_lds((const unsigned*)((const char*)(gbase) + (voff)[_i]), (PG8_LAS unsigned*)(lds + (bufoff) + ldsw + _i * 8192), 16, 0, 0); } while (0)
; #define PG8_LDA(dst, b, h) do { _Pragma("unroll") for (int m = 0; m < 4; ++m) _Pragma("unroll") for (int k = 0; k < 2; ++k) dst[m][k] = *(const PG8_LAS bf16x8*)(lds + PG8_SA(b, h) + aoff + m * 2048 + k * 1024); } while (0)
; #define PG8_LDB(dst, b, h) do { _Pragma("unroll") for (int n = 0; n < 2; ++n) _Pragma("unroll") for (int k = 0; k < 2; ++k) dst[n][k] = *(const PG8_LAS bf16x8*)(lds + PG8_SB(b, h) + boff + n * 2048 + k * 1024); } while (0)
; #define PG8_MMA(ai, bj, At, Bt) do { __builtin_amdgcn_s_setprio(1); _Pragma("unroll") for (int m = 0; m < 4; ++m) _Pragma("unroll") for (int n = 0; n < 2; ++n) _Pragma("unroll") for (int k = 0; k < 2; ++k) \
;         acc[ai][bj][m][n] = __builtin_amdgcn_mfma_f32_16x16x32_bf16(Bt[n][k], At[m][k], acc[ai][bj][m][n], 0, 0, 0); __builtin_amdgcn_s_setprio(0); } while (0)
; #define PG8_WAIT_V(n) asm volatile("s_waitcnt vmcnt(" #n ")" ::: "memory")
; #define PG8_WAIT_L(n) asm volatile("s_waitcnt lgkmcnt(" #n ")" ::: "memory")
; #define PG8_BAR __builtin_amdgcn_s_barrier()
; #define PG8_SCHED __builtin_amdgcn_sched_barrier(0)
; template <class Epi, class Sched, bool ALIGN_EPI = false, bool SP2 = false>
; __device__ __forceinline__ void gemm_phase(PG8_LAS unsigned char* lds, const Gemm g, const Sched& S, const Epi& E) {
;     ...
;         for (int t = 0; t < nt; t += 2) {
;     ...
;             PG8_LDB(B0, 1, 0); PG8_LDB(B1, 1, 1); PG8_SCHED; PG8_LDA(At, 1, 0); PG8_STAGE(PG8_SA(0, 1), a2 + hstepA, voffA);
;             PG8_WAIT_V(8); PG8_WAIT_L(0); PG8_BAR; PG8_MMA(0, 0, At, B0); PG8_MMA(0, 1, At, B1); PG8_BAR; PG8_SCHED;
;             PG8_LDA(At, 1, 1); PG8_STAGE(PG8_SB(1, 0), b3, voffB); PG8_STAGE(PG8_SB(1, 1), b3 + hstep, voffB); PG8_STAGE(PG8_SA(1, 0), a3, voffA);
;             PG8_WAIT_V(8); PG8_WAIT_L(0); PG8_BAR; PG8_MMA(1, 0, At, B0); PG8_MMA(1, 1, At, B1); PG8_BAR; PG8_SCHED;
	s_add_i32 s66, 0, 0x18000
	v_add_u32_e32 v157, s66, v151
	s_add_i32 s67, 0, 0x1c000
	ds_read_b128 v[144:147], v157
	ds_read_b128 v[158:161], v157 offset:1024
	ds_read_b128 v[162:165], v157 offset:2048
	ds_read_b128 v[166:169], v157 offset:3072
	v_add_u32_e32 v157, s67, v151
	ds_read_b128 v[170:173], v157
	ds_read_b128 v[174:177], v157 offset:1024
	ds_read_b128 v[178:181], v157 offset:2048
	ds_read_b128 v[182:185], v157 offset:3072
	s_add_u32 s42, s42, 0x4000
	s_addc_u32 s43, s43, 0
	s_mov_b32 m0, s46
	ds_read_b128 v[186:189], v155 offset:32768
	ds_read_b128 v[190:193], v155 offset:33792
	ds_read_b128 v[194:197], v155 offset:34816
	ds_read_b128 v[198:201], v155 offset:35840
	ds_read_b128 v[202:205], v155 offset:36864
	ds_read_b128 v[206:209], v155 offset:37888
	ds_read_b128 v[210:213], v155 offset:38912
	ds_read_b128 v[214:217], v155 offset:39936
	global_load_lds_dwordx4 v128, s[42:43]
	s_mov_b32 m0, s47
	s_nop 0
	global_load_lds_dwordx4 v132, s[42:43]
	s_waitcnt vmcnt(8)
	s_waitcnt lgkmcnt(0)
	s_barrier
	s_setprio 1
	s_waitcnt lgkmcnt(0)
	v_mfma_f32_16x16x32_bf16 v[124:127], v[144:147], v[186:189], v[124:127]
	v_mfma_f32_16x16x32_bf16 v[120:123], v[162:165], v[186:189], v[120:123]
	v_mfma_f32_16x16x32_bf16 v[108:111], v[144:147], v[194:197], v[108:111]
	v_mfma_f32_16x16x32_bf16 v[104:107], v[162:165], v[194:197], v[104:107]
	v_mfma_f32_16x16x32_bf16 v[92:95], v[144:147], v[202:205], v[92:95]
	v_mfma_f32_16x16x32_bf16 v[88:91], v[162:165], v[202:205], v[88:91]
	v_mfma_f32_16x16x32_bf16 v[76:79], v[144:147], v[210:213], v[76:79]
	v_mfma_f32_16x16x32_bf16 v[72:75], v[162:165], v[210:213], v[72:75]
	v_mfma_f32_16x16x32_bf16 v[124:127], v[158:161], v[190:193], v[124:127]
	v_mfma_f32_16x16x32_bf16 v[120:123], v[166:169], v[190:193], v[120:123]
	v_mfma_f32_16x16x32_bf16 v[108:111], v[158:161], v[198:201], v[108:111]
	v_mfma_f32_16x16x32_bf16 v[104:107], v[166:169], v[198:201], v[104:107]
	v_mfma_f32_16x16x32_bf16 v[92:95], v[158:161], v[206:209], v[92:95]
	v_mfma_f32_16x16x32_bf16 v[88:91], v[166:169], v[206:209], v[88:91]
	v_mfma_f32_16x16x32_bf16 v[76:79], v[158:161], v[214:217], v[76:79]
	v_mfma_f32_16x16x32_bf16 v[72:75], v[166:169], v[214:217], v[72:75]
	s_setprio 0
	s_setprio 1
	v_mfma_f32_16x16x32_bf16 v[116:119], v[170:173], v[186:189], v[116:119]
	v_mfma_f32_16x16x32_bf16 v[112:115], v[178:181], v[186:189], v[112:115]
	v_mfma_f32_16x16x32_bf16 v[100:103], v[170:173], v[194:197], v[100:103]
	v_mfma_f32_16x16x32_bf16 v[96:99], v[178:181], v[194:197], v[96:99]
	v_mfma_f32_16x16x32_bf16 v[84:87], v[170:173], v[202:205], v[84:87]
	v_mfma_f32_16x16x32_bf16 v[80:83], v[178:181], v[202:205], v[80:83]
	v_mfma_f32_16x16x32_bf16 v[68:71], v[170:173], v[210:213], v[68:71]
	v_mfma_f32_16x16x32_bf16 v[64:67], v[178:181], v[210:213], v[64:67]
	v_mfma_f32_16x16x32_bf16 v[116:119], v[174:177], v[190:193], v[116:119]
	v_mfma_f32_16x16x32_bf16 v[112:115], v[182:185], v[190:193], v[112:115]
	v_mfma_f32_16x16x32_bf16 v[100:103], v[174:177], v[198:201], v[100:103]
	v_mfma_f32_16x16x32_bf16 v[96:99], v[182:185], v[198:201], v[96:99]
	v_mfma_f32_16x16x32_bf16 v[84:87], v[174:177], v[206:209], v[84:87]
	v_mfma_f32_16x16x32_bf16 v[80:83], v[182:185], v[206:209], v[80:83]
	v_mfma_f32_16x16x32_bf16 v[68:71], v[174:177], v[214:217], v[68:71]
	v_mfma_f32_16x16x32_bf16 v[64:67], v[182:185], v[214:217], v[64:67]
	s_setprio 0
	s_barrier
	s_add_i32 s42, s66, s33
	s_mov_b32 m0, s42
	ds_read_b128 v[186:189], v155 offset:49152
	ds_read_b128 v[190:193], v155 offset:50176
	ds_read_b128 v[194:197], v155 offset:51200
	ds_read_b128 v[198:201], v155 offset:52224
	ds_read_b128 v[202:205], v155 offset:53248
	ds_read_b128 v[206:209], v155 offset:54272
	ds_read_b128 v[210:213], v155 offset:55296
	ds_read_b128 v[214:217], v155 offset:56320
	global_load_lds_dwordx4 v130, s[98:99]
	s_add_i32 m0, s42, 0x2000
	s_add_u32 s40, s40, 0x2b0080
	s_addc_u32 s41, s41, 0
	s_add_i32 s42, s67, s33
	global_load_lds_dwordx4 v134, s[98:99]
	s_mov_b32 m0, s42
	s_nop 0
	global_load_lds_dwordx4 v130, s[40:41]
	s_add_i32 m0, s42, 0x2000
	s_nop 0
	global_load_lds_dwordx4 v134, s[40:41]
	s_mov_b32 m0, s49
	s_nop 0
	global_load_lds_dwordx4 v128, s[36:37]
	s_mov_b32 m0, s50
	s_nop 0
	global_load_lds_dwordx4 v132, s[36:37]
	s_waitcnt vmcnt(8)
	s_waitcnt lgkmcnt(0)
	s_barrier
	s_setprio 1
	s_waitcnt lgkmcnt(0)
	v_mfma_f32_16x16x32_bf16 v[60:63], v[144:147], v[186:189], v[60:63]
	v_mfma_f32_16x16x32_bf16 v[56:59], v[162:165], v[186:189], v[56:59]
	v_mfma_f32_16x16x32_bf16 v[44:47], v[144:147], v[194:197], v[44:47]
	v_mfma_f32_16x16x32_bf16 v[40:43], v[162:165], v[194:197], v[40:43]
	v_mfma_f32_16x16x32_bf16 v[28:31], v[144:147], v[202:205], v[28:31]
	v_mfma_f32_16x16x32_bf16 v[24:27], v[162:165], v[202:205], v[24:27]
	v_mfma_f32_16x16x32_bf16 v[12:15], v[144:147], v[210:213], v[12:15]
	v_mfma_f32_16x16x32_bf16 v[8:11], v[162:165], v[210:213], v[8:11]
	v_mfma_f32_16x16x32_bf16 v[60:63], v[158:161], v[190:193], v[60:63]
	v_mfma_f32_16x16x32_bf16 v[56:59], v[166:169], v[190:193], v[56:59]
	v_mfma_f32_16x16x32_bf16 v[44:47], v[158:161], v[198:201], v[44:47]
	v_mfma_f32_16x16x32_bf16 v[40:43], v[166:169], v[198:201], v[40:43]
	v_mfma_f32_16x16x32_bf16 v[28:31], v[158:161], v[206:209], v[28:31]
	v_mfma_f32_16x16x32_bf16 v[24:27], v[166:169], v[206:209], v[24:27]
	v_mfma_f32_16x16x32_bf16 v[12:15], v[158:161], v[214:217], v[12:15]
	v_mfma_f32_16x16x32_bf16 v[8:11], v[166:169], v[214:217], v[8:11]
	s_setprio 0
	s_setprio 1
	v_mfma_f32_16x16x32_bf16 v[52:55], v[170:173], v[186:189], v[52:55]
	v_mfma_f32_16x16x32_bf16 v[48:51], v[178:181], v[186:189], v[48:51]
	v_mfma_f32_16x16x32_bf16 v[36:39], v[170:173], v[194:197], v[36:39]
	v_mfma_f32_16x16x32_bf16 v[32:35], v[178:181], v[194:197], v[32:35]
	v_mfma_f32_16x16x32_bf16 v[20:23], v[170:173], v[202:205], v[20:23]
	v_mfma_f32_16x16x32_bf16 v[16:19], v[178:181], v[202:205], v[16:19]
	v_mfma_f32_16x16x32_bf16 v[4:7], v[170:173], v[210:213], v[4:7]
	v_mfma_f32_16x16x32_bf16 v[0:3], v[178:181], v[210:213], v[0:3]
	v_mfma_f32_16x16x32_bf16 v[52:55], v[174:177], v[190:193], v[52:55]
	v_mfma_f32_16x16x32_bf16 v[48:51], v[182:185], v[190:193], v[48:51]
	v_mfma_f32_16x16x32_bf16 v[36:39], v[174:177], v[198:201], v[36:39]
	v_mfma_f32_16x16x32_bf16 v[32:35], v[182:185], v[198:201], v[32:35]
	v_mfma_f32_16x16x32_bf16 v[20:23], v[174:177], v[206:209], v[20:23]
	v_mfma_f32_16x16x32_bf16 v[16:19], v[182:185], v[206:209], v[16:19]
	v_mfma_f32_16x16x32_bf16 v[4:7], v[174:177], v[214:217], v[4:7]
	v_mfma_f32_16x16x32_bf16 v[0:3], v[182:185], v[214:217], v[0:3]
	s_setprio 0
	s_barrier
	s_add_i32 s65, s65, 2
	s_add_u32 s63, s63, 0x100
	s_addc_u32 s64, s64, 0
	s_add_u32 s34, s34, 0x10000
	s_addc_u32 s35, s35, 0
	s_cmpk_gt_u32 s65, 0xa9
	s_cbranch_scc0 .LBB0_3087
	s_and_b64 vcc, exec, s[18:19]
	s_cbranch_vccz .LBB0_3090
	s_barrier

; #define PG8_STAGE(bufoff, gbase, voff) do { _Pragma("unroll") for (int _i = 0; _i < 2; ++_i) \
;         __builtin_amdgcn_global_load_lds((const unsigned*)((const char*)(gbase) + (voff)[_i]), (PG8_LAS unsigned*)(lds + (bufoff) + ldsw + _i * 8192), 16, 0, 0); } while (0)
; #define PG8_LDA(dst, b, h) do { _Pragma("unroll") for (int m = 0; m < 4; ++m) _Pragma("unroll") for (int k = 0; k < 2; ++k) dst[m][k] = *(const PG8_LAS bf16x8*)(lds + PG8_SA(b, h) + aoff + m * 2048 + k * 1024); } while (0)
; #define PG8_LDB(dst, b, h) do { _Pragma("unroll") for (int n = 0; n < 2; ++n) _Pragma("unroll") for (int k = 0; k < 2; ++k) dst[n][k] = *(const PG8_LAS bf16x8*)(lds + PG8_SB(b, h) + boff + n * 2048 + k * 1024); } while (0)
; #define PG8_MMA(ai, bj, At, Bt) do { __builtin_amdgcn_s_setprio(1); _Pragma("unroll") for (int m = 0; m < 4; ++m) _Pragma("unroll") for (int n = 0; n < 2; ++n) _Pragma("unroll") for (int k = 0; k < 2; ++k) \
;         acc[ai][bj][m][n] = __builtin_amdgcn_mfma_f32_16x16x32_bf16(Bt[n][k], At[m][k], acc[ai][bj][m][n], 0, 0, 0); __builtin_amdgcn_s_setprio(0); } while (0)
; #define PG8_WAIT_V(n) asm volatile("s_waitcnt vmcnt(" #n ")" ::: "memory")
; #define PG8_WAIT_L(n) asm volatile("s_waitcnt lgkmcnt(" #n ")" ::: "memory")
; #define PG8_BAR __builtin_amdgcn_s_barrier()
; #define PG8_SCHED __builtin_amdgcn_sched_barrier(0)
; template <class Epi, class Sched, bool ALIGN_EPI = false, bool SP2 = false>
; __device__ __forceinline__ void gemm_phase(PG8_LAS unsigned char* lds, const Gemm g, const Sched& S, const Epi& E) {
;     ...
;             PG8_LDB(B0, 0, 0); PG8_LDB(B1, 0, 1); PG8_SCHED; PG8_LDA(At, 0, 0); PG8_STAGE(PG8_SA(1, 1), a1 + hstepA, voffA);
;             PG8_WAIT_V(8); PG8_WAIT_L(0); PG8_BAR; PG8_MMA(0, 0, At, B0); PG8_MMA(0, 1, At, B1); PG8_BAR; PG8_SCHED;
;             PG8_LDA(At, 0, 1); PG8_STAGE(PG8_SB(0, 0), b2, voffB); PG8_STAGE(PG8_SB(0, 1), b2 + hstep, voffB); PG8_STAGE(PG8_SA(0, 0), a2, voffA);
;             PG8_WAIT_V(8); PG8_WAIT_L(0); PG8_BAR; PG8_MMA(1, 0, At, B0); PG8_MMA(1, 1, At, B1); PG8_BAR; PG8_SCHED;
.LBB0_3203:
	ds_read_b128 v[144:147], v155
	ds_read_b128 v[148:151], v155 offset:1024
	ds_read_b128 v[160:163], v155 offset:2048
	ds_read_b128 v[164:167], v155 offset:3072
	ds_read_b128 v[168:171], v156
	ds_read_b128 v[172:175], v156 offset:1024
	ds_read_b128 v[176:179], v156 offset:2048
	ds_read_b128 v[180:183], v156 offset:3072
	s_add_u32 s58, s56, 0xfff00080
	s_addc_u32 s59, s57, -1
	s_cmp_eq_u32 s74, 60
	s_cselect_b32 s61, s47, s59
	s_cselect_b32 s60, s53, s58
	s_cselect_b32 s59, s45, s73
	s_cselect_b32 s58, s71, s72
	s_add_i32 m0, s29, 0xc000
	ds_read_b128 v[184:187], v157
	ds_read_b128 v[188:191], v157 offset:1024
	ds_read_b128 v[192:195], v157 offset:2048
	ds_read_b128 v[196:199], v157 offset:3072
	ds_read_b128 v[200:203], v157 offset:4096
	ds_read_b128 v[204:207], v157 offset:5120
	ds_read_b128 v[208:211], v157 offset:6144
	ds_read_b128 v[212:215], v157 offset:7168
	global_load_lds_dwordx4 v136, s[56:57]
	s_add_i32 m0, s29, 0xe000
	s_nop 0
	global_load_lds_dwordx4 v138, s[56:57]
	s_waitcnt vmcnt(8)
	s_waitcnt lgkmcnt(0)
	s_barrier
	s_setprio 1
	s_waitcnt lgkmcnt(0)
	v_mfma_f32_16x16x32_bf16 v[124:127], v[144:147], v[184:187], v[124:127]
	v_mfma_f32_16x16x32_bf16 v[72:75], v[160:163], v[184:187], v[72:75]
	v_mfma_f32_16x16x32_bf16 v[116:119], v[144:147], v[192:195], v[116:119]
	v_mfma_f32_16x16x32_bf16 v[68:71], v[160:163], v[192:195], v[68:71]
	v_mfma_f32_16x16x32_bf16 v[108:111], v[144:147], v[200:203], v[108:111]
	v_mfma_f32_16x16x32_bf16 v[96:99], v[160:163], v[200:203], v[96:99]
	v_mfma_f32_16x16x32_bf16 v[92:95], v[144:147], v[208:211], v[92:95]
	v_mfma_f32_16x16x32_bf16 v[88:91], v[160:163], v[208:211], v[88:91]
	v_mfma_f32_16x16x32_bf16 v[124:127], v[148:151], v[188:191], v[124:127]
	v_mfma_f32_16x16x32_bf16 v[72:75], v[164:167], v[188:191], v[72:75]
	v_mfma_f32_16x16x32_bf16 v[116:119], v[148:151], v[196:199], v[116:119]
	v_mfma_f32_16x16x32_bf16 v[68:71], v[164:167], v[196:199], v[68:71]
	v_mfma_f32_16x16x32_bf16 v[108:111], v[148:151], v[204:207], v[108:111]
	v_mfma_f32_16x16x32_bf16 v[96:99], v[164:167], v[204:207], v[96:99]
	v_mfma_f32_16x16x32_bf16 v[92:95], v[148:151], v[212:215], v[92:95]
	v_mfma_f32_16x16x32_bf16 v[88:91], v[164:167], v[212:215], v[88:91]
	s_setprio 0
	s_setprio 1
	v_mfma_f32_16x16x32_bf16 v[120:123], v[168:171], v[184:187], v[120:123]
	v_mfma_f32_16x16x32_bf16 v[84:87], v[176:179], v[184:187], v[84:87]
	v_mfma_f32_16x16x32_bf16 v[112:115], v[168:171], v[192:195], v[112:115]
	v_mfma_f32_16x16x32_bf16 v[80:83], v[176:179], v[192:195], v[80:83]
	v_mfma_f32_16x16x32_bf16 v[104:107], v[168:171], v[200:203], v[104:107]
	v_mfma_f32_16x16x32_bf16 v[100:103], v[176:179], v[200:203], v[100:103]
	v_mfma_f32_16x16x32_bf16 v[76:79], v[168:171], v[208:211], v[76:79]
	v_mfma_f32_16x16x32_bf16 v[64:67], v[176:179], v[208:211], v[64:67]
	v_mfma_f32_16x16x32_bf16 v[120:123], v[172:175], v[188:191], v[120:123]
	v_mfma_f32_16x16x32_bf16 v[84:87], v[180:183], v[188:191], v[84:87]
	v_mfma_f32_16x16x32_bf16 v[112:115], v[172:175], v[196:199], v[112:115]
	v_mfma_f32_16x16x32_bf16 v[80:83], v[180:183], v[196:199], v[80:83]
	v_mfma_f32_16x16x32_bf16 v[104:107], v[172:175], v[204:207], v[104:107]
	v_mfma_f32_16x16x32_bf16 v[100:103], v[180:183], v[204:207], v[100:103]
	v_mfma_f32_16x16x32_bf16 v[76:79], v[172:175], v[212:215], v[76:79]
	v_mfma_f32_16x16x32_bf16 v[64:67], v[180:183], v[212:215], v[64:67]
	s_setprio 0
	s_barrier
	s_add_u32 s98, s58, s20
	s_addc_u32 s99, s59, s21
	s_add_u32 s100, s60, s20
	s_addc_u32 s101, s61, s21
	s_add_i32 s75, s68, s3
	s_mov_b32 m0, s75
	ds_read_b128 v[184:187], v157 offset:16384
	ds_read_b128 v[188:191], v157 offset:17408
	ds_read_b128 v[192:195], v157 offset:18432
	ds_read_b128 v[196:199], v157 offset:19456
	ds_read_b128 v[200:203], v157 offset:20480
	ds_read_b128 v[204:207], v157 offset:21504
	ds_read_b128 v[208:211], v157 offset:22528
	ds_read_b128 v[212:215], v157 offset:23552
	global_load_lds_dwordx4 v130, s[58:59]
	s_add_i32 m0, s75, 0x2000
	s_add_u32 s84, s58, 0x100000
	s_addc_u32 s85, s59, 0
	s_add_i32 s75, s69, s3
	global_load_lds_dwordx4 v134, s[58:59]
	s_mov_b32 m0, s75
	s_nop 0
	global_load_lds_dwordx4 v130, s[84:85]
	s_add_i32 m0, s75, 0x2000
	s_nop 0
	global_load_lds_dwordx4 v134, s[84:85]
	s_mov_b32 m0, s29
	s_nop 0
	global_load_lds_dwordx4 v128, s[60:61]
	s_mov_b32 m0, s33
	s_nop 0
	global_load_lds_dwordx4 v132, s[60:61]
	s_waitcnt vmcnt(8)
	s_waitcnt lgkmcnt(0)
	s_barrier
	s_setprio 1
	s_waitcnt lgkmcnt(0)
	v_mfma_f32_16x16x32_bf16 v[60:63], v[144:147], v[184:187], v[60:63]
	v_mfma_f32_16x16x32_bf16 v[56:59], v[160:163], v[184:187], v[56:59]
	v_mfma_f32_16x16x32_bf16 v[44:47], v[144:147], v[192:195], v[44:47]
	v_mfma_f32_16x16x32_bf16 v[40:43], v[160:163], v[192:195], v[40:43]
	v_mfma_f32_16x16x32_bf16 v[28:31], v[144:147], v[200:203], v[28:31]
	v_mfma_f32_16x16x32_bf16 v[24:27], v[160:163], v[200:203], v[24:27]
	v_mfma_f32_16x16x32_bf16 v[12:15], v[144:147], v[208:211], v[12:15]
	v_mfma_f32_16x16x32_bf16 v[8:11], v[160:163], v[208:211], v[8:11]
	v_mfma_f32_16x16x32_bf16 v[60:63], v[148:151], v[188:191], v[60:63]
	v_mfma_f32_16x16x32_bf16 v[56:59], v[164:167], v[188:191], v[56:59]
	v_mfma_f32_16x16x32_bf16 v[44:47], v[148:151], v[196:199], v[44:47]
	v_mfma_f32_16x16x32_bf16 v[40:43], v[164:167], v[196:199], v[40:43]
	v_mfma_f32_16x16x32_bf16 v[28:31], v[148:151], v[204:207], v[28:31]
	v_mfma_f32_16x16x32_bf16 v[24:27], v[164:167], v[204:207], v[24:27]
	v_mfma_f32_16x16x32_bf16 v[12:15], v[148:151], v[212:215], v[12:15]
	v_mfma_f32_16x16x32_bf16 v[8:11], v[164:167], v[212:215], v[8:11]
	s_setprio 0
	s_setprio 1
	v_mfma_f32_16x16x32_bf16 v[52:55], v[168:171], v[184:187], v[52:55]
	v_mfma_f32_16x16x32_bf16 v[48:51], v[176:179], v[184:187], v[48:51]
	v_mfma_f32_16x16x32_bf16 v[36:39], v[168:171], v[192:195], v[36:39]
	v_mfma_f32_16x16x32_bf16 v[32:35], v[176:179], v[192:195], v[32:35]
	v_mfma_f32_16x16x32_bf16 v[20:23], v[168:171], v[200:203], v[20:23]
	v_mfma_f32_16x16x32_bf16 v[16:19], v[176:179], v[200:203], v[16:19]
	v_mfma_f32_16x16x32_bf16 v[4:7], v[168:171], v[208:211], v[4:7]
	v_mfma_f32_16x16x32_bf16 v[0:3], v[176:179], v[208:211], v[0:3]
	v_mfma_f32_16x16x32_bf16 v[52:55], v[172:175], v[188:191], v[52:55]
	v_mfma_f32_16x16x32_bf16 v[48:51], v[180:183], v[188:191], v[48:51]
	v_mfma_f32_16x16x32_bf16 v[36:39], v[172:175], v[196:199], v[36:39]
	v_mfma_f32_16x16x32_bf16 v[32:35], v[180:183], v[196:199], v[32:35]
	v_mfma_f32_16x16x32_bf16 v[20:23], v[172:175], v[204:207], v[20:23]
	v_mfma_f32_16x16x32_bf16 v[16:19], v[180:183], v[204:207], v[16:19]
	v_mfma_f32_16x16x32_bf16 v[4:7], v[172:175], v[212:215], v[4:7]
	v_mfma_f32_16x16x32_bf16 v[0:3], v[180:183], v[212:215], v[0:3]
	s_setprio 0
	s_barrier
; #define PG8_STAGE(bufoff, gbase, voff) do { _Pragma("unroll") for (int _i = 0; _i < 2; ++_i) \
;         __builtin_amdgcn_global_load_lds((const unsigned*)((const char*)(gbase) + (voff)[_i]), (PG8_LAS unsigned*)(lds + (bufoff) + ldsw + _i * 8192), 16, 0, 0); } while (0)
; #define PG8_LDA(dst, b, h) do { _Pragma("unroll") for (int m = 0; m < 4; ++m) _Pragma("unroll") for (int k = 0; k < 2; ++k) dst[m][k] = *(const PG8_LAS bf16x8*)(lds + PG8_SA(b, h) + aoff + m * 2048 + k * 1024); } while (0)
; #define PG8_LDB(dst, b, h) do { _Pragma("unroll") for (int n = 0; n < 2; ++n) _Pragma("unroll") for (int k = 0; k < 2; ++k) dst[n][k] = *(const PG8_LAS bf16x8*)(lds + PG8_SB(b, h) + boff + n * 2048 + k * 1024); } while (0)
; #define PG8_MMA(ai, bj, At, Bt) do { __builtin_amdgcn_s_setprio(1); _Pragma("unroll") for (int m = 0; m < 4; ++m) _Pragma("unroll") for (int n = 0; n < 2; ++n) _Pragma("unroll") for (int k = 0; k < 2; ++k) \
;         acc[ai][bj][m][n] = __builtin_amdgcn_mfma_f32_16x16x32_bf16(Bt[n][k], At[m][k], acc[ai][bj][m][n], 0, 0, 0); __builtin_amdgcn_s_setprio(0); } while (0)
; #define PG8_WAIT_V(n) asm volatile("s_waitcnt vmcnt(" #n ")" ::: "memory")
; #define PG8_WAIT_L(n) asm volatile("s_waitcnt lgkmcnt(" #n ")" ::: "memory")
; #define PG8_BAR __builtin_amdgcn_s_barrier()
; #define PG8_SCHED __builtin_amdgcn_sched_barrier(0)
; template <class Epi, class Sched, bool ALIGN_EPI = false, bool SP2 = false>
; __device__ __forceinline__ void gemm_phase(PG8_LAS unsigned char* lds, const Gemm g, const Sched& S, const Epi& E) {
;     ...
;         for (int t = 0; t < nt; t += 2) {
;     ...
;             PG8_LDB(B0, 1, 0); PG8_LDB(B1, 1, 1); PG8_SCHED; PG8_LDA(At, 1, 0); PG8_STAGE(PG8_SA(0, 1), a2 + hstepA, voffA);
;             PG8_WAIT_V(8); PG8_WAIT_L(0); PG8_BAR; PG8_MMA(0, 0, At, B0); PG8_MMA(0, 1, At, B1); PG8_BAR; PG8_SCHED;
;             PG8_LDA(At, 1, 1); PG8_STAGE(PG8_SB(1, 0), b3, voffB); PG8_STAGE(PG8_SB(1, 1), b3 + hstep, voffB); PG8_STAGE(PG8_SA(1, 0), a3, voffA);
;             PG8_WAIT_V(8); PG8_WAIT_L(0); PG8_BAR; PG8_MMA(1, 0, At, B0); PG8_MMA(1, 1, At, B1); PG8_BAR; PG8_SCHED;
	s_add_i32 s75, 0, 0x18000
	s_add_i32 s84, 0, 0x1c000
	v_add_u32_e32 v164, s75, v153
	v_add_u32_e32 v180, s84, v153
	ds_read_b128 v[144:147], v164
	ds_read_b128 v[148:151], v164 offset:1024
	ds_read_b128 v[160:163], v164 offset:2048
	ds_read_b128 v[164:167], v164 offset:3072
	ds_read_b128 v[168:171], v180
	ds_read_b128 v[172:175], v180 offset:1024
	ds_read_b128 v[176:179], v180 offset:2048
	ds_read_b128 v[180:183], v180 offset:3072
	s_add_u32 s60, s60, 0x100000
	s_addc_u32 s61, s61, 0
	s_mov_b32 m0, s55
	ds_read_b128 v[184:187], v157 offset:32768
	ds_read_b128 v[188:191], v157 offset:33792
	ds_read_b128 v[192:195], v157 offset:34816
	ds_read_b128 v[196:199], v157 offset:35840
	ds_read_b128 v[200:203], v157 offset:36864
	ds_read_b128 v[204:207], v157 offset:37888
	ds_read_b128 v[208:211], v157 offset:38912
	ds_read_b128 v[212:215], v157 offset:39936
	global_load_lds_dwordx4 v128, s[60:61]
	s_mov_b32 m0, s62
	s_nop 0
	global_load_lds_dwordx4 v132, s[60:61]
	s_waitcnt vmcnt(8)
	s_waitcnt lgkmcnt(0)
	s_barrier
	s_setprio 1
	s_waitcnt lgkmcnt(0)
	v_mfma_f32_16x16x32_bf16 v[124:127], v[144:147], v[184:187], v[124:127]
	v_mfma_f32_16x16x32_bf16 v[72:75], v[160:163], v[184:187], v[72:75]
	v_mfma_f32_16x16x32_bf16 v[116:119], v[144:147], v[192:195], v[116:119]
	v_mfma_f32_16x16x32_bf16 v[68:71], v[160:163], v[192:195], v[68:71]
	v_mfma_f32_16x16x32_bf16 v[108:111], v[144:147], v[200:203], v[108:111]
	v_mfma_f32_16x16x32_bf16 v[96:99], v[160:163], v[200:203], v[96:99]
	v_mfma_f32_16x16x32_bf16 v[92:95], v[144:147], v[208:211], v[92:95]
	v_mfma_f32_16x16x32_bf16 v[88:91], v[160:163], v[208:211], v[88:91]
	v_mfma_f32_16x16x32_bf16 v[124:127], v[148:151], v[188:191], v[124:127]
	v_mfma_f32_16x16x32_bf16 v[72:75], v[164:167], v[188:191], v[72:75]
	v_mfma_f32_16x16x32_bf16 v[116:119], v[148:151], v[196:199], v[116:119]
	v_mfma_f32_16x16x32_bf16 v[68:71], v[164:167], v[196:199], v[68:71]
	v_mfma_f32_16x16x32_bf16 v[108:111], v[148:151], v[204:207], v[108:111]
	v_mfma_f32_16x16x32_bf16 v[96:99], v[164:167], v[204:207], v[96:99]
	v_mfma_f32_16x16x32_bf16 v[92:95], v[148:151], v[212:215], v[92:95]
	v_mfma_f32_16x16x32_bf16 v[88:91], v[164:167], v[212:215], v[88:91]
	s_setprio 0
	s_setprio 1
	v_mfma_f32_16x16x32_bf16 v[120:123], v[168:171], v[184:187], v[120:123]
	v_mfma_f32_16x16x32_bf16 v[84:87], v[176:179], v[184:187], v[84:87]
	v_mfma_f32_16x16x32_bf16 v[112:115], v[168:171], v[192:195], v[112:115]
	v_mfma_f32_16x16x32_bf16 v[80:83], v[176:179], v[192:195], v[80:83]
	v_mfma_f32_16x16x32_bf16 v[104:107], v[168:171], v[200:203], v[104:107]
	v_mfma_f32_16x16x32_bf16 v[100:103], v[176:179], v[200:203], v[100:103]
	v_mfma_f32_16x16x32_bf16 v[76:79], v[168:171], v[208:211], v[76:79]
	v_mfma_f32_16x16x32_bf16 v[64:67], v[176:179], v[208:211], v[64:67]
	v_mfma_f32_16x16x32_bf16 v[120:123], v[172:175], v[188:191], v[120:123]
	v_mfma_f32_16x16x32_bf16 v[84:87], v[180:183], v[188:191], v[84:87]
	v_mfma_f32_16x16x32_bf16 v[112:115], v[172:175], v[196:199], v[112:115]
	v_mfma_f32_16x16x32_bf16 v[80:83], v[180:183], v[196:199], v[80:83]
	v_mfma_f32_16x16x32_bf16 v[104:107], v[172:175], v[204:207], v[104:107]
	v_mfma_f32_16x16x32_bf16 v[100:103], v[180:183], v[204:207], v[100:103]
	v_mfma_f32_16x16x32_bf16 v[76:79], v[172:175], v[212:215], v[76:79]
	v_mfma_f32_16x16x32_bf16 v[64:67], v[180:183], v[212:215], v[64:67]
	s_setprio 0
	s_barrier
	s_add_i32 s60, s75, s3
	s_mov_b32 m0, s60
	ds_read_b128 v[184:187], v157 offset:49152
	ds_read_b128 v[188:191], v157 offset:50176
	ds_read_b128 v[192:195], v157 offset:51200
	ds_read_b128 v[196:199], v157 offset:52224
	ds_read_b128 v[200:203], v157 offset:53248
	ds_read_b128 v[204:207], v157 offset:54272
	ds_read_b128 v[208:211], v157 offset:55296
	ds_read_b128 v[212:215], v157 offset:56320
	global_load_lds_dwordx4 v130, s[98:99]
	s_add_i32 m0, s60, 0x2000
	s_add_u32 s58, s58, 0x100080
	s_addc_u32 s59, s59, 0
	s_add_i32 s60, s84, s3
	global_load_lds_dwordx4 v134, s[98:99]
	s_mov_b32 m0, s60
	s_nop 0
	global_load_lds_dwordx4 v130, s[58:59]
	s_add_i32 m0, s60, 0x2000
	s_nop 0
	global_load_lds_dwordx4 v134, s[58:59]
	s_mov_b32 m0, s64
	s_nop 0
	global_load_lds_dwordx4 v128, s[100:101]
	s_mov_b32 m0, s65
	s_nop 0
	global_load_lds_dwordx4 v132, s[100:101]
	s_waitcnt vmcnt(8)
	s_waitcnt lgkmcnt(0)
	s_barrier
	s_setprio 1
	s_waitcnt lgkmcnt(0)
	v_mfma_f32_16x16x32_bf16 v[60:63], v[144:147], v[184:187], v[60:63]
	v_mfma_f32_16x16x32_bf16 v[56:59], v[160:163], v[184:187], v[56:59]
	v_mfma_f32_16x16x32_bf16 v[44:47], v[144:147], v[192:195], v[44:47]
	v_mfma_f32_16x16x32_bf16 v[40:43], v[160:163], v[192:195], v[40:43]
	v_mfma_f32_16x16x32_bf16 v[28:31], v[144:147], v[200:203], v[28:31]
	v_mfma_f32_16x16x32_bf16 v[24:27], v[160:163], v[200:203], v[24:27]
	v_mfma_f32_16x16x32_bf16 v[12:15], v[144:147], v[208:211], v[12:15]
	v_mfma_f32_16x16x32_bf16 v[8:11], v[160:163], v[208:211], v[8:11]
	v_mfma_f32_16x16x32_bf16 v[60:63], v[148:151], v[188:191], v[60:63]
	v_mfma_f32_16x16x32_bf16 v[56:59], v[164:167], v[188:191], v[56:59]
	v_mfma_f32_16x16x32_bf16 v[44:47], v[148:151], v[196:199], v[44:47]
	v_mfma_f32_16x16x32_bf16 v[40:43], v[164:167], v[196:199], v[40:43]
	v_mfma_f32_16x16x32_bf16 v[28:31], v[148:151], v[204:207], v[28:31]
	v_mfma_f32_16x16x32_bf16 v[24:27], v[164:167], v[204:207], v[24:27]
	v_mfma_f32_16x16x32_bf16 v[12:15], v[148:151], v[212:215], v[12:15]
	v_mfma_f32_16x16x32_bf16 v[8:11], v[164:167], v[212:215], v[8:11]
	s_setprio 0
	s_setprio 1
	v_mfma_f32_16x16x32_bf16 v[52:55], v[168:171], v[184:187], v[52:55]
	v_mfma_f32_16x16x32_bf16 v[48:51], v[176:179], v[184:187], v[48:51]
	v_mfma_f32_16x16x32_bf16 v[36:39], v[168:171], v[192:195], v[36:39]
	v_mfma_f32_16x16x32_bf16 v[32:35], v[176:179], v[192:195], v[32:35]
	v_mfma_f32_16x16x32_bf16 v[20:23], v[168:171], v[200:203], v[20:23]
	v_mfma_f32_16x16x32_bf16 v[16:19], v[176:179], v[200:203], v[16:19]
	v_mfma_f32_16x16x32_bf16 v[4:7], v[168:171], v[208:211], v[4:7]
	v_mfma_f32_16x16x32_bf16 v[0:3], v[176:179], v[208:211], v[0:3]
	v_mfma_f32_16x16x32_bf16 v[52:55], v[172:175], v[188:191], v[52:55]
	v_mfma_f32_16x16x32_bf16 v[48:51], v[180:183], v[188:191], v[48:51]
	v_mfma_f32_16x16x32_bf16 v[36:39], v[172:175], v[196:199], v[36:39]
	v_mfma_f32_16x16x32_bf16 v[32:35], v[180:183], v[196:199], v[32:35]
	v_mfma_f32_16x16x32_bf16 v[20:23], v[172:175], v[204:207], v[20:23]
	v_mfma_f32_16x16x32_bf16 v[16:19], v[180:183], v[204:207], v[16:19]
	v_mfma_f32_16x16x32_bf16 v[4:7], v[172:175], v[212:215], v[4:7]
	v_mfma_f32_16x16x32_bf16 v[0:3], v[180:183], v[212:215], v[0:3]
	s_setprio 0
	s_barrier
	s_add_i32 s74, s74, 2
	s_add_u32 s56, s56, 0x100
	s_addc_u32 s57, s57, 0
	s_add_u32 s72, s72, 0x100
	s_addc_u32 s73, s73, 0
	s_cmp_gt_u32 s74, 61
	s_cbranch_scc0 .LBB0_3203
	s_and_b64 vcc, exec, s[22:23]
	s_cbranch_vccz .LBB0_3206
	s_barrier
